# P4 scan chunk body rewritten by hand: 4 compute waves x (2 rows x 8 cols per lane), row-paired pk math, operands shared by both rows
# speedup vs baseline: 1.0367x; 1.0367x over previous
.LBB0_672:
	s_add_i32 s22, s65, 1
	s_cmpk_ge_u32 s62, 0x100
	s_cbranch_scc1 .Lmy_scan_skip
	s_and_b32 s23, s65, 1
	s_mul_i32 s24, s23, 0xc000
	v_lshl_add_u32 v74, s23, 13, v49
	s_lshr_b32 s23, s62, 1
	v_add_u32_e32 v72, s24, v69
	v_lshl_add_u32 v73, v66, 2, s24
	v_add_u32_e32 v74, s23, v74
	v_add_u32_e32 v73, s23, v73
	ds_read_b128 v[88:91], v72 offset:8192
	ds_read_b128 v[92:95], v72 offset:8208
	ds_read_b128 v[80:83], v72 offset:0
	ds_read_b128 v[84:87], v72 offset:16
	ds_read_b32 v200, v73 offset:40960
	ds_read_b32 v201, v73 offset:40992
	ds_read_b128 v[104:107], v72 offset:24576
	ds_read_b128 v[108:111], v72 offset:24592
	ds_read_b128 v[96:99], v72 offset:16384
	ds_read_b128 v[100:103], v72 offset:16400
	ds_read_b128 v[112:115], v72 offset:32768
	ds_read_b128 v[116:119], v72 offset:32784
	ds_read_b128 v[128:131], v72 offset:8448
	ds_read_b128 v[132:135], v72 offset:8464
	ds_read_b128 v[120:123], v72 offset:256
	ds_read_b128 v[124:127], v72 offset:272
	ds_read_b32 v202, v73 offset:41216
	ds_read_b32 v203, v73 offset:41248
	ds_read_b128 v[144:147], v72 offset:24832
	ds_read_b128 v[148:151], v72 offset:24848
	ds_read_b128 v[136:139], v72 offset:16640
	ds_read_b128 v[140:143], v72 offset:16656
	ds_read_b128 v[152:155], v72 offset:33024
	ds_read_b128 v[156:159], v72 offset:33040
	s_cmp_lg_u32 s65, 0
	s_cbranch_scc1 .Lmy_scan_nz
	v_mov_b32_e32 v208, 0
	v_mov_b32_e32 v209, 0
	v_mov_b32_e32 v210, 0
	v_mov_b32_e32 v211, 0
	v_mov_b32_e32 v212, 0
	v_mov_b32_e32 v213, 0
	v_mov_b32_e32 v214, 0
	v_mov_b32_e32 v215, 0
	v_mov_b32_e32 v216, 0
	v_mov_b32_e32 v217, 0
	v_mov_b32_e32 v218, 0
	v_mov_b32_e32 v219, 0
	v_mov_b32_e32 v220, 0
	v_mov_b32_e32 v221, 0
	v_mov_b32_e32 v222, 0
	v_mov_b32_e32 v223, 0
.Lmy_scan_nz:
	s_waitcnt lgkmcnt(15)
	v_pk_mul_f32 v[240:241], v[208:209], v[88:89] op_sel_hi:[1,0]
	v_pk_mul_f32 v[224:225], v[208:209], v[80:81] op_sel_hi:[1,0]
	v_pk_mul_f32 v[226:227], v[210:211], v[80:81] op_sel:[0,1] op_sel_hi:[1,1]
	v_pk_fma_f32 v[240:241], v[210:211], v[88:89], v[240:241] op_sel:[0,1,0] op_sel_hi:[1,1,1]
	v_pk_mul_f32 v[228:229], v[212:213], v[82:83] op_sel_hi:[1,0]
	v_pk_mul_f32 v[230:231], v[214:215], v[82:83] op_sel:[0,1] op_sel_hi:[1,1]
	v_pk_fma_f32 v[240:241], v[212:213], v[90:91], v[240:241] op_sel_hi:[1,0,1]
	v_pk_mul_f32 v[232:233], v[216:217], v[84:85] op_sel_hi:[1,0]
	v_pk_mul_f32 v[234:235], v[218:219], v[84:85] op_sel:[0,1] op_sel_hi:[1,1]
	v_pk_fma_f32 v[240:241], v[214:215], v[90:91], v[240:241] op_sel:[0,1,0] op_sel_hi:[1,1,1]
	v_pk_mul_f32 v[236:237], v[220:221], v[86:87] op_sel_hi:[1,0]
	v_pk_mul_f32 v[238:239], v[222:223], v[86:87] op_sel:[0,1] op_sel_hi:[1,1]
	v_pk_fma_f32 v[240:241], v[216:217], v[92:93], v[240:241] op_sel_hi:[1,0,1]
	v_pk_fma_f32 v[224:225], v[200:201], v[104:105], v[224:225] op_sel_hi:[1,0,1]
	v_pk_fma_f32 v[226:227], v[200:201], v[104:105], v[226:227] op_sel:[0,1,0] op_sel_hi:[1,1,1]
	v_pk_fma_f32 v[240:241], v[218:219], v[92:93], v[240:241] op_sel:[0,1,0] op_sel_hi:[1,1,1]
	v_pk_fma_f32 v[228:229], v[200:201], v[106:107], v[228:229] op_sel_hi:[1,0,1]
	v_pk_fma_f32 v[230:231], v[200:201], v[106:107], v[230:231] op_sel:[0,1,0] op_sel_hi:[1,1,1]
	v_pk_fma_f32 v[240:241], v[220:221], v[94:95], v[240:241] op_sel_hi:[1,0,1]
	v_pk_fma_f32 v[232:233], v[200:201], v[108:109], v[232:233] op_sel_hi:[1,0,1]
	v_pk_fma_f32 v[234:235], v[200:201], v[108:109], v[234:235] op_sel:[0,1,0] op_sel_hi:[1,1,1]
	v_pk_fma_f32 v[240:241], v[222:223], v[94:95], v[240:241] op_sel:[0,1,0] op_sel_hi:[1,1,1]
	v_pk_fma_f32 v[236:237], v[200:201], v[110:111], v[236:237] op_sel_hi:[1,0,1]
	v_pk_fma_f32 v[238:239], v[200:201], v[110:111], v[238:239] op_sel:[0,1,0] op_sel_hi:[1,1,1]
	v_add_f32_dpp v240, v240, v240 quad_perm:[1,0,3,2] row_mask:0xf bank_mask:0xf bound_ctrl:1
	v_add_f32_dpp v241, v241, v241 quad_perm:[1,0,3,2] row_mask:0xf bank_mask:0xf bound_ctrl:1
	s_nop 0
	v_add_f32_dpp v240, v240, v240 quad_perm:[2,3,0,1] row_mask:0xf bank_mask:0xf bound_ctrl:1
	v_add_f32_dpp v241, v241, v241 quad_perm:[2,3,0,1] row_mask:0xf bank_mask:0xf bound_ctrl:1
	s_nop 0
	v_add_f32_dpp v248, v240, v240 row_half_mirror row_mask:0xf bank_mask:0xf bound_ctrl:1
	v_add_f32_dpp v249, v241, v241 row_half_mirror row_mask:0xf bank_mask:0xf bound_ctrl:1
	v_pk_fma_f32 v[224:225], v[248:249], v[96:97], v[224:225] op_sel_hi:[1,0,1]
	v_pk_fma_f32 v[226:227], v[248:249], v[96:97], v[226:227] op_sel:[0,1,0] op_sel_hi:[1,1,1]
	v_pk_fma_f32 v[228:229], v[248:249], v[98:99], v[228:229] op_sel_hi:[1,0,1]
	v_pk_fma_f32 v[230:231], v[248:249], v[98:99], v[230:231] op_sel:[0,1,0] op_sel_hi:[1,1,1]
	s_waitcnt lgkmcnt(13)
	v_pk_mul_f32 v[244:245], v[224:225], v[112:113] op_sel_hi:[1,0]
	v_pk_fma_f32 v[232:233], v[248:249], v[100:101], v[232:233] op_sel_hi:[1,0,1]
	v_pk_fma_f32 v[234:235], v[248:249], v[100:101], v[234:235] op_sel:[0,1,0] op_sel_hi:[1,1,1]
	v_pk_fma_f32 v[244:245], v[226:227], v[112:113], v[244:245] op_sel:[0,1,0] op_sel_hi:[1,1,1]
	v_pk_fma_f32 v[236:237], v[248:249], v[102:103], v[236:237] op_sel_hi:[1,0,1]
	v_pk_fma_f32 v[238:239], v[248:249], v[102:103], v[238:239] op_sel:[0,1,0] op_sel_hi:[1,1,1]
	v_pk_fma_f32 v[244:245], v[228:229], v[114:115], v[244:245] op_sel_hi:[1,0,1]
	ds_read_b128 v[168:171], v72 offset:8704
	ds_read_b128 v[172:175], v72 offset:8720
	v_pk_fma_f32 v[244:245], v[230:231], v[114:115], v[244:245] op_sel:[0,1,0] op_sel_hi:[1,1,1]
	ds_read_b128 v[160:163], v72 offset:512
	ds_read_b128 v[164:167], v72 offset:528
	s_waitcnt lgkmcnt(15)
	v_pk_fma_f32 v[244:245], v[232:233], v[116:117], v[244:245] op_sel_hi:[1,0,1]
	ds_read_b32 v204, v73 offset:41472
	ds_read_b32 v205, v73 offset:41504
	v_pk_fma_f32 v[244:245], v[234:235], v[116:117], v[244:245] op_sel:[0,1,0] op_sel_hi:[1,1,1]
	ds_read_b128 v[184:187], v72 offset:25088
	ds_read_b128 v[188:191], v72 offset:25104
	v_pk_fma_f32 v[244:245], v[236:237], v[118:119], v[244:245] op_sel_hi:[1,0,1]
	ds_read_b128 v[176:179], v72 offset:16896
	ds_read_b128 v[180:183], v72 offset:16912
	v_pk_fma_f32 v[244:245], v[238:239], v[118:119], v[244:245] op_sel:[0,1,0] op_sel_hi:[1,1,1]
	ds_read_b128 v[192:195], v72 offset:33280
	ds_read_b128 v[196:199], v72 offset:33296
	v_pk_mul_f32 v[240:241], v[224:225], v[128:129] op_sel_hi:[1,0]
	s_waitcnt lgkmcnt(15)
	v_pk_mul_f32 v[208:209], v[224:225], v[120:121] op_sel_hi:[1,0]
	v_pk_mul_f32 v[210:211], v[226:227], v[120:121] op_sel:[0,1] op_sel_hi:[1,1]
	v_pk_fma_f32 v[240:241], v[226:227], v[128:129], v[240:241] op_sel:[0,1,0] op_sel_hi:[1,1,1]
	v_pk_mul_f32 v[212:213], v[228:229], v[122:123] op_sel_hi:[1,0]
	v_pk_mul_f32 v[214:215], v[230:231], v[122:123] op_sel:[0,1] op_sel_hi:[1,1]
	v_pk_fma_f32 v[240:241], v[228:229], v[130:131], v[240:241] op_sel_hi:[1,0,1]
	v_pk_mul_f32 v[216:217], v[232:233], v[124:125] op_sel_hi:[1,0]
	v_pk_mul_f32 v[218:219], v[234:235], v[124:125] op_sel:[0,1] op_sel_hi:[1,1]
	v_pk_fma_f32 v[240:241], v[230:231], v[130:131], v[240:241] op_sel:[0,1,0] op_sel_hi:[1,1,1]
	v_pk_mul_f32 v[220:221], v[236:237], v[126:127] op_sel_hi:[1,0]
	v_pk_mul_f32 v[222:223], v[238:239], v[126:127] op_sel:[0,1] op_sel_hi:[1,1]
	v_pk_fma_f32 v[240:241], v[232:233], v[132:133], v[240:241] op_sel_hi:[1,0,1]
	v_pk_fma_f32 v[208:209], v[202:203], v[144:145], v[208:209] op_sel_hi:[1,0,1]
	v_pk_fma_f32 v[210:211], v[202:203], v[144:145], v[210:211] op_sel:[0,1,0] op_sel_hi:[1,1,1]
	v_pk_fma_f32 v[240:241], v[234:235], v[132:133], v[240:241] op_sel:[0,1,0] op_sel_hi:[1,1,1]
	v_pk_fma_f32 v[212:213], v[202:203], v[146:147], v[212:213] op_sel_hi:[1,0,1]
	v_pk_fma_f32 v[214:215], v[202:203], v[146:147], v[214:215] op_sel:[0,1,0] op_sel_hi:[1,1,1]
	v_pk_fma_f32 v[240:241], v[236:237], v[134:135], v[240:241] op_sel_hi:[1,0,1]
	v_pk_fma_f32 v[216:217], v[202:203], v[148:149], v[216:217] op_sel_hi:[1,0,1]
	v_pk_fma_f32 v[218:219], v[202:203], v[148:149], v[218:219] op_sel:[0,1,0] op_sel_hi:[1,1,1]
	v_pk_fma_f32 v[240:241], v[238:239], v[134:135], v[240:241] op_sel:[0,1,0] op_sel_hi:[1,1,1]
	v_pk_fma_f32 v[220:221], v[202:203], v[150:151], v[220:221] op_sel_hi:[1,0,1]
	v_pk_fma_f32 v[222:223], v[202:203], v[150:151], v[222:223] op_sel:[0,1,0] op_sel_hi:[1,1,1]
	v_add_f32_dpp v240, v240, v240 quad_perm:[1,0,3,2] row_mask:0xf bank_mask:0xf bound_ctrl:1
	v_add_f32_dpp v241, v241, v241 quad_perm:[1,0,3,2] row_mask:0xf bank_mask:0xf bound_ctrl:1
	v_add_f32_dpp v244, v244, v244 quad_perm:[1,0,3,2] row_mask:0xf bank_mask:0xf bound_ctrl:1
	v_add_f32_dpp v240, v240, v240 quad_perm:[2,3,0,1] row_mask:0xf bank_mask:0xf bound_ctrl:1
	v_add_f32_dpp v241, v241, v241 quad_perm:[2,3,0,1] row_mask:0xf bank_mask:0xf bound_ctrl:1
	v_add_f32_dpp v245, v245, v245 quad_perm:[1,0,3,2] row_mask:0xf bank_mask:0xf bound_ctrl:1
	v_add_f32_dpp v248, v240, v240 row_half_mirror row_mask:0xf bank_mask:0xf bound_ctrl:1
	v_add_f32_dpp v249, v241, v241 row_half_mirror row_mask:0xf bank_mask:0xf bound_ctrl:1
	v_add_f32_dpp v244, v244, v244 quad_perm:[2,3,0,1] row_mask:0xf bank_mask:0xf bound_ctrl:1
	v_add_f32_dpp v245, v245, v245 quad_perm:[2,3,0,1] row_mask:0xf bank_mask:0xf bound_ctrl:1
	v_pk_fma_f32 v[208:209], v[248:249], v[136:137], v[208:209] op_sel_hi:[1,0,1]
	v_pk_fma_f32 v[210:211], v[248:249], v[136:137], v[210:211] op_sel:[0,1,0] op_sel_hi:[1,1,1]
	v_add_f32_dpp v244, v244, v244 row_half_mirror row_mask:0xf bank_mask:0xf bound_ctrl:1
	v_add_f32_dpp v245, v245, v245 row_half_mirror row_mask:0xf bank_mask:0xf bound_ctrl:1
	v_pk_fma_f32 v[212:213], v[248:249], v[138:139], v[212:213] op_sel_hi:[1,0,1]
	v_cndmask_b32_e64 v75, 0, v244, s[6:7]
	v_cndmask_b32_e64 v76, 0, v245, s[6:7]
	v_pk_fma_f32 v[214:215], v[248:249], v[138:139], v[214:215] op_sel:[0,1,0] op_sel_hi:[1,1,1]
	s_waitcnt lgkmcnt(13)
	v_pk_mul_f32 v[244:245], v[208:209], v[152:153] op_sel_hi:[1,0]
	v_pk_fma_f32 v[216:217], v[248:249], v[140:141], v[216:217] op_sel_hi:[1,0,1]
	v_pk_fma_f32 v[218:219], v[248:249], v[140:141], v[218:219] op_sel:[0,1,0] op_sel_hi:[1,1,1]
	v_pk_fma_f32 v[244:245], v[210:211], v[152:153], v[244:245] op_sel:[0,1,0] op_sel_hi:[1,1,1]
	v_pk_fma_f32 v[220:221], v[248:249], v[142:143], v[220:221] op_sel_hi:[1,0,1]
	v_pk_fma_f32 v[222:223], v[248:249], v[142:143], v[222:223] op_sel:[0,1,0] op_sel_hi:[1,1,1]
	v_pk_fma_f32 v[244:245], v[212:213], v[154:155], v[244:245] op_sel_hi:[1,0,1]
	ds_read_b128 v[88:91], v72 offset:8960
	ds_read_b128 v[92:95], v72 offset:8976
	v_pk_fma_f32 v[244:245], v[214:215], v[154:155], v[244:245] op_sel:[0,1,0] op_sel_hi:[1,1,1]
	ds_read_b128 v[80:83], v72 offset:768
	ds_read_b128 v[84:87], v72 offset:784
	s_waitcnt lgkmcnt(15)
	v_pk_fma_f32 v[244:245], v[216:217], v[156:157], v[244:245] op_sel_hi:[1,0,1]
	ds_read_b32 v200, v73 offset:41728
	ds_read_b32 v201, v73 offset:41760
	v_pk_fma_f32 v[244:245], v[218:219], v[156:157], v[244:245] op_sel:[0,1,0] op_sel_hi:[1,1,1]
	ds_read_b128 v[104:107], v72 offset:25344
	ds_read_b128 v[108:111], v72 offset:25360
	v_pk_fma_f32 v[244:245], v[220:221], v[158:159], v[244:245] op_sel_hi:[1,0,1]
	ds_read_b128 v[96:99], v72 offset:17152
	ds_read_b128 v[100:103], v72 offset:17168
	v_pk_fma_f32 v[244:245], v[222:223], v[158:159], v[244:245] op_sel:[0,1,0] op_sel_hi:[1,1,1]
	ds_read_b128 v[112:115], v72 offset:33536
	ds_read_b128 v[116:119], v72 offset:33552
	v_pk_mul_f32 v[240:241], v[208:209], v[168:169] op_sel_hi:[1,0]
	s_waitcnt lgkmcnt(15)
	v_pk_mul_f32 v[224:225], v[208:209], v[160:161] op_sel_hi:[1,0]
	v_pk_mul_f32 v[226:227], v[210:211], v[160:161] op_sel:[0,1] op_sel_hi:[1,1]
	v_pk_fma_f32 v[240:241], v[210:211], v[168:169], v[240:241] op_sel:[0,1,0] op_sel_hi:[1,1,1]
	v_pk_mul_f32 v[228:229], v[212:213], v[162:163] op_sel_hi:[1,0]
	v_pk_mul_f32 v[230:231], v[214:215], v[162:163] op_sel:[0,1] op_sel_hi:[1,1]
	v_pk_fma_f32 v[240:241], v[212:213], v[170:171], v[240:241] op_sel_hi:[1,0,1]
	v_pk_mul_f32 v[232:233], v[216:217], v[164:165] op_sel_hi:[1,0]
	v_pk_mul_f32 v[234:235], v[218:219], v[164:165] op_sel:[0,1] op_sel_hi:[1,1]
	v_pk_fma_f32 v[240:241], v[214:215], v[170:171], v[240:241] op_sel:[0,1,0] op_sel_hi:[1,1,1]
	v_pk_mul_f32 v[236:237], v[220:221], v[166:167] op_sel_hi:[1,0]
	v_pk_mul_f32 v[238:239], v[222:223], v[166:167] op_sel:[0,1] op_sel_hi:[1,1]
	v_pk_fma_f32 v[240:241], v[216:217], v[172:173], v[240:241] op_sel_hi:[1,0,1]
	v_pk_fma_f32 v[224:225], v[204:205], v[184:185], v[224:225] op_sel_hi:[1,0,1]
	v_pk_fma_f32 v[226:227], v[204:205], v[184:185], v[226:227] op_sel:[0,1,0] op_sel_hi:[1,1,1]
	v_pk_fma_f32 v[240:241], v[218:219], v[172:173], v[240:241] op_sel:[0,1,0] op_sel_hi:[1,1,1]
	v_pk_fma_f32 v[228:229], v[204:205], v[186:187], v[228:229] op_sel_hi:[1,0,1]
	v_pk_fma_f32 v[230:231], v[204:205], v[186:187], v[230:231] op_sel:[0,1,0] op_sel_hi:[1,1,1]
	v_pk_fma_f32 v[240:241], v[220:221], v[174:175], v[240:241] op_sel_hi:[1,0,1]
	v_pk_fma_f32 v[232:233], v[204:205], v[188:189], v[232:233] op_sel_hi:[1,0,1]
	v_pk_fma_f32 v[234:235], v[204:205], v[188:189], v[234:235] op_sel:[0,1,0] op_sel_hi:[1,1,1]
	v_pk_fma_f32 v[240:241], v[222:223], v[174:175], v[240:241] op_sel:[0,1,0] op_sel_hi:[1,1,1]
	v_pk_fma_f32 v[236:237], v[204:205], v[190:191], v[236:237] op_sel_hi:[1,0,1]
	v_pk_fma_f32 v[238:239], v[204:205], v[190:191], v[238:239] op_sel:[0,1,0] op_sel_hi:[1,1,1]
	v_add_f32_dpp v240, v240, v240 quad_perm:[1,0,3,2] row_mask:0xf bank_mask:0xf bound_ctrl:1
	v_add_f32_dpp v241, v241, v241 quad_perm:[1,0,3,2] row_mask:0xf bank_mask:0xf bound_ctrl:1
	v_add_f32_dpp v244, v244, v244 quad_perm:[1,0,3,2] row_mask:0xf bank_mask:0xf bound_ctrl:1
	v_add_f32_dpp v240, v240, v240 quad_perm:[2,3,0,1] row_mask:0xf bank_mask:0xf bound_ctrl:1
	v_add_f32_dpp v241, v241, v241 quad_perm:[2,3,0,1] row_mask:0xf bank_mask:0xf bound_ctrl:1
	v_add_f32_dpp v245, v245, v245 quad_perm:[1,0,3,2] row_mask:0xf bank_mask:0xf bound_ctrl:1
	v_add_f32_dpp v248, v240, v240 row_half_mirror row_mask:0xf bank_mask:0xf bound_ctrl:1
	v_add_f32_dpp v249, v241, v241 row_half_mirror row_mask:0xf bank_mask:0xf bound_ctrl:1
	v_add_f32_dpp v244, v244, v244 quad_perm:[2,3,0,1] row_mask:0xf bank_mask:0xf bound_ctrl:1
	v_add_f32_dpp v245, v245, v245 quad_perm:[2,3,0,1] row_mask:0xf bank_mask:0xf bound_ctrl:1
	v_pk_fma_f32 v[224:225], v[248:249], v[176:177], v[224:225] op_sel_hi:[1,0,1]
	v_pk_fma_f32 v[226:227], v[248:249], v[176:177], v[226:227] op_sel:[0,1,0] op_sel_hi:[1,1,1]
	v_add_f32_dpp v244, v244, v244 row_half_mirror row_mask:0xf bank_mask:0xf bound_ctrl:1
	v_add_f32_dpp v245, v245, v245 row_half_mirror row_mask:0xf bank_mask:0xf bound_ctrl:1
	v_pk_fma_f32 v[228:229], v[248:249], v[178:179], v[228:229] op_sel_hi:[1,0,1]
	v_cndmask_b32_e64 v75, v75, v244, s[8:9]
	v_cndmask_b32_e64 v76, v76, v245, s[8:9]
	v_pk_fma_f32 v[230:231], v[248:249], v[178:179], v[230:231] op_sel:[0,1,0] op_sel_hi:[1,1,1]
	s_waitcnt lgkmcnt(13)
	v_pk_mul_f32 v[244:245], v[224:225], v[192:193] op_sel_hi:[1,0]
	v_pk_fma_f32 v[232:233], v[248:249], v[180:181], v[232:233] op_sel_hi:[1,0,1]
	v_pk_fma_f32 v[234:235], v[248:249], v[180:181], v[234:235] op_sel:[0,1,0] op_sel_hi:[1,1,1]
	v_pk_fma_f32 v[244:245], v[226:227], v[192:193], v[244:245] op_sel:[0,1,0] op_sel_hi:[1,1,1]
	v_pk_fma_f32 v[236:237], v[248:249], v[182:183], v[236:237] op_sel_hi:[1,0,1]
	v_pk_fma_f32 v[238:239], v[248:249], v[182:183], v[238:239] op_sel:[0,1,0] op_sel_hi:[1,1,1]
	v_pk_fma_f32 v[244:245], v[228:229], v[194:195], v[244:245] op_sel_hi:[1,0,1]
	ds_read_b128 v[128:131], v72 offset:9216
	ds_read_b128 v[132:135], v72 offset:9232
	v_pk_fma_f32 v[244:245], v[230:231], v[194:195], v[244:245] op_sel:[0,1,0] op_sel_hi:[1,1,1]
	ds_read_b128 v[120:123], v72 offset:1024
	ds_read_b128 v[124:127], v72 offset:1040
	s_waitcnt lgkmcnt(15)
	v_pk_fma_f32 v[244:245], v[232:233], v[196:197], v[244:245] op_sel_hi:[1,0,1]
	ds_read_b32 v202, v73 offset:41984
	ds_read_b32 v203, v73 offset:42016
	v_pk_fma_f32 v[244:245], v[234:235], v[196:197], v[244:245] op_sel:[0,1,0] op_sel_hi:[1,1,1]
	ds_read_b128 v[144:147], v72 offset:25600
	ds_read_b128 v[148:151], v72 offset:25616
	v_pk_fma_f32 v[244:245], v[236:237], v[198:199], v[244:245] op_sel_hi:[1,0,1]
	ds_read_b128 v[136:139], v72 offset:17408
	ds_read_b128 v[140:143], v72 offset:17424
	v_pk_fma_f32 v[244:245], v[238:239], v[198:199], v[244:245] op_sel:[0,1,0] op_sel_hi:[1,1,1]
	ds_read_b128 v[152:155], v72 offset:33792
	ds_read_b128 v[156:159], v72 offset:33808
	v_pk_mul_f32 v[240:241], v[224:225], v[88:89] op_sel_hi:[1,0]
	s_waitcnt lgkmcnt(15)
	v_pk_mul_f32 v[208:209], v[224:225], v[80:81] op_sel_hi:[1,0]
	v_pk_mul_f32 v[210:211], v[226:227], v[80:81] op_sel:[0,1] op_sel_hi:[1,1]
	v_pk_fma_f32 v[240:241], v[226:227], v[88:89], v[240:241] op_sel:[0,1,0] op_sel_hi:[1,1,1]
	v_pk_mul_f32 v[212:213], v[228:229], v[82:83] op_sel_hi:[1,0]
	v_pk_mul_f32 v[214:215], v[230:231], v[82:83] op_sel:[0,1] op_sel_hi:[1,1]
	v_pk_fma_f32 v[240:241], v[228:229], v[90:91], v[240:241] op_sel_hi:[1,0,1]
	v_pk_mul_f32 v[216:217], v[232:233], v[84:85] op_sel_hi:[1,0]
	v_pk_mul_f32 v[218:219], v[234:235], v[84:85] op_sel:[0,1] op_sel_hi:[1,1]
	v_pk_fma_f32 v[240:241], v[230:231], v[90:91], v[240:241] op_sel:[0,1,0] op_sel_hi:[1,1,1]
	v_pk_mul_f32 v[220:221], v[236:237], v[86:87] op_sel_hi:[1,0]
	v_pk_mul_f32 v[222:223], v[238:239], v[86:87] op_sel:[0,1] op_sel_hi:[1,1]
	v_pk_fma_f32 v[240:241], v[232:233], v[92:93], v[240:241] op_sel_hi:[1,0,1]
	v_pk_fma_f32 v[208:209], v[200:201], v[104:105], v[208:209] op_sel_hi:[1,0,1]
	v_pk_fma_f32 v[210:211], v[200:201], v[104:105], v[210:211] op_sel:[0,1,0] op_sel_hi:[1,1,1]
	v_pk_fma_f32 v[240:241], v[234:235], v[92:93], v[240:241] op_sel:[0,1,0] op_sel_hi:[1,1,1]
	v_pk_fma_f32 v[212:213], v[200:201], v[106:107], v[212:213] op_sel_hi:[1,0,1]
	v_pk_fma_f32 v[214:215], v[200:201], v[106:107], v[214:215] op_sel:[0,1,0] op_sel_hi:[1,1,1]
	v_pk_fma_f32 v[240:241], v[236:237], v[94:95], v[240:241] op_sel_hi:[1,0,1]
	v_pk_fma_f32 v[216:217], v[200:201], v[108:109], v[216:217] op_sel_hi:[1,0,1]
	v_pk_fma_f32 v[218:219], v[200:201], v[108:109], v[218:219] op_sel:[0,1,0] op_sel_hi:[1,1,1]
	v_pk_fma_f32 v[240:241], v[238:239], v[94:95], v[240:241] op_sel:[0,1,0] op_sel_hi:[1,1,1]
	v_pk_fma_f32 v[220:221], v[200:201], v[110:111], v[220:221] op_sel_hi:[1,0,1]
	v_pk_fma_f32 v[222:223], v[200:201], v[110:111], v[222:223] op_sel:[0,1,0] op_sel_hi:[1,1,1]
	v_add_f32_dpp v240, v240, v240 quad_perm:[1,0,3,2] row_mask:0xf bank_mask:0xf bound_ctrl:1
	v_add_f32_dpp v241, v241, v241 quad_perm:[1,0,3,2] row_mask:0xf bank_mask:0xf bound_ctrl:1
	v_add_f32_dpp v244, v244, v244 quad_perm:[1,0,3,2] row_mask:0xf bank_mask:0xf bound_ctrl:1
	v_add_f32_dpp v240, v240, v240 quad_perm:[2,3,0,1] row_mask:0xf bank_mask:0xf bound_ctrl:1
	v_add_f32_dpp v241, v241, v241 quad_perm:[2,3,0,1] row_mask:0xf bank_mask:0xf bound_ctrl:1
	v_add_f32_dpp v245, v245, v245 quad_perm:[1,0,3,2] row_mask:0xf bank_mask:0xf bound_ctrl:1
	v_add_f32_dpp v248, v240, v240 row_half_mirror row_mask:0xf bank_mask:0xf bound_ctrl:1
	v_add_f32_dpp v249, v241, v241 row_half_mirror row_mask:0xf bank_mask:0xf bound_ctrl:1
	v_add_f32_dpp v244, v244, v244 quad_perm:[2,3,0,1] row_mask:0xf bank_mask:0xf bound_ctrl:1
	v_add_f32_dpp v245, v245, v245 quad_perm:[2,3,0,1] row_mask:0xf bank_mask:0xf bound_ctrl:1
	v_pk_fma_f32 v[208:209], v[248:249], v[96:97], v[208:209] op_sel_hi:[1,0,1]
	v_pk_fma_f32 v[210:211], v[248:249], v[96:97], v[210:211] op_sel:[0,1,0] op_sel_hi:[1,1,1]
	v_add_f32_dpp v244, v244, v244 row_half_mirror row_mask:0xf bank_mask:0xf bound_ctrl:1
	v_add_f32_dpp v245, v245, v245 row_half_mirror row_mask:0xf bank_mask:0xf bound_ctrl:1
	v_pk_fma_f32 v[212:213], v[248:249], v[98:99], v[212:213] op_sel_hi:[1,0,1]
	v_cndmask_b32_e64 v75, v75, v244, s[10:11]
	v_cndmask_b32_e64 v76, v76, v245, s[10:11]
	v_pk_fma_f32 v[214:215], v[248:249], v[98:99], v[214:215] op_sel:[0,1,0] op_sel_hi:[1,1,1]
	s_waitcnt lgkmcnt(13)
	v_pk_mul_f32 v[244:245], v[208:209], v[112:113] op_sel_hi:[1,0]
	v_pk_fma_f32 v[216:217], v[248:249], v[100:101], v[216:217] op_sel_hi:[1,0,1]
	v_pk_fma_f32 v[218:219], v[248:249], v[100:101], v[218:219] op_sel:[0,1,0] op_sel_hi:[1,1,1]
	v_pk_fma_f32 v[244:245], v[210:211], v[112:113], v[244:245] op_sel:[0,1,0] op_sel_hi:[1,1,1]
	v_pk_fma_f32 v[220:221], v[248:249], v[102:103], v[220:221] op_sel_hi:[1,0,1]
	v_pk_fma_f32 v[222:223], v[248:249], v[102:103], v[222:223] op_sel:[0,1,0] op_sel_hi:[1,1,1]
	v_pk_fma_f32 v[244:245], v[212:213], v[114:115], v[244:245] op_sel_hi:[1,0,1]
	ds_read_b128 v[168:171], v72 offset:9472
	ds_read_b128 v[172:175], v72 offset:9488
	v_pk_fma_f32 v[244:245], v[214:215], v[114:115], v[244:245] op_sel:[0,1,0] op_sel_hi:[1,1,1]
	ds_read_b128 v[160:163], v72 offset:1280
	ds_read_b128 v[164:167], v72 offset:1296
	s_waitcnt lgkmcnt(15)
	v_pk_fma_f32 v[244:245], v[216:217], v[116:117], v[244:245] op_sel_hi:[1,0,1]
	ds_read_b32 v204, v73 offset:42240
	ds_read_b32 v205, v73 offset:42272
	v_pk_fma_f32 v[244:245], v[218:219], v[116:117], v[244:245] op_sel:[0,1,0] op_sel_hi:[1,1,1]
	ds_read_b128 v[184:187], v72 offset:25856
	ds_read_b128 v[188:191], v72 offset:25872
	v_pk_fma_f32 v[244:245], v[220:221], v[118:119], v[244:245] op_sel_hi:[1,0,1]
	ds_read_b128 v[176:179], v72 offset:17664
	ds_read_b128 v[180:183], v72 offset:17680
	v_pk_fma_f32 v[244:245], v[222:223], v[118:119], v[244:245] op_sel:[0,1,0] op_sel_hi:[1,1,1]
	ds_read_b128 v[192:195], v72 offset:34048
	ds_read_b128 v[196:199], v72 offset:34064
	v_pk_mul_f32 v[240:241], v[208:209], v[128:129] op_sel_hi:[1,0]
	s_waitcnt lgkmcnt(15)
	v_pk_mul_f32 v[224:225], v[208:209], v[120:121] op_sel_hi:[1,0]
	v_pk_mul_f32 v[226:227], v[210:211], v[120:121] op_sel:[0,1] op_sel_hi:[1,1]
	v_pk_fma_f32 v[240:241], v[210:211], v[128:129], v[240:241] op_sel:[0,1,0] op_sel_hi:[1,1,1]
	v_pk_mul_f32 v[228:229], v[212:213], v[122:123] op_sel_hi:[1,0]
	v_pk_mul_f32 v[230:231], v[214:215], v[122:123] op_sel:[0,1] op_sel_hi:[1,1]
	v_pk_fma_f32 v[240:241], v[212:213], v[130:131], v[240:241] op_sel_hi:[1,0,1]
	v_pk_mul_f32 v[232:233], v[216:217], v[124:125] op_sel_hi:[1,0]
	v_pk_mul_f32 v[234:235], v[218:219], v[124:125] op_sel:[0,1] op_sel_hi:[1,1]
	v_pk_fma_f32 v[240:241], v[214:215], v[130:131], v[240:241] op_sel:[0,1,0] op_sel_hi:[1,1,1]
	v_pk_mul_f32 v[236:237], v[220:221], v[126:127] op_sel_hi:[1,0]
	v_pk_mul_f32 v[238:239], v[222:223], v[126:127] op_sel:[0,1] op_sel_hi:[1,1]
	v_pk_fma_f32 v[240:241], v[216:217], v[132:133], v[240:241] op_sel_hi:[1,0,1]
	v_pk_fma_f32 v[224:225], v[202:203], v[144:145], v[224:225] op_sel_hi:[1,0,1]
	v_pk_fma_f32 v[226:227], v[202:203], v[144:145], v[226:227] op_sel:[0,1,0] op_sel_hi:[1,1,1]
	v_pk_fma_f32 v[240:241], v[218:219], v[132:133], v[240:241] op_sel:[0,1,0] op_sel_hi:[1,1,1]
	v_pk_fma_f32 v[228:229], v[202:203], v[146:147], v[228:229] op_sel_hi:[1,0,1]
	v_pk_fma_f32 v[230:231], v[202:203], v[146:147], v[230:231] op_sel:[0,1,0] op_sel_hi:[1,1,1]
	v_pk_fma_f32 v[240:241], v[220:221], v[134:135], v[240:241] op_sel_hi:[1,0,1]
	v_pk_fma_f32 v[232:233], v[202:203], v[148:149], v[232:233] op_sel_hi:[1,0,1]
	v_pk_fma_f32 v[234:235], v[202:203], v[148:149], v[234:235] op_sel:[0,1,0] op_sel_hi:[1,1,1]
	v_pk_fma_f32 v[240:241], v[222:223], v[134:135], v[240:241] op_sel:[0,1,0] op_sel_hi:[1,1,1]
	v_pk_fma_f32 v[236:237], v[202:203], v[150:151], v[236:237] op_sel_hi:[1,0,1]
	v_pk_fma_f32 v[238:239], v[202:203], v[150:151], v[238:239] op_sel:[0,1,0] op_sel_hi:[1,1,1]
	v_add_f32_dpp v240, v240, v240 quad_perm:[1,0,3,2] row_mask:0xf bank_mask:0xf bound_ctrl:1
	v_add_f32_dpp v241, v241, v241 quad_perm:[1,0,3,2] row_mask:0xf bank_mask:0xf bound_ctrl:1
	v_add_f32_dpp v244, v244, v244 quad_perm:[1,0,3,2] row_mask:0xf bank_mask:0xf bound_ctrl:1
	v_add_f32_dpp v240, v240, v240 quad_perm:[2,3,0,1] row_mask:0xf bank_mask:0xf bound_ctrl:1
	v_add_f32_dpp v241, v241, v241 quad_perm:[2,3,0,1] row_mask:0xf bank_mask:0xf bound_ctrl:1
	v_add_f32_dpp v245, v245, v245 quad_perm:[1,0,3,2] row_mask:0xf bank_mask:0xf bound_ctrl:1
	v_add_f32_dpp v248, v240, v240 row_half_mirror row_mask:0xf bank_mask:0xf bound_ctrl:1
	v_add_f32_dpp v249, v241, v241 row_half_mirror row_mask:0xf bank_mask:0xf bound_ctrl:1
	v_add_f32_dpp v244, v244, v244 quad_perm:[2,3,0,1] row_mask:0xf bank_mask:0xf bound_ctrl:1
	v_add_f32_dpp v245, v245, v245 quad_perm:[2,3,0,1] row_mask:0xf bank_mask:0xf bound_ctrl:1
	v_pk_fma_f32 v[224:225], v[248:249], v[136:137], v[224:225] op_sel_hi:[1,0,1]
	v_pk_fma_f32 v[226:227], v[248:249], v[136:137], v[226:227] op_sel:[0,1,0] op_sel_hi:[1,1,1]
	v_add_f32_dpp v244, v244, v244 row_half_mirror row_mask:0xf bank_mask:0xf bound_ctrl:1
	v_add_f32_dpp v245, v245, v245 row_half_mirror row_mask:0xf bank_mask:0xf bound_ctrl:1
	v_pk_fma_f32 v[228:229], v[248:249], v[138:139], v[228:229] op_sel_hi:[1,0,1]
	v_cndmask_b32_e64 v75, v75, v244, s[12:13]
	v_cndmask_b32_e64 v76, v76, v245, s[12:13]
	v_pk_fma_f32 v[230:231], v[248:249], v[138:139], v[230:231] op_sel:[0,1,0] op_sel_hi:[1,1,1]
	s_waitcnt lgkmcnt(13)
	v_pk_mul_f32 v[244:245], v[224:225], v[152:153] op_sel_hi:[1,0]
	v_pk_fma_f32 v[232:233], v[248:249], v[140:141], v[232:233] op_sel_hi:[1,0,1]
	v_pk_fma_f32 v[234:235], v[248:249], v[140:141], v[234:235] op_sel:[0,1,0] op_sel_hi:[1,1,1]
	v_pk_fma_f32 v[244:245], v[226:227], v[152:153], v[244:245] op_sel:[0,1,0] op_sel_hi:[1,1,1]
	v_pk_fma_f32 v[236:237], v[248:249], v[142:143], v[236:237] op_sel_hi:[1,0,1]
	v_pk_fma_f32 v[238:239], v[248:249], v[142:143], v[238:239] op_sel:[0,1,0] op_sel_hi:[1,1,1]
	v_pk_fma_f32 v[244:245], v[228:229], v[154:155], v[244:245] op_sel_hi:[1,0,1]
	ds_read_b128 v[88:91], v72 offset:9728
	ds_read_b128 v[92:95], v72 offset:9744
	v_pk_fma_f32 v[244:245], v[230:231], v[154:155], v[244:245] op_sel:[0,1,0] op_sel_hi:[1,1,1]
	ds_read_b128 v[80:83], v72 offset:1536
	ds_read_b128 v[84:87], v72 offset:1552
	s_waitcnt lgkmcnt(15)
	v_pk_fma_f32 v[244:245], v[232:233], v[156:157], v[244:245] op_sel_hi:[1,0,1]
	ds_read_b32 v200, v73 offset:42496
	ds_read_b32 v201, v73 offset:42528
	v_pk_fma_f32 v[244:245], v[234:235], v[156:157], v[244:245] op_sel:[0,1,0] op_sel_hi:[1,1,1]
	ds_read_b128 v[104:107], v72 offset:26112
	ds_read_b128 v[108:111], v72 offset:26128
	v_pk_fma_f32 v[244:245], v[236:237], v[158:159], v[244:245] op_sel_hi:[1,0,1]
	ds_read_b128 v[96:99], v72 offset:17920
	ds_read_b128 v[100:103], v72 offset:17936
	v_pk_fma_f32 v[244:245], v[238:239], v[158:159], v[244:245] op_sel:[0,1,0] op_sel_hi:[1,1,1]
	ds_read_b128 v[112:115], v72 offset:34304
	ds_read_b128 v[116:119], v72 offset:34320
	v_pk_mul_f32 v[240:241], v[224:225], v[168:169] op_sel_hi:[1,0]
	s_waitcnt lgkmcnt(15)
	v_pk_mul_f32 v[208:209], v[224:225], v[160:161] op_sel_hi:[1,0]
	v_pk_mul_f32 v[210:211], v[226:227], v[160:161] op_sel:[0,1] op_sel_hi:[1,1]
	v_pk_fma_f32 v[240:241], v[226:227], v[168:169], v[240:241] op_sel:[0,1,0] op_sel_hi:[1,1,1]
	v_pk_mul_f32 v[212:213], v[228:229], v[162:163] op_sel_hi:[1,0]
	v_pk_mul_f32 v[214:215], v[230:231], v[162:163] op_sel:[0,1] op_sel_hi:[1,1]
	v_pk_fma_f32 v[240:241], v[228:229], v[170:171], v[240:241] op_sel_hi:[1,0,1]
	v_pk_mul_f32 v[216:217], v[232:233], v[164:165] op_sel_hi:[1,0]
	v_pk_mul_f32 v[218:219], v[234:235], v[164:165] op_sel:[0,1] op_sel_hi:[1,1]
	v_pk_fma_f32 v[240:241], v[230:231], v[170:171], v[240:241] op_sel:[0,1,0] op_sel_hi:[1,1,1]
	v_pk_mul_f32 v[220:221], v[236:237], v[166:167] op_sel_hi:[1,0]
	v_pk_mul_f32 v[222:223], v[238:239], v[166:167] op_sel:[0,1] op_sel_hi:[1,1]
	v_pk_fma_f32 v[240:241], v[232:233], v[172:173], v[240:241] op_sel_hi:[1,0,1]
	v_pk_fma_f32 v[208:209], v[204:205], v[184:185], v[208:209] op_sel_hi:[1,0,1]
	v_pk_fma_f32 v[210:211], v[204:205], v[184:185], v[210:211] op_sel:[0,1,0] op_sel_hi:[1,1,1]
	v_pk_fma_f32 v[240:241], v[234:235], v[172:173], v[240:241] op_sel:[0,1,0] op_sel_hi:[1,1,1]
	v_pk_fma_f32 v[212:213], v[204:205], v[186:187], v[212:213] op_sel_hi:[1,0,1]
	v_pk_fma_f32 v[214:215], v[204:205], v[186:187], v[214:215] op_sel:[0,1,0] op_sel_hi:[1,1,1]
	v_pk_fma_f32 v[240:241], v[236:237], v[174:175], v[240:241] op_sel_hi:[1,0,1]
	v_pk_fma_f32 v[216:217], v[204:205], v[188:189], v[216:217] op_sel_hi:[1,0,1]
	v_pk_fma_f32 v[218:219], v[204:205], v[188:189], v[218:219] op_sel:[0,1,0] op_sel_hi:[1,1,1]
	v_pk_fma_f32 v[240:241], v[238:239], v[174:175], v[240:241] op_sel:[0,1,0] op_sel_hi:[1,1,1]
	v_pk_fma_f32 v[220:221], v[204:205], v[190:191], v[220:221] op_sel_hi:[1,0,1]
	v_pk_fma_f32 v[222:223], v[204:205], v[190:191], v[222:223] op_sel:[0,1,0] op_sel_hi:[1,1,1]
	v_add_f32_dpp v240, v240, v240 quad_perm:[1,0,3,2] row_mask:0xf bank_mask:0xf bound_ctrl:1
	v_add_f32_dpp v241, v241, v241 quad_perm:[1,0,3,2] row_mask:0xf bank_mask:0xf bound_ctrl:1
	v_add_f32_dpp v244, v244, v244 quad_perm:[1,0,3,2] row_mask:0xf bank_mask:0xf bound_ctrl:1
	v_add_f32_dpp v240, v240, v240 quad_perm:[2,3,0,1] row_mask:0xf bank_mask:0xf bound_ctrl:1
	v_add_f32_dpp v241, v241, v241 quad_perm:[2,3,0,1] row_mask:0xf bank_mask:0xf bound_ctrl:1
	v_add_f32_dpp v245, v245, v245 quad_perm:[1,0,3,2] row_mask:0xf bank_mask:0xf bound_ctrl:1
	v_add_f32_dpp v248, v240, v240 row_half_mirror row_mask:0xf bank_mask:0xf bound_ctrl:1
	v_add_f32_dpp v249, v241, v241 row_half_mirror row_mask:0xf bank_mask:0xf bound_ctrl:1
	v_add_f32_dpp v244, v244, v244 quad_perm:[2,3,0,1] row_mask:0xf bank_mask:0xf bound_ctrl:1
	v_add_f32_dpp v245, v245, v245 quad_perm:[2,3,0,1] row_mask:0xf bank_mask:0xf bound_ctrl:1
	v_pk_fma_f32 v[208:209], v[248:249], v[176:177], v[208:209] op_sel_hi:[1,0,1]
	v_pk_fma_f32 v[210:211], v[248:249], v[176:177], v[210:211] op_sel:[0,1,0] op_sel_hi:[1,1,1]
	v_add_f32_dpp v244, v244, v244 row_half_mirror row_mask:0xf bank_mask:0xf bound_ctrl:1
	v_add_f32_dpp v245, v245, v245 row_half_mirror row_mask:0xf bank_mask:0xf bound_ctrl:1
	v_pk_fma_f32 v[212:213], v[248:249], v[178:179], v[212:213] op_sel_hi:[1,0,1]
	v_cndmask_b32_e64 v75, v75, v244, s[14:15]
	v_cndmask_b32_e64 v76, v76, v245, s[14:15]
	v_pk_fma_f32 v[214:215], v[248:249], v[178:179], v[214:215] op_sel:[0,1,0] op_sel_hi:[1,1,1]
	s_waitcnt lgkmcnt(13)
	v_pk_mul_f32 v[244:245], v[208:209], v[192:193] op_sel_hi:[1,0]
	v_pk_fma_f32 v[216:217], v[248:249], v[180:181], v[216:217] op_sel_hi:[1,0,1]
	v_pk_fma_f32 v[218:219], v[248:249], v[180:181], v[218:219] op_sel:[0,1,0] op_sel_hi:[1,1,1]
	v_pk_fma_f32 v[244:245], v[210:211], v[192:193], v[244:245] op_sel:[0,1,0] op_sel_hi:[1,1,1]
	v_pk_fma_f32 v[220:221], v[248:249], v[182:183], v[220:221] op_sel_hi:[1,0,1]
	v_pk_fma_f32 v[222:223], v[248:249], v[182:183], v[222:223] op_sel:[0,1,0] op_sel_hi:[1,1,1]
	v_pk_fma_f32 v[244:245], v[212:213], v[194:195], v[244:245] op_sel_hi:[1,0,1]
	ds_read_b128 v[128:131], v72 offset:9984
	ds_read_b128 v[132:135], v72 offset:10000
	v_pk_fma_f32 v[244:245], v[214:215], v[194:195], v[244:245] op_sel:[0,1,0] op_sel_hi:[1,1,1]
	ds_read_b128 v[120:123], v72 offset:1792
	ds_read_b128 v[124:127], v72 offset:1808
	s_waitcnt lgkmcnt(15)
	v_pk_fma_f32 v[244:245], v[216:217], v[196:197], v[244:245] op_sel_hi:[1,0,1]
	ds_read_b32 v202, v73 offset:42752
	ds_read_b32 v203, v73 offset:42784
	v_pk_fma_f32 v[244:245], v[218:219], v[196:197], v[244:245] op_sel:[0,1,0] op_sel_hi:[1,1,1]
	ds_read_b128 v[144:147], v72 offset:26368
	ds_read_b128 v[148:151], v72 offset:26384
	v_pk_fma_f32 v[244:245], v[220:221], v[198:199], v[244:245] op_sel_hi:[1,0,1]
	ds_read_b128 v[136:139], v72 offset:18176
	ds_read_b128 v[140:143], v72 offset:18192
	v_pk_fma_f32 v[244:245], v[222:223], v[198:199], v[244:245] op_sel:[0,1,0] op_sel_hi:[1,1,1]
	ds_read_b128 v[152:155], v72 offset:34560
	ds_read_b128 v[156:159], v72 offset:34576
	v_pk_mul_f32 v[240:241], v[208:209], v[88:89] op_sel_hi:[1,0]
	s_waitcnt lgkmcnt(15)
	v_pk_mul_f32 v[224:225], v[208:209], v[80:81] op_sel_hi:[1,0]
	v_pk_mul_f32 v[226:227], v[210:211], v[80:81] op_sel:[0,1] op_sel_hi:[1,1]
	v_pk_fma_f32 v[240:241], v[210:211], v[88:89], v[240:241] op_sel:[0,1,0] op_sel_hi:[1,1,1]
	v_pk_mul_f32 v[228:229], v[212:213], v[82:83] op_sel_hi:[1,0]
	v_pk_mul_f32 v[230:231], v[214:215], v[82:83] op_sel:[0,1] op_sel_hi:[1,1]
	v_pk_fma_f32 v[240:241], v[212:213], v[90:91], v[240:241] op_sel_hi:[1,0,1]
	v_pk_mul_f32 v[232:233], v[216:217], v[84:85] op_sel_hi:[1,0]
	v_pk_mul_f32 v[234:235], v[218:219], v[84:85] op_sel:[0,1] op_sel_hi:[1,1]
	v_pk_fma_f32 v[240:241], v[214:215], v[90:91], v[240:241] op_sel:[0,1,0] op_sel_hi:[1,1,1]
	v_pk_mul_f32 v[236:237], v[220:221], v[86:87] op_sel_hi:[1,0]
	v_pk_mul_f32 v[238:239], v[222:223], v[86:87] op_sel:[0,1] op_sel_hi:[1,1]
	v_pk_fma_f32 v[240:241], v[216:217], v[92:93], v[240:241] op_sel_hi:[1,0,1]
	v_pk_fma_f32 v[224:225], v[200:201], v[104:105], v[224:225] op_sel_hi:[1,0,1]
	v_pk_fma_f32 v[226:227], v[200:201], v[104:105], v[226:227] op_sel:[0,1,0] op_sel_hi:[1,1,1]
	v_pk_fma_f32 v[240:241], v[218:219], v[92:93], v[240:241] op_sel:[0,1,0] op_sel_hi:[1,1,1]
	v_pk_fma_f32 v[228:229], v[200:201], v[106:107], v[228:229] op_sel_hi:[1,0,1]
	v_pk_fma_f32 v[230:231], v[200:201], v[106:107], v[230:231] op_sel:[0,1,0] op_sel_hi:[1,1,1]
	v_pk_fma_f32 v[240:241], v[220:221], v[94:95], v[240:241] op_sel_hi:[1,0,1]
	v_pk_fma_f32 v[232:233], v[200:201], v[108:109], v[232:233] op_sel_hi:[1,0,1]
	v_pk_fma_f32 v[234:235], v[200:201], v[108:109], v[234:235] op_sel:[0,1,0] op_sel_hi:[1,1,1]
	v_pk_fma_f32 v[240:241], v[222:223], v[94:95], v[240:241] op_sel:[0,1,0] op_sel_hi:[1,1,1]
	v_pk_fma_f32 v[236:237], v[200:201], v[110:111], v[236:237] op_sel_hi:[1,0,1]
	v_pk_fma_f32 v[238:239], v[200:201], v[110:111], v[238:239] op_sel:[0,1,0] op_sel_hi:[1,1,1]
	v_add_f32_dpp v240, v240, v240 quad_perm:[1,0,3,2] row_mask:0xf bank_mask:0xf bound_ctrl:1
	v_add_f32_dpp v241, v241, v241 quad_perm:[1,0,3,2] row_mask:0xf bank_mask:0xf bound_ctrl:1
	v_add_f32_dpp v244, v244, v244 quad_perm:[1,0,3,2] row_mask:0xf bank_mask:0xf bound_ctrl:1
	v_add_f32_dpp v240, v240, v240 quad_perm:[2,3,0,1] row_mask:0xf bank_mask:0xf bound_ctrl:1
	v_add_f32_dpp v241, v241, v241 quad_perm:[2,3,0,1] row_mask:0xf bank_mask:0xf bound_ctrl:1
	v_add_f32_dpp v245, v245, v245 quad_perm:[1,0,3,2] row_mask:0xf bank_mask:0xf bound_ctrl:1
	v_add_f32_dpp v248, v240, v240 row_half_mirror row_mask:0xf bank_mask:0xf bound_ctrl:1
	v_add_f32_dpp v249, v241, v241 row_half_mirror row_mask:0xf bank_mask:0xf bound_ctrl:1
	v_add_f32_dpp v244, v244, v244 quad_perm:[2,3,0,1] row_mask:0xf bank_mask:0xf bound_ctrl:1
	v_add_f32_dpp v245, v245, v245 quad_perm:[2,3,0,1] row_mask:0xf bank_mask:0xf bound_ctrl:1
	v_pk_fma_f32 v[224:225], v[248:249], v[96:97], v[224:225] op_sel_hi:[1,0,1]
	v_pk_fma_f32 v[226:227], v[248:249], v[96:97], v[226:227] op_sel:[0,1,0] op_sel_hi:[1,1,1]
	v_add_f32_dpp v244, v244, v244 row_half_mirror row_mask:0xf bank_mask:0xf bound_ctrl:1
	v_add_f32_dpp v245, v245, v245 row_half_mirror row_mask:0xf bank_mask:0xf bound_ctrl:1
	v_pk_fma_f32 v[228:229], v[248:249], v[98:99], v[228:229] op_sel_hi:[1,0,1]
	v_cndmask_b32_e64 v75, v75, v244, s[16:17]
	v_cndmask_b32_e64 v76, v76, v245, s[16:17]
	v_pk_fma_f32 v[230:231], v[248:249], v[98:99], v[230:231] op_sel:[0,1,0] op_sel_hi:[1,1,1]
	s_waitcnt lgkmcnt(13)
	v_pk_mul_f32 v[244:245], v[224:225], v[112:113] op_sel_hi:[1,0]
	v_pk_fma_f32 v[232:233], v[248:249], v[100:101], v[232:233] op_sel_hi:[1,0,1]
	v_pk_fma_f32 v[234:235], v[248:249], v[100:101], v[234:235] op_sel:[0,1,0] op_sel_hi:[1,1,1]
	v_pk_fma_f32 v[244:245], v[226:227], v[112:113], v[244:245] op_sel:[0,1,0] op_sel_hi:[1,1,1]
	v_pk_fma_f32 v[236:237], v[248:249], v[102:103], v[236:237] op_sel_hi:[1,0,1]
	v_pk_fma_f32 v[238:239], v[248:249], v[102:103], v[238:239] op_sel:[0,1,0] op_sel_hi:[1,1,1]
	v_pk_fma_f32 v[244:245], v[228:229], v[114:115], v[244:245] op_sel_hi:[1,0,1]
	ds_read_b128 v[168:171], v72 offset:10240
	ds_read_b128 v[172:175], v72 offset:10256
	v_pk_fma_f32 v[244:245], v[230:231], v[114:115], v[244:245] op_sel:[0,1,0] op_sel_hi:[1,1,1]
	ds_read_b128 v[160:163], v72 offset:2048
	ds_read_b128 v[164:167], v72 offset:2064
	s_waitcnt lgkmcnt(15)
	v_pk_fma_f32 v[244:245], v[232:233], v[116:117], v[244:245] op_sel_hi:[1,0,1]
	ds_read_b32 v204, v73 offset:43008
	ds_read_b32 v205, v73 offset:43040
	v_pk_fma_f32 v[244:245], v[234:235], v[116:117], v[244:245] op_sel:[0,1,0] op_sel_hi:[1,1,1]
	ds_read_b128 v[184:187], v72 offset:26624
	ds_read_b128 v[188:191], v72 offset:26640
	v_pk_fma_f32 v[244:245], v[236:237], v[118:119], v[244:245] op_sel_hi:[1,0,1]
	ds_read_b128 v[176:179], v72 offset:18432
	ds_read_b128 v[180:183], v72 offset:18448
	v_pk_fma_f32 v[244:245], v[238:239], v[118:119], v[244:245] op_sel:[0,1,0] op_sel_hi:[1,1,1]
	ds_read_b128 v[192:195], v72 offset:34816
	ds_read_b128 v[196:199], v72 offset:34832
	v_pk_mul_f32 v[240:241], v[224:225], v[128:129] op_sel_hi:[1,0]
	s_waitcnt lgkmcnt(15)
	v_pk_mul_f32 v[208:209], v[224:225], v[120:121] op_sel_hi:[1,0]
	v_pk_mul_f32 v[210:211], v[226:227], v[120:121] op_sel:[0,1] op_sel_hi:[1,1]
	v_pk_fma_f32 v[240:241], v[226:227], v[128:129], v[240:241] op_sel:[0,1,0] op_sel_hi:[1,1,1]
	v_pk_mul_f32 v[212:213], v[228:229], v[122:123] op_sel_hi:[1,0]
	v_pk_mul_f32 v[214:215], v[230:231], v[122:123] op_sel:[0,1] op_sel_hi:[1,1]
	v_pk_fma_f32 v[240:241], v[228:229], v[130:131], v[240:241] op_sel_hi:[1,0,1]
	v_pk_mul_f32 v[216:217], v[232:233], v[124:125] op_sel_hi:[1,0]
	v_pk_mul_f32 v[218:219], v[234:235], v[124:125] op_sel:[0,1] op_sel_hi:[1,1]
	v_pk_fma_f32 v[240:241], v[230:231], v[130:131], v[240:241] op_sel:[0,1,0] op_sel_hi:[1,1,1]
	v_pk_mul_f32 v[220:221], v[236:237], v[126:127] op_sel_hi:[1,0]
	v_pk_mul_f32 v[222:223], v[238:239], v[126:127] op_sel:[0,1] op_sel_hi:[1,1]
	v_pk_fma_f32 v[240:241], v[232:233], v[132:133], v[240:241] op_sel_hi:[1,0,1]
	v_pk_fma_f32 v[208:209], v[202:203], v[144:145], v[208:209] op_sel_hi:[1,0,1]
	v_pk_fma_f32 v[210:211], v[202:203], v[144:145], v[210:211] op_sel:[0,1,0] op_sel_hi:[1,1,1]
	v_pk_fma_f32 v[240:241], v[234:235], v[132:133], v[240:241] op_sel:[0,1,0] op_sel_hi:[1,1,1]
	v_pk_fma_f32 v[212:213], v[202:203], v[146:147], v[212:213] op_sel_hi:[1,0,1]
	v_pk_fma_f32 v[214:215], v[202:203], v[146:147], v[214:215] op_sel:[0,1,0] op_sel_hi:[1,1,1]
	v_pk_fma_f32 v[240:241], v[236:237], v[134:135], v[240:241] op_sel_hi:[1,0,1]
	v_pk_fma_f32 v[216:217], v[202:203], v[148:149], v[216:217] op_sel_hi:[1,0,1]
	v_pk_fma_f32 v[218:219], v[202:203], v[148:149], v[218:219] op_sel:[0,1,0] op_sel_hi:[1,1,1]
	v_pk_fma_f32 v[240:241], v[238:239], v[134:135], v[240:241] op_sel:[0,1,0] op_sel_hi:[1,1,1]
	v_pk_fma_f32 v[220:221], v[202:203], v[150:151], v[220:221] op_sel_hi:[1,0,1]
	v_pk_fma_f32 v[222:223], v[202:203], v[150:151], v[222:223] op_sel:[0,1,0] op_sel_hi:[1,1,1]
	v_add_f32_dpp v240, v240, v240 quad_perm:[1,0,3,2] row_mask:0xf bank_mask:0xf bound_ctrl:1
	v_add_f32_dpp v241, v241, v241 quad_perm:[1,0,3,2] row_mask:0xf bank_mask:0xf bound_ctrl:1
	v_add_f32_dpp v244, v244, v244 quad_perm:[1,0,3,2] row_mask:0xf bank_mask:0xf bound_ctrl:1
	v_add_f32_dpp v240, v240, v240 quad_perm:[2,3,0,1] row_mask:0xf bank_mask:0xf bound_ctrl:1
	v_add_f32_dpp v241, v241, v241 quad_perm:[2,3,0,1] row_mask:0xf bank_mask:0xf bound_ctrl:1
	v_add_f32_dpp v245, v245, v245 quad_perm:[1,0,3,2] row_mask:0xf bank_mask:0xf bound_ctrl:1
	v_add_f32_dpp v248, v240, v240 row_half_mirror row_mask:0xf bank_mask:0xf bound_ctrl:1
	v_add_f32_dpp v249, v241, v241 row_half_mirror row_mask:0xf bank_mask:0xf bound_ctrl:1
	v_add_f32_dpp v244, v244, v244 quad_perm:[2,3,0,1] row_mask:0xf bank_mask:0xf bound_ctrl:1
	v_add_f32_dpp v245, v245, v245 quad_perm:[2,3,0,1] row_mask:0xf bank_mask:0xf bound_ctrl:1
	v_pk_fma_f32 v[208:209], v[248:249], v[136:137], v[208:209] op_sel_hi:[1,0,1]
	v_pk_fma_f32 v[210:211], v[248:249], v[136:137], v[210:211] op_sel:[0,1,0] op_sel_hi:[1,1,1]
	v_add_f32_dpp v244, v244, v244 row_half_mirror row_mask:0xf bank_mask:0xf bound_ctrl:1
	v_add_f32_dpp v245, v245, v245 row_half_mirror row_mask:0xf bank_mask:0xf bound_ctrl:1
	v_pk_fma_f32 v[212:213], v[248:249], v[138:139], v[212:213] op_sel_hi:[1,0,1]
	v_cndmask_b32_e64 v75, v75, v244, s[18:19]
	v_cndmask_b32_e64 v76, v76, v245, s[18:19]
	v_pk_fma_f32 v[214:215], v[248:249], v[138:139], v[214:215] op_sel:[0,1,0] op_sel_hi:[1,1,1]
	s_waitcnt lgkmcnt(13)
	v_pk_mul_f32 v[244:245], v[208:209], v[152:153] op_sel_hi:[1,0]
	v_pk_fma_f32 v[216:217], v[248:249], v[140:141], v[216:217] op_sel_hi:[1,0,1]
	v_pk_fma_f32 v[218:219], v[248:249], v[140:141], v[218:219] op_sel:[0,1,0] op_sel_hi:[1,1,1]
	v_pk_fma_f32 v[244:245], v[210:211], v[152:153], v[244:245] op_sel:[0,1,0] op_sel_hi:[1,1,1]
	v_pk_fma_f32 v[220:221], v[248:249], v[142:143], v[220:221] op_sel_hi:[1,0,1]
	v_pk_fma_f32 v[222:223], v[248:249], v[142:143], v[222:223] op_sel:[0,1,0] op_sel_hi:[1,1,1]
	v_pk_fma_f32 v[244:245], v[212:213], v[154:155], v[244:245] op_sel_hi:[1,0,1]
	ds_read_b128 v[88:91], v72 offset:10496
	ds_read_b128 v[92:95], v72 offset:10512
	v_pk_fma_f32 v[244:245], v[214:215], v[154:155], v[244:245] op_sel:[0,1,0] op_sel_hi:[1,1,1]
	ds_read_b128 v[80:83], v72 offset:2304
	ds_read_b128 v[84:87], v72 offset:2320
	s_waitcnt lgkmcnt(15)
	v_pk_fma_f32 v[244:245], v[216:217], v[156:157], v[244:245] op_sel_hi:[1,0,1]
	ds_read_b32 v200, v73 offset:43264
	ds_read_b32 v201, v73 offset:43296
	v_pk_fma_f32 v[244:245], v[218:219], v[156:157], v[244:245] op_sel:[0,1,0] op_sel_hi:[1,1,1]
	ds_read_b128 v[104:107], v72 offset:26880
	ds_read_b128 v[108:111], v72 offset:26896
	v_pk_fma_f32 v[244:245], v[220:221], v[158:159], v[244:245] op_sel_hi:[1,0,1]
	ds_read_b128 v[96:99], v72 offset:18688
	ds_read_b128 v[100:103], v72 offset:18704
	v_pk_fma_f32 v[244:245], v[222:223], v[158:159], v[244:245] op_sel:[0,1,0] op_sel_hi:[1,1,1]
	ds_read_b128 v[112:115], v72 offset:35072
	ds_read_b128 v[116:119], v72 offset:35088
	v_pk_mul_f32 v[240:241], v[208:209], v[168:169] op_sel_hi:[1,0]
	s_waitcnt lgkmcnt(15)
	v_pk_mul_f32 v[224:225], v[208:209], v[160:161] op_sel_hi:[1,0]
	v_pk_mul_f32 v[226:227], v[210:211], v[160:161] op_sel:[0,1] op_sel_hi:[1,1]
	v_pk_fma_f32 v[240:241], v[210:211], v[168:169], v[240:241] op_sel:[0,1,0] op_sel_hi:[1,1,1]
	v_pk_mul_f32 v[228:229], v[212:213], v[162:163] op_sel_hi:[1,0]
	v_pk_mul_f32 v[230:231], v[214:215], v[162:163] op_sel:[0,1] op_sel_hi:[1,1]
	v_pk_fma_f32 v[240:241], v[212:213], v[170:171], v[240:241] op_sel_hi:[1,0,1]
	v_pk_mul_f32 v[232:233], v[216:217], v[164:165] op_sel_hi:[1,0]
	v_pk_mul_f32 v[234:235], v[218:219], v[164:165] op_sel:[0,1] op_sel_hi:[1,1]
	v_pk_fma_f32 v[240:241], v[214:215], v[170:171], v[240:241] op_sel:[0,1,0] op_sel_hi:[1,1,1]
	v_pk_mul_f32 v[236:237], v[220:221], v[166:167] op_sel_hi:[1,0]
	v_pk_mul_f32 v[238:239], v[222:223], v[166:167] op_sel:[0,1] op_sel_hi:[1,1]
	v_pk_fma_f32 v[240:241], v[216:217], v[172:173], v[240:241] op_sel_hi:[1,0,1]
	v_pk_fma_f32 v[224:225], v[204:205], v[184:185], v[224:225] op_sel_hi:[1,0,1]
	v_pk_fma_f32 v[226:227], v[204:205], v[184:185], v[226:227] op_sel:[0,1,0] op_sel_hi:[1,1,1]
	v_pk_fma_f32 v[240:241], v[218:219], v[172:173], v[240:241] op_sel:[0,1,0] op_sel_hi:[1,1,1]
	v_pk_fma_f32 v[228:229], v[204:205], v[186:187], v[228:229] op_sel_hi:[1,0,1]
	v_pk_fma_f32 v[230:231], v[204:205], v[186:187], v[230:231] op_sel:[0,1,0] op_sel_hi:[1,1,1]
	v_pk_fma_f32 v[240:241], v[220:221], v[174:175], v[240:241] op_sel_hi:[1,0,1]
	v_pk_fma_f32 v[232:233], v[204:205], v[188:189], v[232:233] op_sel_hi:[1,0,1]
	v_pk_fma_f32 v[234:235], v[204:205], v[188:189], v[234:235] op_sel:[0,1,0] op_sel_hi:[1,1,1]
	v_pk_fma_f32 v[240:241], v[222:223], v[174:175], v[240:241] op_sel:[0,1,0] op_sel_hi:[1,1,1]
	v_pk_fma_f32 v[236:237], v[204:205], v[190:191], v[236:237] op_sel_hi:[1,0,1]
	v_pk_fma_f32 v[238:239], v[204:205], v[190:191], v[238:239] op_sel:[0,1,0] op_sel_hi:[1,1,1]
	v_add_f32_dpp v240, v240, v240 quad_perm:[1,0,3,2] row_mask:0xf bank_mask:0xf bound_ctrl:1
	v_add_f32_dpp v241, v241, v241 quad_perm:[1,0,3,2] row_mask:0xf bank_mask:0xf bound_ctrl:1
	v_add_f32_dpp v244, v244, v244 quad_perm:[1,0,3,2] row_mask:0xf bank_mask:0xf bound_ctrl:1
	v_add_f32_dpp v240, v240, v240 quad_perm:[2,3,0,1] row_mask:0xf bank_mask:0xf bound_ctrl:1
	v_add_f32_dpp v241, v241, v241 quad_perm:[2,3,0,1] row_mask:0xf bank_mask:0xf bound_ctrl:1
	v_add_f32_dpp v245, v245, v245 quad_perm:[1,0,3,2] row_mask:0xf bank_mask:0xf bound_ctrl:1
	v_add_f32_dpp v248, v240, v240 row_half_mirror row_mask:0xf bank_mask:0xf bound_ctrl:1
	v_add_f32_dpp v249, v241, v241 row_half_mirror row_mask:0xf bank_mask:0xf bound_ctrl:1
	v_add_f32_dpp v244, v244, v244 quad_perm:[2,3,0,1] row_mask:0xf bank_mask:0xf bound_ctrl:1
	v_add_f32_dpp v245, v245, v245 quad_perm:[2,3,0,1] row_mask:0xf bank_mask:0xf bound_ctrl:1
	v_pk_fma_f32 v[224:225], v[248:249], v[176:177], v[224:225] op_sel_hi:[1,0,1]
	v_pk_fma_f32 v[226:227], v[248:249], v[176:177], v[226:227] op_sel:[0,1,0] op_sel_hi:[1,1,1]
	v_add_f32_dpp v244, v244, v244 row_half_mirror row_mask:0xf bank_mask:0xf bound_ctrl:1
	v_add_f32_dpp v245, v245, v245 row_half_mirror row_mask:0xf bank_mask:0xf bound_ctrl:1
	v_pk_fma_f32 v[228:229], v[248:249], v[178:179], v[228:229] op_sel_hi:[1,0,1]
	v_cndmask_b32_e64 v75, v75, v244, s[20:21]
	v_cndmask_b32_e64 v76, v76, v245, s[20:21]
	ds_write_b32 v74, v75
	ds_write_b32 v74, v76 offset:32
	v_pk_fma_f32 v[230:231], v[248:249], v[178:179], v[230:231] op_sel:[0,1,0] op_sel_hi:[1,1,1]
	s_waitcnt lgkmcnt(15)
	v_pk_mul_f32 v[244:245], v[224:225], v[192:193] op_sel_hi:[1,0]
	v_pk_fma_f32 v[232:233], v[248:249], v[180:181], v[232:233] op_sel_hi:[1,0,1]
	v_pk_fma_f32 v[234:235], v[248:249], v[180:181], v[234:235] op_sel:[0,1,0] op_sel_hi:[1,1,1]
	v_pk_fma_f32 v[244:245], v[226:227], v[192:193], v[244:245] op_sel:[0,1,0] op_sel_hi:[1,1,1]
	v_pk_fma_f32 v[236:237], v[248:249], v[182:183], v[236:237] op_sel_hi:[1,0,1]
	v_pk_fma_f32 v[238:239], v[248:249], v[182:183], v[238:239] op_sel:[0,1,0] op_sel_hi:[1,1,1]
	v_pk_fma_f32 v[244:245], v[228:229], v[194:195], v[244:245] op_sel_hi:[1,0,1]
	ds_read_b128 v[128:131], v72 offset:10752
	ds_read_b128 v[132:135], v72 offset:10768
	v_pk_fma_f32 v[244:245], v[230:231], v[194:195], v[244:245] op_sel:[0,1,0] op_sel_hi:[1,1,1]
	ds_read_b128 v[120:123], v72 offset:2560
	ds_read_b128 v[124:127], v72 offset:2576
	s_waitcnt lgkmcnt(15)
	v_pk_fma_f32 v[244:245], v[232:233], v[196:197], v[244:245] op_sel_hi:[1,0,1]
	ds_read_b32 v202, v73 offset:43520
	ds_read_b32 v203, v73 offset:43552
	v_pk_fma_f32 v[244:245], v[234:235], v[196:197], v[244:245] op_sel:[0,1,0] op_sel_hi:[1,1,1]
	ds_read_b128 v[144:147], v72 offset:27136
	ds_read_b128 v[148:151], v72 offset:27152
	v_pk_fma_f32 v[244:245], v[236:237], v[198:199], v[244:245] op_sel_hi:[1,0,1]
	ds_read_b128 v[136:139], v72 offset:18944
	ds_read_b128 v[140:143], v72 offset:18960
	v_pk_fma_f32 v[244:245], v[238:239], v[198:199], v[244:245] op_sel:[0,1,0] op_sel_hi:[1,1,1]
	ds_read_b128 v[152:155], v72 offset:35328
	ds_read_b128 v[156:159], v72 offset:35344
	v_pk_mul_f32 v[240:241], v[224:225], v[88:89] op_sel_hi:[1,0]
	v_pk_mul_f32 v[208:209], v[224:225], v[80:81] op_sel_hi:[1,0]
	v_pk_mul_f32 v[210:211], v[226:227], v[80:81] op_sel:[0,1] op_sel_hi:[1,1]
	v_pk_fma_f32 v[240:241], v[226:227], v[88:89], v[240:241] op_sel:[0,1,0] op_sel_hi:[1,1,1]
	v_pk_mul_f32 v[212:213], v[228:229], v[82:83] op_sel_hi:[1,0]
	v_pk_mul_f32 v[214:215], v[230:231], v[82:83] op_sel:[0,1] op_sel_hi:[1,1]
	v_pk_fma_f32 v[240:241], v[228:229], v[90:91], v[240:241] op_sel_hi:[1,0,1]
	s_waitcnt lgkmcnt(15)
	v_pk_mul_f32 v[216:217], v[232:233], v[84:85] op_sel_hi:[1,0]
	v_pk_mul_f32 v[218:219], v[234:235], v[84:85] op_sel:[0,1] op_sel_hi:[1,1]
	v_pk_fma_f32 v[240:241], v[230:231], v[90:91], v[240:241] op_sel:[0,1,0] op_sel_hi:[1,1,1]
	v_pk_mul_f32 v[220:221], v[236:237], v[86:87] op_sel_hi:[1,0]
	v_pk_mul_f32 v[222:223], v[238:239], v[86:87] op_sel:[0,1] op_sel_hi:[1,1]
	v_pk_fma_f32 v[240:241], v[232:233], v[92:93], v[240:241] op_sel_hi:[1,0,1]
	v_pk_fma_f32 v[208:209], v[200:201], v[104:105], v[208:209] op_sel_hi:[1,0,1]
	v_pk_fma_f32 v[210:211], v[200:201], v[104:105], v[210:211] op_sel:[0,1,0] op_sel_hi:[1,1,1]
	v_pk_fma_f32 v[240:241], v[234:235], v[92:93], v[240:241] op_sel:[0,1,0] op_sel_hi:[1,1,1]
	v_pk_fma_f32 v[212:213], v[200:201], v[106:107], v[212:213] op_sel_hi:[1,0,1]
	v_pk_fma_f32 v[214:215], v[200:201], v[106:107], v[214:215] op_sel:[0,1,0] op_sel_hi:[1,1,1]
	v_pk_fma_f32 v[240:241], v[236:237], v[94:95], v[240:241] op_sel_hi:[1,0,1]
	v_pk_fma_f32 v[216:217], v[200:201], v[108:109], v[216:217] op_sel_hi:[1,0,1]
	v_pk_fma_f32 v[218:219], v[200:201], v[108:109], v[218:219] op_sel:[0,1,0] op_sel_hi:[1,1,1]
	v_pk_fma_f32 v[240:241], v[238:239], v[94:95], v[240:241] op_sel:[0,1,0] op_sel_hi:[1,1,1]
	v_pk_fma_f32 v[220:221], v[200:201], v[110:111], v[220:221] op_sel_hi:[1,0,1]
	v_pk_fma_f32 v[222:223], v[200:201], v[110:111], v[222:223] op_sel:[0,1,0] op_sel_hi:[1,1,1]
	v_add_f32_dpp v240, v240, v240 quad_perm:[1,0,3,2] row_mask:0xf bank_mask:0xf bound_ctrl:1
	v_add_f32_dpp v241, v241, v241 quad_perm:[1,0,3,2] row_mask:0xf bank_mask:0xf bound_ctrl:1
	v_add_f32_dpp v244, v244, v244 quad_perm:[1,0,3,2] row_mask:0xf bank_mask:0xf bound_ctrl:1
	v_add_f32_dpp v240, v240, v240 quad_perm:[2,3,0,1] row_mask:0xf bank_mask:0xf bound_ctrl:1
	v_add_f32_dpp v241, v241, v241 quad_perm:[2,3,0,1] row_mask:0xf bank_mask:0xf bound_ctrl:1
	v_add_f32_dpp v245, v245, v245 quad_perm:[1,0,3,2] row_mask:0xf bank_mask:0xf bound_ctrl:1
	v_add_f32_dpp v248, v240, v240 row_half_mirror row_mask:0xf bank_mask:0xf bound_ctrl:1
	v_add_f32_dpp v249, v241, v241 row_half_mirror row_mask:0xf bank_mask:0xf bound_ctrl:1
	v_add_f32_dpp v244, v244, v244 quad_perm:[2,3,0,1] row_mask:0xf bank_mask:0xf bound_ctrl:1
	v_add_f32_dpp v245, v245, v245 quad_perm:[2,3,0,1] row_mask:0xf bank_mask:0xf bound_ctrl:1
	v_pk_fma_f32 v[208:209], v[248:249], v[96:97], v[208:209] op_sel_hi:[1,0,1]
	v_pk_fma_f32 v[210:211], v[248:249], v[96:97], v[210:211] op_sel:[0,1,0] op_sel_hi:[1,1,1]
	v_add_f32_dpp v244, v244, v244 row_half_mirror row_mask:0xf bank_mask:0xf bound_ctrl:1
	v_add_f32_dpp v245, v245, v245 row_half_mirror row_mask:0xf bank_mask:0xf bound_ctrl:1
	v_pk_fma_f32 v[212:213], v[248:249], v[98:99], v[212:213] op_sel_hi:[1,0,1]
	v_cndmask_b32_e64 v75, 0, v244, s[6:7]
	v_cndmask_b32_e64 v76, 0, v245, s[6:7]
	v_pk_fma_f32 v[214:215], v[248:249], v[98:99], v[214:215] op_sel:[0,1,0] op_sel_hi:[1,1,1]
	v_pk_mul_f32 v[244:245], v[208:209], v[112:113] op_sel_hi:[1,0]
	v_pk_fma_f32 v[216:217], v[248:249], v[100:101], v[216:217] op_sel_hi:[1,0,1]
	v_pk_fma_f32 v[218:219], v[248:249], v[100:101], v[218:219] op_sel:[0,1,0] op_sel_hi:[1,1,1]
	v_pk_fma_f32 v[244:245], v[210:211], v[112:113], v[244:245] op_sel:[0,1,0] op_sel_hi:[1,1,1]
	v_pk_fma_f32 v[220:221], v[248:249], v[102:103], v[220:221] op_sel_hi:[1,0,1]
	v_pk_fma_f32 v[222:223], v[248:249], v[102:103], v[222:223] op_sel:[0,1,0] op_sel_hi:[1,1,1]
	v_pk_fma_f32 v[244:245], v[212:213], v[114:115], v[244:245] op_sel_hi:[1,0,1]
	ds_read_b128 v[168:171], v72 offset:11008
	ds_read_b128 v[172:175], v72 offset:11024
	v_pk_fma_f32 v[244:245], v[214:215], v[114:115], v[244:245] op_sel:[0,1,0] op_sel_hi:[1,1,1]
	ds_read_b128 v[160:163], v72 offset:2816
	ds_read_b128 v[164:167], v72 offset:2832
	s_waitcnt lgkmcnt(15)
	v_pk_fma_f32 v[244:245], v[216:217], v[116:117], v[244:245] op_sel_hi:[1,0,1]
	ds_read_b32 v204, v73 offset:43776
	ds_read_b32 v205, v73 offset:43808
	v_pk_fma_f32 v[244:245], v[218:219], v[116:117], v[244:245] op_sel:[0,1,0] op_sel_hi:[1,1,1]
	ds_read_b128 v[184:187], v72 offset:27392
	ds_read_b128 v[188:191], v72 offset:27408
	v_pk_fma_f32 v[244:245], v[220:221], v[118:119], v[244:245] op_sel_hi:[1,0,1]
	ds_read_b128 v[176:179], v72 offset:19200
	ds_read_b128 v[180:183], v72 offset:19216
	v_pk_fma_f32 v[244:245], v[222:223], v[118:119], v[244:245] op_sel:[0,1,0] op_sel_hi:[1,1,1]
	ds_read_b128 v[192:195], v72 offset:35584
	ds_read_b128 v[196:199], v72 offset:35600
	v_pk_mul_f32 v[240:241], v[208:209], v[128:129] op_sel_hi:[1,0]
	s_waitcnt lgkmcnt(15)
	v_pk_mul_f32 v[224:225], v[208:209], v[120:121] op_sel_hi:[1,0]
	v_pk_mul_f32 v[226:227], v[210:211], v[120:121] op_sel:[0,1] op_sel_hi:[1,1]
	v_pk_fma_f32 v[240:241], v[210:211], v[128:129], v[240:241] op_sel:[0,1,0] op_sel_hi:[1,1,1]
	v_pk_mul_f32 v[228:229], v[212:213], v[122:123] op_sel_hi:[1,0]
	v_pk_mul_f32 v[230:231], v[214:215], v[122:123] op_sel:[0,1] op_sel_hi:[1,1]
	v_pk_fma_f32 v[240:241], v[212:213], v[130:131], v[240:241] op_sel_hi:[1,0,1]
	v_pk_mul_f32 v[232:233], v[216:217], v[124:125] op_sel_hi:[1,0]
	v_pk_mul_f32 v[234:235], v[218:219], v[124:125] op_sel:[0,1] op_sel_hi:[1,1]
	v_pk_fma_f32 v[240:241], v[214:215], v[130:131], v[240:241] op_sel:[0,1,0] op_sel_hi:[1,1,1]
	v_pk_mul_f32 v[236:237], v[220:221], v[126:127] op_sel_hi:[1,0]
	v_pk_mul_f32 v[238:239], v[222:223], v[126:127] op_sel:[0,1] op_sel_hi:[1,1]
	v_pk_fma_f32 v[240:241], v[216:217], v[132:133], v[240:241] op_sel_hi:[1,0,1]
	v_pk_fma_f32 v[224:225], v[202:203], v[144:145], v[224:225] op_sel_hi:[1,0,1]
	v_pk_fma_f32 v[226:227], v[202:203], v[144:145], v[226:227] op_sel:[0,1,0] op_sel_hi:[1,1,1]
	v_pk_fma_f32 v[240:241], v[218:219], v[132:133], v[240:241] op_sel:[0,1,0] op_sel_hi:[1,1,1]
	v_pk_fma_f32 v[228:229], v[202:203], v[146:147], v[228:229] op_sel_hi:[1,0,1]
	v_pk_fma_f32 v[230:231], v[202:203], v[146:147], v[230:231] op_sel:[0,1,0] op_sel_hi:[1,1,1]
	v_pk_fma_f32 v[240:241], v[220:221], v[134:135], v[240:241] op_sel_hi:[1,0,1]
	v_pk_fma_f32 v[232:233], v[202:203], v[148:149], v[232:233] op_sel_hi:[1,0,1]
	v_pk_fma_f32 v[234:235], v[202:203], v[148:149], v[234:235] op_sel:[0,1,0] op_sel_hi:[1,1,1]
	v_pk_fma_f32 v[240:241], v[222:223], v[134:135], v[240:241] op_sel:[0,1,0] op_sel_hi:[1,1,1]
	v_pk_fma_f32 v[236:237], v[202:203], v[150:151], v[236:237] op_sel_hi:[1,0,1]
	v_pk_fma_f32 v[238:239], v[202:203], v[150:151], v[238:239] op_sel:[0,1,0] op_sel_hi:[1,1,1]
	v_add_f32_dpp v240, v240, v240 quad_perm:[1,0,3,2] row_mask:0xf bank_mask:0xf bound_ctrl:1
	v_add_f32_dpp v241, v241, v241 quad_perm:[1,0,3,2] row_mask:0xf bank_mask:0xf bound_ctrl:1
	v_add_f32_dpp v244, v244, v244 quad_perm:[1,0,3,2] row_mask:0xf bank_mask:0xf bound_ctrl:1
	v_add_f32_dpp v240, v240, v240 quad_perm:[2,3,0,1] row_mask:0xf bank_mask:0xf bound_ctrl:1
	v_add_f32_dpp v241, v241, v241 quad_perm:[2,3,0,1] row_mask:0xf bank_mask:0xf bound_ctrl:1
	v_add_f32_dpp v245, v245, v245 quad_perm:[1,0,3,2] row_mask:0xf bank_mask:0xf bound_ctrl:1
	v_add_f32_dpp v248, v240, v240 row_half_mirror row_mask:0xf bank_mask:0xf bound_ctrl:1
	v_add_f32_dpp v249, v241, v241 row_half_mirror row_mask:0xf bank_mask:0xf bound_ctrl:1
	v_add_f32_dpp v244, v244, v244 quad_perm:[2,3,0,1] row_mask:0xf bank_mask:0xf bound_ctrl:1
	v_add_f32_dpp v245, v245, v245 quad_perm:[2,3,0,1] row_mask:0xf bank_mask:0xf bound_ctrl:1
	v_pk_fma_f32 v[224:225], v[248:249], v[136:137], v[224:225] op_sel_hi:[1,0,1]
	v_pk_fma_f32 v[226:227], v[248:249], v[136:137], v[226:227] op_sel:[0,1,0] op_sel_hi:[1,1,1]
	v_add_f32_dpp v244, v244, v244 row_half_mirror row_mask:0xf bank_mask:0xf bound_ctrl:1
	v_add_f32_dpp v245, v245, v245 row_half_mirror row_mask:0xf bank_mask:0xf bound_ctrl:1
	v_pk_fma_f32 v[228:229], v[248:249], v[138:139], v[228:229] op_sel_hi:[1,0,1]
	v_cndmask_b32_e64 v75, v75, v244, s[8:9]
	v_cndmask_b32_e64 v76, v76, v245, s[8:9]
	v_pk_fma_f32 v[230:231], v[248:249], v[138:139], v[230:231] op_sel:[0,1,0] op_sel_hi:[1,1,1]
	s_waitcnt lgkmcnt(13)
	v_pk_mul_f32 v[244:245], v[224:225], v[152:153] op_sel_hi:[1,0]
	v_pk_fma_f32 v[232:233], v[248:249], v[140:141], v[232:233] op_sel_hi:[1,0,1]
	v_pk_fma_f32 v[234:235], v[248:249], v[140:141], v[234:235] op_sel:[0,1,0] op_sel_hi:[1,1,1]
	v_pk_fma_f32 v[244:245], v[226:227], v[152:153], v[244:245] op_sel:[0,1,0] op_sel_hi:[1,1,1]
	v_pk_fma_f32 v[236:237], v[248:249], v[142:143], v[236:237] op_sel_hi:[1,0,1]
	v_pk_fma_f32 v[238:239], v[248:249], v[142:143], v[238:239] op_sel:[0,1,0] op_sel_hi:[1,1,1]
	v_pk_fma_f32 v[244:245], v[228:229], v[154:155], v[244:245] op_sel_hi:[1,0,1]
	ds_read_b128 v[88:91], v72 offset:11264
	ds_read_b128 v[92:95], v72 offset:11280
	v_pk_fma_f32 v[244:245], v[230:231], v[154:155], v[244:245] op_sel:[0,1,0] op_sel_hi:[1,1,1]
	ds_read_b128 v[80:83], v72 offset:3072
	ds_read_b128 v[84:87], v72 offset:3088
	s_waitcnt lgkmcnt(15)
	v_pk_fma_f32 v[244:245], v[232:233], v[156:157], v[244:245] op_sel_hi:[1,0,1]
	ds_read_b32 v200, v73 offset:44032
	ds_read_b32 v201, v73 offset:44064
	v_pk_fma_f32 v[244:245], v[234:235], v[156:157], v[244:245] op_sel:[0,1,0] op_sel_hi:[1,1,1]
	ds_read_b128 v[104:107], v72 offset:27648
	ds_read_b128 v[108:111], v72 offset:27664
	v_pk_fma_f32 v[244:245], v[236:237], v[158:159], v[244:245] op_sel_hi:[1,0,1]
	ds_read_b128 v[96:99], v72 offset:19456
	ds_read_b128 v[100:103], v72 offset:19472
	v_pk_fma_f32 v[244:245], v[238:239], v[158:159], v[244:245] op_sel:[0,1,0] op_sel_hi:[1,1,1]
	ds_read_b128 v[112:115], v72 offset:35840
	ds_read_b128 v[116:119], v72 offset:35856
	v_pk_mul_f32 v[240:241], v[224:225], v[168:169] op_sel_hi:[1,0]
	s_waitcnt lgkmcnt(15)
	v_pk_mul_f32 v[208:209], v[224:225], v[160:161] op_sel_hi:[1,0]
	v_pk_mul_f32 v[210:211], v[226:227], v[160:161] op_sel:[0,1] op_sel_hi:[1,1]
	v_pk_fma_f32 v[240:241], v[226:227], v[168:169], v[240:241] op_sel:[0,1,0] op_sel_hi:[1,1,1]
	v_pk_mul_f32 v[212:213], v[228:229], v[162:163] op_sel_hi:[1,0]
	v_pk_mul_f32 v[214:215], v[230:231], v[162:163] op_sel:[0,1] op_sel_hi:[1,1]
	v_pk_fma_f32 v[240:241], v[228:229], v[170:171], v[240:241] op_sel_hi:[1,0,1]
	v_pk_mul_f32 v[216:217], v[232:233], v[164:165] op_sel_hi:[1,0]
	v_pk_mul_f32 v[218:219], v[234:235], v[164:165] op_sel:[0,1] op_sel_hi:[1,1]
	v_pk_fma_f32 v[240:241], v[230:231], v[170:171], v[240:241] op_sel:[0,1,0] op_sel_hi:[1,1,1]
	v_pk_mul_f32 v[220:221], v[236:237], v[166:167] op_sel_hi:[1,0]
	v_pk_mul_f32 v[222:223], v[238:239], v[166:167] op_sel:[0,1] op_sel_hi:[1,1]
	v_pk_fma_f32 v[240:241], v[232:233], v[172:173], v[240:241] op_sel_hi:[1,0,1]
	v_pk_fma_f32 v[208:209], v[204:205], v[184:185], v[208:209] op_sel_hi:[1,0,1]
	v_pk_fma_f32 v[210:211], v[204:205], v[184:185], v[210:211] op_sel:[0,1,0] op_sel_hi:[1,1,1]
	v_pk_fma_f32 v[240:241], v[234:235], v[172:173], v[240:241] op_sel:[0,1,0] op_sel_hi:[1,1,1]
	v_pk_fma_f32 v[212:213], v[204:205], v[186:187], v[212:213] op_sel_hi:[1,0,1]
	v_pk_fma_f32 v[214:215], v[204:205], v[186:187], v[214:215] op_sel:[0,1,0] op_sel_hi:[1,1,1]
	v_pk_fma_f32 v[240:241], v[236:237], v[174:175], v[240:241] op_sel_hi:[1,0,1]
	v_pk_fma_f32 v[216:217], v[204:205], v[188:189], v[216:217] op_sel_hi:[1,0,1]
	v_pk_fma_f32 v[218:219], v[204:205], v[188:189], v[218:219] op_sel:[0,1,0] op_sel_hi:[1,1,1]
	v_pk_fma_f32 v[240:241], v[238:239], v[174:175], v[240:241] op_sel:[0,1,0] op_sel_hi:[1,1,1]
	v_pk_fma_f32 v[220:221], v[204:205], v[190:191], v[220:221] op_sel_hi:[1,0,1]
	v_pk_fma_f32 v[222:223], v[204:205], v[190:191], v[222:223] op_sel:[0,1,0] op_sel_hi:[1,1,1]
	v_add_f32_dpp v240, v240, v240 quad_perm:[1,0,3,2] row_mask:0xf bank_mask:0xf bound_ctrl:1
	v_add_f32_dpp v241, v241, v241 quad_perm:[1,0,3,2] row_mask:0xf bank_mask:0xf bound_ctrl:1
	v_add_f32_dpp v244, v244, v244 quad_perm:[1,0,3,2] row_mask:0xf bank_mask:0xf bound_ctrl:1
	v_add_f32_dpp v240, v240, v240 quad_perm:[2,3,0,1] row_mask:0xf bank_mask:0xf bound_ctrl:1
	v_add_f32_dpp v241, v241, v241 quad_perm:[2,3,0,1] row_mask:0xf bank_mask:0xf bound_ctrl:1
	v_add_f32_dpp v245, v245, v245 quad_perm:[1,0,3,2] row_mask:0xf bank_mask:0xf bound_ctrl:1
	v_add_f32_dpp v248, v240, v240 row_half_mirror row_mask:0xf bank_mask:0xf bound_ctrl:1
	v_add_f32_dpp v249, v241, v241 row_half_mirror row_mask:0xf bank_mask:0xf bound_ctrl:1
	v_add_f32_dpp v244, v244, v244 quad_perm:[2,3,0,1] row_mask:0xf bank_mask:0xf bound_ctrl:1
	v_add_f32_dpp v245, v245, v245 quad_perm:[2,3,0,1] row_mask:0xf bank_mask:0xf bound_ctrl:1
	v_pk_fma_f32 v[208:209], v[248:249], v[176:177], v[208:209] op_sel_hi:[1,0,1]
	v_pk_fma_f32 v[210:211], v[248:249], v[176:177], v[210:211] op_sel:[0,1,0] op_sel_hi:[1,1,1]
	v_add_f32_dpp v244, v244, v244 row_half_mirror row_mask:0xf bank_mask:0xf bound_ctrl:1
	v_add_f32_dpp v245, v245, v245 row_half_mirror row_mask:0xf bank_mask:0xf bound_ctrl:1
	v_pk_fma_f32 v[212:213], v[248:249], v[178:179], v[212:213] op_sel_hi:[1,0,1]
	v_cndmask_b32_e64 v75, v75, v244, s[10:11]
	v_cndmask_b32_e64 v76, v76, v245, s[10:11]
	v_pk_fma_f32 v[214:215], v[248:249], v[178:179], v[214:215] op_sel:[0,1,0] op_sel_hi:[1,1,1]
	s_waitcnt lgkmcnt(13)
	v_pk_mul_f32 v[244:245], v[208:209], v[192:193] op_sel_hi:[1,0]
	v_pk_fma_f32 v[216:217], v[248:249], v[180:181], v[216:217] op_sel_hi:[1,0,1]
	v_pk_fma_f32 v[218:219], v[248:249], v[180:181], v[218:219] op_sel:[0,1,0] op_sel_hi:[1,1,1]
	v_pk_fma_f32 v[244:245], v[210:211], v[192:193], v[244:245] op_sel:[0,1,0] op_sel_hi:[1,1,1]
	v_pk_fma_f32 v[220:221], v[248:249], v[182:183], v[220:221] op_sel_hi:[1,0,1]
	v_pk_fma_f32 v[222:223], v[248:249], v[182:183], v[222:223] op_sel:[0,1,0] op_sel_hi:[1,1,1]
	v_pk_fma_f32 v[244:245], v[212:213], v[194:195], v[244:245] op_sel_hi:[1,0,1]
	ds_read_b128 v[128:131], v72 offset:11520
	ds_read_b128 v[132:135], v72 offset:11536
	v_pk_fma_f32 v[244:245], v[214:215], v[194:195], v[244:245] op_sel:[0,1,0] op_sel_hi:[1,1,1]
	ds_read_b128 v[120:123], v72 offset:3328
	ds_read_b128 v[124:127], v72 offset:3344
	s_waitcnt lgkmcnt(15)
	v_pk_fma_f32 v[244:245], v[216:217], v[196:197], v[244:245] op_sel_hi:[1,0,1]
	ds_read_b32 v202, v73 offset:44288
	ds_read_b32 v203, v73 offset:44320
	v_pk_fma_f32 v[244:245], v[218:219], v[196:197], v[244:245] op_sel:[0,1,0] op_sel_hi:[1,1,1]
	ds_read_b128 v[144:147], v72 offset:27904
	ds_read_b128 v[148:151], v72 offset:27920
	v_pk_fma_f32 v[244:245], v[220:221], v[198:199], v[244:245] op_sel_hi:[1,0,1]
	ds_read_b128 v[136:139], v72 offset:19712
	ds_read_b128 v[140:143], v72 offset:19728
	v_pk_fma_f32 v[244:245], v[222:223], v[198:199], v[244:245] op_sel:[0,1,0] op_sel_hi:[1,1,1]
	ds_read_b128 v[152:155], v72 offset:36096
	ds_read_b128 v[156:159], v72 offset:36112
	v_pk_mul_f32 v[240:241], v[208:209], v[88:89] op_sel_hi:[1,0]
	s_waitcnt lgkmcnt(15)
	v_pk_mul_f32 v[224:225], v[208:209], v[80:81] op_sel_hi:[1,0]
	v_pk_mul_f32 v[226:227], v[210:211], v[80:81] op_sel:[0,1] op_sel_hi:[1,1]
	v_pk_fma_f32 v[240:241], v[210:211], v[88:89], v[240:241] op_sel:[0,1,0] op_sel_hi:[1,1,1]
	v_pk_mul_f32 v[228:229], v[212:213], v[82:83] op_sel_hi:[1,0]
	v_pk_mul_f32 v[230:231], v[214:215], v[82:83] op_sel:[0,1] op_sel_hi:[1,1]
	v_pk_fma_f32 v[240:241], v[212:213], v[90:91], v[240:241] op_sel_hi:[1,0,1]
	v_pk_mul_f32 v[232:233], v[216:217], v[84:85] op_sel_hi:[1,0]
	v_pk_mul_f32 v[234:235], v[218:219], v[84:85] op_sel:[0,1] op_sel_hi:[1,1]
	v_pk_fma_f32 v[240:241], v[214:215], v[90:91], v[240:241] op_sel:[0,1,0] op_sel_hi:[1,1,1]
	v_pk_mul_f32 v[236:237], v[220:221], v[86:87] op_sel_hi:[1,0]
	v_pk_mul_f32 v[238:239], v[222:223], v[86:87] op_sel:[0,1] op_sel_hi:[1,1]
	v_pk_fma_f32 v[240:241], v[216:217], v[92:93], v[240:241] op_sel_hi:[1,0,1]
	v_pk_fma_f32 v[224:225], v[200:201], v[104:105], v[224:225] op_sel_hi:[1,0,1]
	v_pk_fma_f32 v[226:227], v[200:201], v[104:105], v[226:227] op_sel:[0,1,0] op_sel_hi:[1,1,1]
	v_pk_fma_f32 v[240:241], v[218:219], v[92:93], v[240:241] op_sel:[0,1,0] op_sel_hi:[1,1,1]
	v_pk_fma_f32 v[228:229], v[200:201], v[106:107], v[228:229] op_sel_hi:[1,0,1]
	v_pk_fma_f32 v[230:231], v[200:201], v[106:107], v[230:231] op_sel:[0,1,0] op_sel_hi:[1,1,1]
	v_pk_fma_f32 v[240:241], v[220:221], v[94:95], v[240:241] op_sel_hi:[1,0,1]
	v_pk_fma_f32 v[232:233], v[200:201], v[108:109], v[232:233] op_sel_hi:[1,0,1]
	v_pk_fma_f32 v[234:235], v[200:201], v[108:109], v[234:235] op_sel:[0,1,0] op_sel_hi:[1,1,1]
	v_pk_fma_f32 v[240:241], v[222:223], v[94:95], v[240:241] op_sel:[0,1,0] op_sel_hi:[1,1,1]
	v_pk_fma_f32 v[236:237], v[200:201], v[110:111], v[236:237] op_sel_hi:[1,0,1]
	v_pk_fma_f32 v[238:239], v[200:201], v[110:111], v[238:239] op_sel:[0,1,0] op_sel_hi:[1,1,1]
	v_add_f32_dpp v240, v240, v240 quad_perm:[1,0,3,2] row_mask:0xf bank_mask:0xf bound_ctrl:1
	v_add_f32_dpp v241, v241, v241 quad_perm:[1,0,3,2] row_mask:0xf bank_mask:0xf bound_ctrl:1
	v_add_f32_dpp v244, v244, v244 quad_perm:[1,0,3,2] row_mask:0xf bank_mask:0xf bound_ctrl:1
	v_add_f32_dpp v240, v240, v240 quad_perm:[2,3,0,1] row_mask:0xf bank_mask:0xf bound_ctrl:1
	v_add_f32_dpp v241, v241, v241 quad_perm:[2,3,0,1] row_mask:0xf bank_mask:0xf bound_ctrl:1
	v_add_f32_dpp v245, v245, v245 quad_perm:[1,0,3,2] row_mask:0xf bank_mask:0xf bound_ctrl:1
	v_add_f32_dpp v248, v240, v240 row_half_mirror row_mask:0xf bank_mask:0xf bound_ctrl:1
	v_add_f32_dpp v249, v241, v241 row_half_mirror row_mask:0xf bank_mask:0xf bound_ctrl:1
	v_add_f32_dpp v244, v244, v244 quad_perm:[2,3,0,1] row_mask:0xf bank_mask:0xf bound_ctrl:1
	v_add_f32_dpp v245, v245, v245 quad_perm:[2,3,0,1] row_mask:0xf bank_mask:0xf bound_ctrl:1
	v_pk_fma_f32 v[224:225], v[248:249], v[96:97], v[224:225] op_sel_hi:[1,0,1]
	v_pk_fma_f32 v[226:227], v[248:249], v[96:97], v[226:227] op_sel:[0,1,0] op_sel_hi:[1,1,1]
	v_add_f32_dpp v244, v244, v244 row_half_mirror row_mask:0xf bank_mask:0xf bound_ctrl:1
	v_add_f32_dpp v245, v245, v245 row_half_mirror row_mask:0xf bank_mask:0xf bound_ctrl:1
	v_pk_fma_f32 v[228:229], v[248:249], v[98:99], v[228:229] op_sel_hi:[1,0,1]
	v_cndmask_b32_e64 v75, v75, v244, s[12:13]
	v_cndmask_b32_e64 v76, v76, v245, s[12:13]
	v_pk_fma_f32 v[230:231], v[248:249], v[98:99], v[230:231] op_sel:[0,1,0] op_sel_hi:[1,1,1]
	s_waitcnt lgkmcnt(13)
	v_pk_mul_f32 v[244:245], v[224:225], v[112:113] op_sel_hi:[1,0]
	v_pk_fma_f32 v[232:233], v[248:249], v[100:101], v[232:233] op_sel_hi:[1,0,1]
	v_pk_fma_f32 v[234:235], v[248:249], v[100:101], v[234:235] op_sel:[0,1,0] op_sel_hi:[1,1,1]
	v_pk_fma_f32 v[244:245], v[226:227], v[112:113], v[244:245] op_sel:[0,1,0] op_sel_hi:[1,1,1]
	v_pk_fma_f32 v[236:237], v[248:249], v[102:103], v[236:237] op_sel_hi:[1,0,1]
	v_pk_fma_f32 v[238:239], v[248:249], v[102:103], v[238:239] op_sel:[0,1,0] op_sel_hi:[1,1,1]
	v_pk_fma_f32 v[244:245], v[228:229], v[114:115], v[244:245] op_sel_hi:[1,0,1]
	ds_read_b128 v[168:171], v72 offset:11776
	ds_read_b128 v[172:175], v72 offset:11792
	v_pk_fma_f32 v[244:245], v[230:231], v[114:115], v[244:245] op_sel:[0,1,0] op_sel_hi:[1,1,1]
	ds_read_b128 v[160:163], v72 offset:3584
	ds_read_b128 v[164:167], v72 offset:3600
	s_waitcnt lgkmcnt(15)
	v_pk_fma_f32 v[244:245], v[232:233], v[116:117], v[244:245] op_sel_hi:[1,0,1]
	ds_read_b32 v204, v73 offset:44544
	ds_read_b32 v205, v73 offset:44576
	v_pk_fma_f32 v[244:245], v[234:235], v[116:117], v[244:245] op_sel:[0,1,0] op_sel_hi:[1,1,1]
	ds_read_b128 v[184:187], v72 offset:28160
	ds_read_b128 v[188:191], v72 offset:28176
	v_pk_fma_f32 v[244:245], v[236:237], v[118:119], v[244:245] op_sel_hi:[1,0,1]
	ds_read_b128 v[176:179], v72 offset:19968
	ds_read_b128 v[180:183], v72 offset:19984
	v_pk_fma_f32 v[244:245], v[238:239], v[118:119], v[244:245] op_sel:[0,1,0] op_sel_hi:[1,1,1]
	ds_read_b128 v[192:195], v72 offset:36352
	ds_read_b128 v[196:199], v72 offset:36368
	v_pk_mul_f32 v[240:241], v[224:225], v[128:129] op_sel_hi:[1,0]
	s_waitcnt lgkmcnt(15)
	v_pk_mul_f32 v[208:209], v[224:225], v[120:121] op_sel_hi:[1,0]
	v_pk_mul_f32 v[210:211], v[226:227], v[120:121] op_sel:[0,1] op_sel_hi:[1,1]
	v_pk_fma_f32 v[240:241], v[226:227], v[128:129], v[240:241] op_sel:[0,1,0] op_sel_hi:[1,1,1]
	v_pk_mul_f32 v[212:213], v[228:229], v[122:123] op_sel_hi:[1,0]
	v_pk_mul_f32 v[214:215], v[230:231], v[122:123] op_sel:[0,1] op_sel_hi:[1,1]
	v_pk_fma_f32 v[240:241], v[228:229], v[130:131], v[240:241] op_sel_hi:[1,0,1]
	v_pk_mul_f32 v[216:217], v[232:233], v[124:125] op_sel_hi:[1,0]
	v_pk_mul_f32 v[218:219], v[234:235], v[124:125] op_sel:[0,1] op_sel_hi:[1,1]
	v_pk_fma_f32 v[240:241], v[230:231], v[130:131], v[240:241] op_sel:[0,1,0] op_sel_hi:[1,1,1]
	v_pk_mul_f32 v[220:221], v[236:237], v[126:127] op_sel_hi:[1,0]
	v_pk_mul_f32 v[222:223], v[238:239], v[126:127] op_sel:[0,1] op_sel_hi:[1,1]
	v_pk_fma_f32 v[240:241], v[232:233], v[132:133], v[240:241] op_sel_hi:[1,0,1]
	v_pk_fma_f32 v[208:209], v[202:203], v[144:145], v[208:209] op_sel_hi:[1,0,1]
	v_pk_fma_f32 v[210:211], v[202:203], v[144:145], v[210:211] op_sel:[0,1,0] op_sel_hi:[1,1,1]
	v_pk_fma_f32 v[240:241], v[234:235], v[132:133], v[240:241] op_sel:[0,1,0] op_sel_hi:[1,1,1]
	v_pk_fma_f32 v[212:213], v[202:203], v[146:147], v[212:213] op_sel_hi:[1,0,1]
	v_pk_fma_f32 v[214:215], v[202:203], v[146:147], v[214:215] op_sel:[0,1,0] op_sel_hi:[1,1,1]
	v_pk_fma_f32 v[240:241], v[236:237], v[134:135], v[240:241] op_sel_hi:[1,0,1]
	v_pk_fma_f32 v[216:217], v[202:203], v[148:149], v[216:217] op_sel_hi:[1,0,1]
	v_pk_fma_f32 v[218:219], v[202:203], v[148:149], v[218:219] op_sel:[0,1,0] op_sel_hi:[1,1,1]
	v_pk_fma_f32 v[240:241], v[238:239], v[134:135], v[240:241] op_sel:[0,1,0] op_sel_hi:[1,1,1]
	v_pk_fma_f32 v[220:221], v[202:203], v[150:151], v[220:221] op_sel_hi:[1,0,1]
	v_pk_fma_f32 v[222:223], v[202:203], v[150:151], v[222:223] op_sel:[0,1,0] op_sel_hi:[1,1,1]
	v_add_f32_dpp v240, v240, v240 quad_perm:[1,0,3,2] row_mask:0xf bank_mask:0xf bound_ctrl:1
	v_add_f32_dpp v241, v241, v241 quad_perm:[1,0,3,2] row_mask:0xf bank_mask:0xf bound_ctrl:1
	v_add_f32_dpp v244, v244, v244 quad_perm:[1,0,3,2] row_mask:0xf bank_mask:0xf bound_ctrl:1
	v_add_f32_dpp v240, v240, v240 quad_perm:[2,3,0,1] row_mask:0xf bank_mask:0xf bound_ctrl:1
	v_add_f32_dpp v241, v241, v241 quad_perm:[2,3,0,1] row_mask:0xf bank_mask:0xf bound_ctrl:1
	v_add_f32_dpp v245, v245, v245 quad_perm:[1,0,3,2] row_mask:0xf bank_mask:0xf bound_ctrl:1
	v_add_f32_dpp v248, v240, v240 row_half_mirror row_mask:0xf bank_mask:0xf bound_ctrl:1
	v_add_f32_dpp v249, v241, v241 row_half_mirror row_mask:0xf bank_mask:0xf bound_ctrl:1
	v_add_f32_dpp v244, v244, v244 quad_perm:[2,3,0,1] row_mask:0xf bank_mask:0xf bound_ctrl:1
	v_add_f32_dpp v245, v245, v245 quad_perm:[2,3,0,1] row_mask:0xf bank_mask:0xf bound_ctrl:1
	v_pk_fma_f32 v[208:209], v[248:249], v[136:137], v[208:209] op_sel_hi:[1,0,1]
	v_pk_fma_f32 v[210:211], v[248:249], v[136:137], v[210:211] op_sel:[0,1,0] op_sel_hi:[1,1,1]
	v_add_f32_dpp v244, v244, v244 row_half_mirror row_mask:0xf bank_mask:0xf bound_ctrl:1
	v_add_f32_dpp v245, v245, v245 row_half_mirror row_mask:0xf bank_mask:0xf bound_ctrl:1
	v_pk_fma_f32 v[212:213], v[248:249], v[138:139], v[212:213] op_sel_hi:[1,0,1]
	v_cndmask_b32_e64 v75, v75, v244, s[14:15]
	v_cndmask_b32_e64 v76, v76, v245, s[14:15]
	v_pk_fma_f32 v[214:215], v[248:249], v[138:139], v[214:215] op_sel:[0,1,0] op_sel_hi:[1,1,1]
	s_waitcnt lgkmcnt(13)
	v_pk_mul_f32 v[244:245], v[208:209], v[152:153] op_sel_hi:[1,0]
	v_pk_fma_f32 v[216:217], v[248:249], v[140:141], v[216:217] op_sel_hi:[1,0,1]
	v_pk_fma_f32 v[218:219], v[248:249], v[140:141], v[218:219] op_sel:[0,1,0] op_sel_hi:[1,1,1]
	v_pk_fma_f32 v[244:245], v[210:211], v[152:153], v[244:245] op_sel:[0,1,0] op_sel_hi:[1,1,1]
	v_pk_fma_f32 v[220:221], v[248:249], v[142:143], v[220:221] op_sel_hi:[1,0,1]
	v_pk_fma_f32 v[222:223], v[248:249], v[142:143], v[222:223] op_sel:[0,1,0] op_sel_hi:[1,1,1]
	v_pk_fma_f32 v[244:245], v[212:213], v[154:155], v[244:245] op_sel_hi:[1,0,1]
	ds_read_b128 v[88:91], v72 offset:12032
	ds_read_b128 v[92:95], v72 offset:12048
	v_pk_fma_f32 v[244:245], v[214:215], v[154:155], v[244:245] op_sel:[0,1,0] op_sel_hi:[1,1,1]
	ds_read_b128 v[80:83], v72 offset:3840
	ds_read_b128 v[84:87], v72 offset:3856
	s_waitcnt lgkmcnt(15)
	v_pk_fma_f32 v[244:245], v[216:217], v[156:157], v[244:245] op_sel_hi:[1,0,1]
	ds_read_b32 v200, v73 offset:44800
	ds_read_b32 v201, v73 offset:44832
	v_pk_fma_f32 v[244:245], v[218:219], v[156:157], v[244:245] op_sel:[0,1,0] op_sel_hi:[1,1,1]
	ds_read_b128 v[104:107], v72 offset:28416
	ds_read_b128 v[108:111], v72 offset:28432
	v_pk_fma_f32 v[244:245], v[220:221], v[158:159], v[244:245] op_sel_hi:[1,0,1]
	ds_read_b128 v[96:99], v72 offset:20224
	ds_read_b128 v[100:103], v72 offset:20240
	v_pk_fma_f32 v[244:245], v[222:223], v[158:159], v[244:245] op_sel:[0,1,0] op_sel_hi:[1,1,1]
	ds_read_b128 v[112:115], v72 offset:36608
	ds_read_b128 v[116:119], v72 offset:36624
	v_pk_mul_f32 v[240:241], v[208:209], v[168:169] op_sel_hi:[1,0]
	s_waitcnt lgkmcnt(15)
	v_pk_mul_f32 v[224:225], v[208:209], v[160:161] op_sel_hi:[1,0]
	v_pk_mul_f32 v[226:227], v[210:211], v[160:161] op_sel:[0,1] op_sel_hi:[1,1]
	v_pk_fma_f32 v[240:241], v[210:211], v[168:169], v[240:241] op_sel:[0,1,0] op_sel_hi:[1,1,1]
	v_pk_mul_f32 v[228:229], v[212:213], v[162:163] op_sel_hi:[1,0]
	v_pk_mul_f32 v[230:231], v[214:215], v[162:163] op_sel:[0,1] op_sel_hi:[1,1]
	v_pk_fma_f32 v[240:241], v[212:213], v[170:171], v[240:241] op_sel_hi:[1,0,1]
	v_pk_mul_f32 v[232:233], v[216:217], v[164:165] op_sel_hi:[1,0]
	v_pk_mul_f32 v[234:235], v[218:219], v[164:165] op_sel:[0,1] op_sel_hi:[1,1]
	v_pk_fma_f32 v[240:241], v[214:215], v[170:171], v[240:241] op_sel:[0,1,0] op_sel_hi:[1,1,1]
	v_pk_mul_f32 v[236:237], v[220:221], v[166:167] op_sel_hi:[1,0]
	v_pk_mul_f32 v[238:239], v[222:223], v[166:167] op_sel:[0,1] op_sel_hi:[1,1]
	v_pk_fma_f32 v[240:241], v[216:217], v[172:173], v[240:241] op_sel_hi:[1,0,1]
	v_pk_fma_f32 v[224:225], v[204:205], v[184:185], v[224:225] op_sel_hi:[1,0,1]
	v_pk_fma_f32 v[226:227], v[204:205], v[184:185], v[226:227] op_sel:[0,1,0] op_sel_hi:[1,1,1]
	v_pk_fma_f32 v[240:241], v[218:219], v[172:173], v[240:241] op_sel:[0,1,0] op_sel_hi:[1,1,1]
	v_pk_fma_f32 v[228:229], v[204:205], v[186:187], v[228:229] op_sel_hi:[1,0,1]
	v_pk_fma_f32 v[230:231], v[204:205], v[186:187], v[230:231] op_sel:[0,1,0] op_sel_hi:[1,1,1]
	v_pk_fma_f32 v[240:241], v[220:221], v[174:175], v[240:241] op_sel_hi:[1,0,1]
	v_pk_fma_f32 v[232:233], v[204:205], v[188:189], v[232:233] op_sel_hi:[1,0,1]
	v_pk_fma_f32 v[234:235], v[204:205], v[188:189], v[234:235] op_sel:[0,1,0] op_sel_hi:[1,1,1]
	v_pk_fma_f32 v[240:241], v[222:223], v[174:175], v[240:241] op_sel:[0,1,0] op_sel_hi:[1,1,1]
	v_pk_fma_f32 v[236:237], v[204:205], v[190:191], v[236:237] op_sel_hi:[1,0,1]
	v_pk_fma_f32 v[238:239], v[204:205], v[190:191], v[238:239] op_sel:[0,1,0] op_sel_hi:[1,1,1]
	v_add_f32_dpp v240, v240, v240 quad_perm:[1,0,3,2] row_mask:0xf bank_mask:0xf bound_ctrl:1
	v_add_f32_dpp v241, v241, v241 quad_perm:[1,0,3,2] row_mask:0xf bank_mask:0xf bound_ctrl:1
	v_add_f32_dpp v244, v244, v244 quad_perm:[1,0,3,2] row_mask:0xf bank_mask:0xf bound_ctrl:1
	v_add_f32_dpp v240, v240, v240 quad_perm:[2,3,0,1] row_mask:0xf bank_mask:0xf bound_ctrl:1
	v_add_f32_dpp v241, v241, v241 quad_perm:[2,3,0,1] row_mask:0xf bank_mask:0xf bound_ctrl:1
	v_add_f32_dpp v245, v245, v245 quad_perm:[1,0,3,2] row_mask:0xf bank_mask:0xf bound_ctrl:1
	v_add_f32_dpp v248, v240, v240 row_half_mirror row_mask:0xf bank_mask:0xf bound_ctrl:1
	v_add_f32_dpp v249, v241, v241 row_half_mirror row_mask:0xf bank_mask:0xf bound_ctrl:1
	v_add_f32_dpp v244, v244, v244 quad_perm:[2,3,0,1] row_mask:0xf bank_mask:0xf bound_ctrl:1
	v_add_f32_dpp v245, v245, v245 quad_perm:[2,3,0,1] row_mask:0xf bank_mask:0xf bound_ctrl:1
	v_pk_fma_f32 v[224:225], v[248:249], v[176:177], v[224:225] op_sel_hi:[1,0,1]
	v_pk_fma_f32 v[226:227], v[248:249], v[176:177], v[226:227] op_sel:[0,1,0] op_sel_hi:[1,1,1]
	v_add_f32_dpp v244, v244, v244 row_half_mirror row_mask:0xf bank_mask:0xf bound_ctrl:1
	v_add_f32_dpp v245, v245, v245 row_half_mirror row_mask:0xf bank_mask:0xf bound_ctrl:1
	v_pk_fma_f32 v[228:229], v[248:249], v[178:179], v[228:229] op_sel_hi:[1,0,1]
	v_cndmask_b32_e64 v75, v75, v244, s[16:17]
	v_cndmask_b32_e64 v76, v76, v245, s[16:17]
	v_pk_fma_f32 v[230:231], v[248:249], v[178:179], v[230:231] op_sel:[0,1,0] op_sel_hi:[1,1,1]
	s_waitcnt lgkmcnt(13)
	v_pk_mul_f32 v[244:245], v[224:225], v[192:193] op_sel_hi:[1,0]
	v_pk_fma_f32 v[232:233], v[248:249], v[180:181], v[232:233] op_sel_hi:[1,0,1]
	v_pk_fma_f32 v[234:235], v[248:249], v[180:181], v[234:235] op_sel:[0,1,0] op_sel_hi:[1,1,1]
	v_pk_fma_f32 v[244:245], v[226:227], v[192:193], v[244:245] op_sel:[0,1,0] op_sel_hi:[1,1,1]
	v_pk_fma_f32 v[236:237], v[248:249], v[182:183], v[236:237] op_sel_hi:[1,0,1]
	v_pk_fma_f32 v[238:239], v[248:249], v[182:183], v[238:239] op_sel:[0,1,0] op_sel_hi:[1,1,1]
	v_pk_fma_f32 v[244:245], v[228:229], v[194:195], v[244:245] op_sel_hi:[1,0,1]
	ds_read_b128 v[128:131], v72 offset:12288
	ds_read_b128 v[132:135], v72 offset:12304
	v_pk_fma_f32 v[244:245], v[230:231], v[194:195], v[244:245] op_sel:[0,1,0] op_sel_hi:[1,1,1]
	ds_read_b128 v[120:123], v72 offset:4096
	ds_read_b128 v[124:127], v72 offset:4112
	s_waitcnt lgkmcnt(15)
	v_pk_fma_f32 v[244:245], v[232:233], v[196:197], v[244:245] op_sel_hi:[1,0,1]
	ds_read_b32 v202, v73 offset:45056
	ds_read_b32 v203, v73 offset:45088
	v_pk_fma_f32 v[244:245], v[234:235], v[196:197], v[244:245] op_sel:[0,1,0] op_sel_hi:[1,1,1]
	ds_read_b128 v[144:147], v72 offset:28672
	ds_read_b128 v[148:151], v72 offset:28688
	v_pk_fma_f32 v[244:245], v[236:237], v[198:199], v[244:245] op_sel_hi:[1,0,1]
	ds_read_b128 v[136:139], v72 offset:20480
	ds_read_b128 v[140:143], v72 offset:20496
	v_pk_fma_f32 v[244:245], v[238:239], v[198:199], v[244:245] op_sel:[0,1,0] op_sel_hi:[1,1,1]
	ds_read_b128 v[152:155], v72 offset:36864
	ds_read_b128 v[156:159], v72 offset:36880
	v_pk_mul_f32 v[240:241], v[224:225], v[88:89] op_sel_hi:[1,0]
	s_waitcnt lgkmcnt(15)
	v_pk_mul_f32 v[208:209], v[224:225], v[80:81] op_sel_hi:[1,0]
	v_pk_mul_f32 v[210:211], v[226:227], v[80:81] op_sel:[0,1] op_sel_hi:[1,1]
	v_pk_fma_f32 v[240:241], v[226:227], v[88:89], v[240:241] op_sel:[0,1,0] op_sel_hi:[1,1,1]
	v_pk_mul_f32 v[212:213], v[228:229], v[82:83] op_sel_hi:[1,0]
	v_pk_mul_f32 v[214:215], v[230:231], v[82:83] op_sel:[0,1] op_sel_hi:[1,1]
	v_pk_fma_f32 v[240:241], v[228:229], v[90:91], v[240:241] op_sel_hi:[1,0,1]
	v_pk_mul_f32 v[216:217], v[232:233], v[84:85] op_sel_hi:[1,0]
	v_pk_mul_f32 v[218:219], v[234:235], v[84:85] op_sel:[0,1] op_sel_hi:[1,1]
	v_pk_fma_f32 v[240:241], v[230:231], v[90:91], v[240:241] op_sel:[0,1,0] op_sel_hi:[1,1,1]
	v_pk_mul_f32 v[220:221], v[236:237], v[86:87] op_sel_hi:[1,0]
	v_pk_mul_f32 v[222:223], v[238:239], v[86:87] op_sel:[0,1] op_sel_hi:[1,1]
	v_pk_fma_f32 v[240:241], v[232:233], v[92:93], v[240:241] op_sel_hi:[1,0,1]
	v_pk_fma_f32 v[208:209], v[200:201], v[104:105], v[208:209] op_sel_hi:[1,0,1]
	v_pk_fma_f32 v[210:211], v[200:201], v[104:105], v[210:211] op_sel:[0,1,0] op_sel_hi:[1,1,1]
	v_pk_fma_f32 v[240:241], v[234:235], v[92:93], v[240:241] op_sel:[0,1,0] op_sel_hi:[1,1,1]
	v_pk_fma_f32 v[212:213], v[200:201], v[106:107], v[212:213] op_sel_hi:[1,0,1]
	v_pk_fma_f32 v[214:215], v[200:201], v[106:107], v[214:215] op_sel:[0,1,0] op_sel_hi:[1,1,1]
	v_pk_fma_f32 v[240:241], v[236:237], v[94:95], v[240:241] op_sel_hi:[1,0,1]
	v_pk_fma_f32 v[216:217], v[200:201], v[108:109], v[216:217] op_sel_hi:[1,0,1]
	v_pk_fma_f32 v[218:219], v[200:201], v[108:109], v[218:219] op_sel:[0,1,0] op_sel_hi:[1,1,1]
	v_pk_fma_f32 v[240:241], v[238:239], v[94:95], v[240:241] op_sel:[0,1,0] op_sel_hi:[1,1,1]
	v_pk_fma_f32 v[220:221], v[200:201], v[110:111], v[220:221] op_sel_hi:[1,0,1]
	v_pk_fma_f32 v[222:223], v[200:201], v[110:111], v[222:223] op_sel:[0,1,0] op_sel_hi:[1,1,1]
	v_add_f32_dpp v240, v240, v240 quad_perm:[1,0,3,2] row_mask:0xf bank_mask:0xf bound_ctrl:1
	v_add_f32_dpp v241, v241, v241 quad_perm:[1,0,3,2] row_mask:0xf bank_mask:0xf bound_ctrl:1
	v_add_f32_dpp v244, v244, v244 quad_perm:[1,0,3,2] row_mask:0xf bank_mask:0xf bound_ctrl:1
	v_add_f32_dpp v240, v240, v240 quad_perm:[2,3,0,1] row_mask:0xf bank_mask:0xf bound_ctrl:1
	v_add_f32_dpp v241, v241, v241 quad_perm:[2,3,0,1] row_mask:0xf bank_mask:0xf bound_ctrl:1
	v_add_f32_dpp v245, v245, v245 quad_perm:[1,0,3,2] row_mask:0xf bank_mask:0xf bound_ctrl:1
	v_add_f32_dpp v248, v240, v240 row_half_mirror row_mask:0xf bank_mask:0xf bound_ctrl:1
	v_add_f32_dpp v249, v241, v241 row_half_mirror row_mask:0xf bank_mask:0xf bound_ctrl:1
	v_add_f32_dpp v244, v244, v244 quad_perm:[2,3,0,1] row_mask:0xf bank_mask:0xf bound_ctrl:1
	v_add_f32_dpp v245, v245, v245 quad_perm:[2,3,0,1] row_mask:0xf bank_mask:0xf bound_ctrl:1
	v_pk_fma_f32 v[208:209], v[248:249], v[96:97], v[208:209] op_sel_hi:[1,0,1]
	v_pk_fma_f32 v[210:211], v[248:249], v[96:97], v[210:211] op_sel:[0,1,0] op_sel_hi:[1,1,1]
	v_add_f32_dpp v244, v244, v244 row_half_mirror row_mask:0xf bank_mask:0xf bound_ctrl:1
	v_add_f32_dpp v245, v245, v245 row_half_mirror row_mask:0xf bank_mask:0xf bound_ctrl:1
	v_pk_fma_f32 v[212:213], v[248:249], v[98:99], v[212:213] op_sel_hi:[1,0,1]
	v_cndmask_b32_e64 v75, v75, v244, s[18:19]
	v_cndmask_b32_e64 v76, v76, v245, s[18:19]
	v_pk_fma_f32 v[214:215], v[248:249], v[98:99], v[214:215] op_sel:[0,1,0] op_sel_hi:[1,1,1]
	s_waitcnt lgkmcnt(13)
	v_pk_mul_f32 v[244:245], v[208:209], v[112:113] op_sel_hi:[1,0]
	v_pk_fma_f32 v[216:217], v[248:249], v[100:101], v[216:217] op_sel_hi:[1,0,1]
	v_pk_fma_f32 v[218:219], v[248:249], v[100:101], v[218:219] op_sel:[0,1,0] op_sel_hi:[1,1,1]
	v_pk_fma_f32 v[244:245], v[210:211], v[112:113], v[244:245] op_sel:[0,1,0] op_sel_hi:[1,1,1]
	v_pk_fma_f32 v[220:221], v[248:249], v[102:103], v[220:221] op_sel_hi:[1,0,1]
	v_pk_fma_f32 v[222:223], v[248:249], v[102:103], v[222:223] op_sel:[0,1,0] op_sel_hi:[1,1,1]
	v_pk_fma_f32 v[244:245], v[212:213], v[114:115], v[244:245] op_sel_hi:[1,0,1]
	ds_read_b128 v[168:171], v72 offset:12544
	ds_read_b128 v[172:175], v72 offset:12560
	v_pk_fma_f32 v[244:245], v[214:215], v[114:115], v[244:245] op_sel:[0,1,0] op_sel_hi:[1,1,1]
	ds_read_b128 v[160:163], v72 offset:4352
	ds_read_b128 v[164:167], v72 offset:4368
	s_waitcnt lgkmcnt(15)
	v_pk_fma_f32 v[244:245], v[216:217], v[116:117], v[244:245] op_sel_hi:[1,0,1]
	ds_read_b32 v204, v73 offset:45312
	ds_read_b32 v205, v73 offset:45344
	v_pk_fma_f32 v[244:245], v[218:219], v[116:117], v[244:245] op_sel:[0,1,0] op_sel_hi:[1,1,1]
	ds_read_b128 v[184:187], v72 offset:28928
	ds_read_b128 v[188:191], v72 offset:28944
	v_pk_fma_f32 v[244:245], v[220:221], v[118:119], v[244:245] op_sel_hi:[1,0,1]
	ds_read_b128 v[176:179], v72 offset:20736
	ds_read_b128 v[180:183], v72 offset:20752
	v_pk_fma_f32 v[244:245], v[222:223], v[118:119], v[244:245] op_sel:[0,1,0] op_sel_hi:[1,1,1]
	ds_read_b128 v[192:195], v72 offset:37120
	ds_read_b128 v[196:199], v72 offset:37136
	v_pk_mul_f32 v[240:241], v[208:209], v[128:129] op_sel_hi:[1,0]
	s_waitcnt lgkmcnt(15)
	v_pk_mul_f32 v[224:225], v[208:209], v[120:121] op_sel_hi:[1,0]
	v_pk_mul_f32 v[226:227], v[210:211], v[120:121] op_sel:[0,1] op_sel_hi:[1,1]
	v_pk_fma_f32 v[240:241], v[210:211], v[128:129], v[240:241] op_sel:[0,1,0] op_sel_hi:[1,1,1]
	v_pk_mul_f32 v[228:229], v[212:213], v[122:123] op_sel_hi:[1,0]
	v_pk_mul_f32 v[230:231], v[214:215], v[122:123] op_sel:[0,1] op_sel_hi:[1,1]
	v_pk_fma_f32 v[240:241], v[212:213], v[130:131], v[240:241] op_sel_hi:[1,0,1]
	v_pk_mul_f32 v[232:233], v[216:217], v[124:125] op_sel_hi:[1,0]
	v_pk_mul_f32 v[234:235], v[218:219], v[124:125] op_sel:[0,1] op_sel_hi:[1,1]
	v_pk_fma_f32 v[240:241], v[214:215], v[130:131], v[240:241] op_sel:[0,1,0] op_sel_hi:[1,1,1]
	v_pk_mul_f32 v[236:237], v[220:221], v[126:127] op_sel_hi:[1,0]
	v_pk_mul_f32 v[238:239], v[222:223], v[126:127] op_sel:[0,1] op_sel_hi:[1,1]
	v_pk_fma_f32 v[240:241], v[216:217], v[132:133], v[240:241] op_sel_hi:[1,0,1]
	v_pk_fma_f32 v[224:225], v[202:203], v[144:145], v[224:225] op_sel_hi:[1,0,1]
	v_pk_fma_f32 v[226:227], v[202:203], v[144:145], v[226:227] op_sel:[0,1,0] op_sel_hi:[1,1,1]
	v_pk_fma_f32 v[240:241], v[218:219], v[132:133], v[240:241] op_sel:[0,1,0] op_sel_hi:[1,1,1]
	v_pk_fma_f32 v[228:229], v[202:203], v[146:147], v[228:229] op_sel_hi:[1,0,1]
	v_pk_fma_f32 v[230:231], v[202:203], v[146:147], v[230:231] op_sel:[0,1,0] op_sel_hi:[1,1,1]
	v_pk_fma_f32 v[240:241], v[220:221], v[134:135], v[240:241] op_sel_hi:[1,0,1]
	v_pk_fma_f32 v[232:233], v[202:203], v[148:149], v[232:233] op_sel_hi:[1,0,1]
	v_pk_fma_f32 v[234:235], v[202:203], v[148:149], v[234:235] op_sel:[0,1,0] op_sel_hi:[1,1,1]
	v_pk_fma_f32 v[240:241], v[222:223], v[134:135], v[240:241] op_sel:[0,1,0] op_sel_hi:[1,1,1]
	v_pk_fma_f32 v[236:237], v[202:203], v[150:151], v[236:237] op_sel_hi:[1,0,1]
	v_pk_fma_f32 v[238:239], v[202:203], v[150:151], v[238:239] op_sel:[0,1,0] op_sel_hi:[1,1,1]
	v_add_f32_dpp v240, v240, v240 quad_perm:[1,0,3,2] row_mask:0xf bank_mask:0xf bound_ctrl:1
	v_add_f32_dpp v241, v241, v241 quad_perm:[1,0,3,2] row_mask:0xf bank_mask:0xf bound_ctrl:1
	v_add_f32_dpp v244, v244, v244 quad_perm:[1,0,3,2] row_mask:0xf bank_mask:0xf bound_ctrl:1
	v_add_f32_dpp v240, v240, v240 quad_perm:[2,3,0,1] row_mask:0xf bank_mask:0xf bound_ctrl:1
	v_add_f32_dpp v241, v241, v241 quad_perm:[2,3,0,1] row_mask:0xf bank_mask:0xf bound_ctrl:1
	v_add_f32_dpp v245, v245, v245 quad_perm:[1,0,3,2] row_mask:0xf bank_mask:0xf bound_ctrl:1
	v_add_f32_dpp v248, v240, v240 row_half_mirror row_mask:0xf bank_mask:0xf bound_ctrl:1
	v_add_f32_dpp v249, v241, v241 row_half_mirror row_mask:0xf bank_mask:0xf bound_ctrl:1
	v_add_f32_dpp v244, v244, v244 quad_perm:[2,3,0,1] row_mask:0xf bank_mask:0xf bound_ctrl:1
	v_add_f32_dpp v245, v245, v245 quad_perm:[2,3,0,1] row_mask:0xf bank_mask:0xf bound_ctrl:1
	v_pk_fma_f32 v[224:225], v[248:249], v[136:137], v[224:225] op_sel_hi:[1,0,1]
	v_pk_fma_f32 v[226:227], v[248:249], v[136:137], v[226:227] op_sel:[0,1,0] op_sel_hi:[1,1,1]
	v_add_f32_dpp v244, v244, v244 row_half_mirror row_mask:0xf bank_mask:0xf bound_ctrl:1
	v_add_f32_dpp v245, v245, v245 row_half_mirror row_mask:0xf bank_mask:0xf bound_ctrl:1
	v_pk_fma_f32 v[228:229], v[248:249], v[138:139], v[228:229] op_sel_hi:[1,0,1]
	v_cndmask_b32_e64 v75, v75, v244, s[20:21]
	v_cndmask_b32_e64 v76, v76, v245, s[20:21]
	ds_write_b32 v74, v75 offset:2048
	ds_write_b32 v74, v76 offset:2080
	v_pk_fma_f32 v[230:231], v[248:249], v[138:139], v[230:231] op_sel:[0,1,0] op_sel_hi:[1,1,1]
	s_waitcnt lgkmcnt(15)
	v_pk_mul_f32 v[244:245], v[224:225], v[152:153] op_sel_hi:[1,0]
	v_pk_fma_f32 v[232:233], v[248:249], v[140:141], v[232:233] op_sel_hi:[1,0,1]
	v_pk_fma_f32 v[234:235], v[248:249], v[140:141], v[234:235] op_sel:[0,1,0] op_sel_hi:[1,1,1]
	v_pk_fma_f32 v[244:245], v[226:227], v[152:153], v[244:245] op_sel:[0,1,0] op_sel_hi:[1,1,1]
	v_pk_fma_f32 v[236:237], v[248:249], v[142:143], v[236:237] op_sel_hi:[1,0,1]
	v_pk_fma_f32 v[238:239], v[248:249], v[142:143], v[238:239] op_sel:[0,1,0] op_sel_hi:[1,1,1]
	v_pk_fma_f32 v[244:245], v[228:229], v[154:155], v[244:245] op_sel_hi:[1,0,1]
	ds_read_b128 v[88:91], v72 offset:12800
	ds_read_b128 v[92:95], v72 offset:12816
	v_pk_fma_f32 v[244:245], v[230:231], v[154:155], v[244:245] op_sel:[0,1,0] op_sel_hi:[1,1,1]
	ds_read_b128 v[80:83], v72 offset:4608
	ds_read_b128 v[84:87], v72 offset:4624
	s_waitcnt lgkmcnt(15)
	v_pk_fma_f32 v[244:245], v[232:233], v[156:157], v[244:245] op_sel_hi:[1,0,1]
	ds_read_b32 v200, v73 offset:45568
	ds_read_b32 v201, v73 offset:45600
	v_pk_fma_f32 v[244:245], v[234:235], v[156:157], v[244:245] op_sel:[0,1,0] op_sel_hi:[1,1,1]
	ds_read_b128 v[104:107], v72 offset:29184
	ds_read_b128 v[108:111], v72 offset:29200
	v_pk_fma_f32 v[244:245], v[236:237], v[158:159], v[244:245] op_sel_hi:[1,0,1]
	ds_read_b128 v[96:99], v72 offset:20992
	ds_read_b128 v[100:103], v72 offset:21008
	v_pk_fma_f32 v[244:245], v[238:239], v[158:159], v[244:245] op_sel:[0,1,0] op_sel_hi:[1,1,1]
	ds_read_b128 v[112:115], v72 offset:37376
	ds_read_b128 v[116:119], v72 offset:37392
	v_pk_mul_f32 v[240:241], v[224:225], v[168:169] op_sel_hi:[1,0]
	v_pk_mul_f32 v[208:209], v[224:225], v[160:161] op_sel_hi:[1,0]
	v_pk_mul_f32 v[210:211], v[226:227], v[160:161] op_sel:[0,1] op_sel_hi:[1,1]
	v_pk_fma_f32 v[240:241], v[226:227], v[168:169], v[240:241] op_sel:[0,1,0] op_sel_hi:[1,1,1]
	v_pk_mul_f32 v[212:213], v[228:229], v[162:163] op_sel_hi:[1,0]
	v_pk_mul_f32 v[214:215], v[230:231], v[162:163] op_sel:[0,1] op_sel_hi:[1,1]
	v_pk_fma_f32 v[240:241], v[228:229], v[170:171], v[240:241] op_sel_hi:[1,0,1]
	s_waitcnt lgkmcnt(15)
	v_pk_mul_f32 v[216:217], v[232:233], v[164:165] op_sel_hi:[1,0]
	v_pk_mul_f32 v[218:219], v[234:235], v[164:165] op_sel:[0,1] op_sel_hi:[1,1]
	v_pk_fma_f32 v[240:241], v[230:231], v[170:171], v[240:241] op_sel:[0,1,0] op_sel_hi:[1,1,1]
	v_pk_mul_f32 v[220:221], v[236:237], v[166:167] op_sel_hi:[1,0]
	v_pk_mul_f32 v[222:223], v[238:239], v[166:167] op_sel:[0,1] op_sel_hi:[1,1]
	v_pk_fma_f32 v[240:241], v[232:233], v[172:173], v[240:241] op_sel_hi:[1,0,1]
	v_pk_fma_f32 v[208:209], v[204:205], v[184:185], v[208:209] op_sel_hi:[1,0,1]
	v_pk_fma_f32 v[210:211], v[204:205], v[184:185], v[210:211] op_sel:[0,1,0] op_sel_hi:[1,1,1]
	v_pk_fma_f32 v[240:241], v[234:235], v[172:173], v[240:241] op_sel:[0,1,0] op_sel_hi:[1,1,1]
	v_pk_fma_f32 v[212:213], v[204:205], v[186:187], v[212:213] op_sel_hi:[1,0,1]
	v_pk_fma_f32 v[214:215], v[204:205], v[186:187], v[214:215] op_sel:[0,1,0] op_sel_hi:[1,1,1]
	v_pk_fma_f32 v[240:241], v[236:237], v[174:175], v[240:241] op_sel_hi:[1,0,1]
	v_pk_fma_f32 v[216:217], v[204:205], v[188:189], v[216:217] op_sel_hi:[1,0,1]
	v_pk_fma_f32 v[218:219], v[204:205], v[188:189], v[218:219] op_sel:[0,1,0] op_sel_hi:[1,1,1]
	v_pk_fma_f32 v[240:241], v[238:239], v[174:175], v[240:241] op_sel:[0,1,0] op_sel_hi:[1,1,1]
	v_pk_fma_f32 v[220:221], v[204:205], v[190:191], v[220:221] op_sel_hi:[1,0,1]
	v_pk_fma_f32 v[222:223], v[204:205], v[190:191], v[222:223] op_sel:[0,1,0] op_sel_hi:[1,1,1]
	v_add_f32_dpp v240, v240, v240 quad_perm:[1,0,3,2] row_mask:0xf bank_mask:0xf bound_ctrl:1
	v_add_f32_dpp v241, v241, v241 quad_perm:[1,0,3,2] row_mask:0xf bank_mask:0xf bound_ctrl:1
	v_add_f32_dpp v244, v244, v244 quad_perm:[1,0,3,2] row_mask:0xf bank_mask:0xf bound_ctrl:1
	v_add_f32_dpp v240, v240, v240 quad_perm:[2,3,0,1] row_mask:0xf bank_mask:0xf bound_ctrl:1
	v_add_f32_dpp v241, v241, v241 quad_perm:[2,3,0,1] row_mask:0xf bank_mask:0xf bound_ctrl:1
	v_add_f32_dpp v245, v245, v245 quad_perm:[1,0,3,2] row_mask:0xf bank_mask:0xf bound_ctrl:1
	v_add_f32_dpp v248, v240, v240 row_half_mirror row_mask:0xf bank_mask:0xf bound_ctrl:1
	v_add_f32_dpp v249, v241, v241 row_half_mirror row_mask:0xf bank_mask:0xf bound_ctrl:1
	v_add_f32_dpp v244, v244, v244 quad_perm:[2,3,0,1] row_mask:0xf bank_mask:0xf bound_ctrl:1
	v_add_f32_dpp v245, v245, v245 quad_perm:[2,3,0,1] row_mask:0xf bank_mask:0xf bound_ctrl:1
	v_pk_fma_f32 v[208:209], v[248:249], v[176:177], v[208:209] op_sel_hi:[1,0,1]
	v_pk_fma_f32 v[210:211], v[248:249], v[176:177], v[210:211] op_sel:[0,1,0] op_sel_hi:[1,1,1]
	v_add_f32_dpp v244, v244, v244 row_half_mirror row_mask:0xf bank_mask:0xf bound_ctrl:1
	v_add_f32_dpp v245, v245, v245 row_half_mirror row_mask:0xf bank_mask:0xf bound_ctrl:1
	v_pk_fma_f32 v[212:213], v[248:249], v[178:179], v[212:213] op_sel_hi:[1,0,1]
	v_cndmask_b32_e64 v75, 0, v244, s[6:7]
	v_cndmask_b32_e64 v76, 0, v245, s[6:7]
	v_pk_fma_f32 v[214:215], v[248:249], v[178:179], v[214:215] op_sel:[0,1,0] op_sel_hi:[1,1,1]
	v_pk_mul_f32 v[244:245], v[208:209], v[192:193] op_sel_hi:[1,0]
	v_pk_fma_f32 v[216:217], v[248:249], v[180:181], v[216:217] op_sel_hi:[1,0,1]
	v_pk_fma_f32 v[218:219], v[248:249], v[180:181], v[218:219] op_sel:[0,1,0] op_sel_hi:[1,1,1]
	v_pk_fma_f32 v[244:245], v[210:211], v[192:193], v[244:245] op_sel:[0,1,0] op_sel_hi:[1,1,1]
	v_pk_fma_f32 v[220:221], v[248:249], v[182:183], v[220:221] op_sel_hi:[1,0,1]
	v_pk_fma_f32 v[222:223], v[248:249], v[182:183], v[222:223] op_sel:[0,1,0] op_sel_hi:[1,1,1]
	v_pk_fma_f32 v[244:245], v[212:213], v[194:195], v[244:245] op_sel_hi:[1,0,1]
	ds_read_b128 v[128:131], v72 offset:13056
	ds_read_b128 v[132:135], v72 offset:13072
	v_pk_fma_f32 v[244:245], v[214:215], v[194:195], v[244:245] op_sel:[0,1,0] op_sel_hi:[1,1,1]
	ds_read_b128 v[120:123], v72 offset:4864
	ds_read_b128 v[124:127], v72 offset:4880
	s_waitcnt lgkmcnt(15)
	v_pk_fma_f32 v[244:245], v[216:217], v[196:197], v[244:245] op_sel_hi:[1,0,1]
	ds_read_b32 v202, v73 offset:45824
	ds_read_b32 v203, v73 offset:45856
	v_pk_fma_f32 v[244:245], v[218:219], v[196:197], v[244:245] op_sel:[0,1,0] op_sel_hi:[1,1,1]
	ds_read_b128 v[144:147], v72 offset:29440
	ds_read_b128 v[148:151], v72 offset:29456
	v_pk_fma_f32 v[244:245], v[220:221], v[198:199], v[244:245] op_sel_hi:[1,0,1]
	ds_read_b128 v[136:139], v72 offset:21248
	ds_read_b128 v[140:143], v72 offset:21264
	v_pk_fma_f32 v[244:245], v[222:223], v[198:199], v[244:245] op_sel:[0,1,0] op_sel_hi:[1,1,1]
	ds_read_b128 v[152:155], v72 offset:37632
	ds_read_b128 v[156:159], v72 offset:37648
	v_pk_mul_f32 v[240:241], v[208:209], v[88:89] op_sel_hi:[1,0]
	s_waitcnt lgkmcnt(15)
	v_pk_mul_f32 v[224:225], v[208:209], v[80:81] op_sel_hi:[1,0]
	v_pk_mul_f32 v[226:227], v[210:211], v[80:81] op_sel:[0,1] op_sel_hi:[1,1]
	v_pk_fma_f32 v[240:241], v[210:211], v[88:89], v[240:241] op_sel:[0,1,0] op_sel_hi:[1,1,1]
	v_pk_mul_f32 v[228:229], v[212:213], v[82:83] op_sel_hi:[1,0]
	v_pk_mul_f32 v[230:231], v[214:215], v[82:83] op_sel:[0,1] op_sel_hi:[1,1]
	v_pk_fma_f32 v[240:241], v[212:213], v[90:91], v[240:241] op_sel_hi:[1,0,1]
	v_pk_mul_f32 v[232:233], v[216:217], v[84:85] op_sel_hi:[1,0]
	v_pk_mul_f32 v[234:235], v[218:219], v[84:85] op_sel:[0,1] op_sel_hi:[1,1]
	v_pk_fma_f32 v[240:241], v[214:215], v[90:91], v[240:241] op_sel:[0,1,0] op_sel_hi:[1,1,1]
	v_pk_mul_f32 v[236:237], v[220:221], v[86:87] op_sel_hi:[1,0]
	v_pk_mul_f32 v[238:239], v[222:223], v[86:87] op_sel:[0,1] op_sel_hi:[1,1]
	v_pk_fma_f32 v[240:241], v[216:217], v[92:93], v[240:241] op_sel_hi:[1,0,1]
	v_pk_fma_f32 v[224:225], v[200:201], v[104:105], v[224:225] op_sel_hi:[1,0,1]
	v_pk_fma_f32 v[226:227], v[200:201], v[104:105], v[226:227] op_sel:[0,1,0] op_sel_hi:[1,1,1]
	v_pk_fma_f32 v[240:241], v[218:219], v[92:93], v[240:241] op_sel:[0,1,0] op_sel_hi:[1,1,1]
	v_pk_fma_f32 v[228:229], v[200:201], v[106:107], v[228:229] op_sel_hi:[1,0,1]
	v_pk_fma_f32 v[230:231], v[200:201], v[106:107], v[230:231] op_sel:[0,1,0] op_sel_hi:[1,1,1]
	v_pk_fma_f32 v[240:241], v[220:221], v[94:95], v[240:241] op_sel_hi:[1,0,1]
	v_pk_fma_f32 v[232:233], v[200:201], v[108:109], v[232:233] op_sel_hi:[1,0,1]
	v_pk_fma_f32 v[234:235], v[200:201], v[108:109], v[234:235] op_sel:[0,1,0] op_sel_hi:[1,1,1]
	v_pk_fma_f32 v[240:241], v[222:223], v[94:95], v[240:241] op_sel:[0,1,0] op_sel_hi:[1,1,1]
	v_pk_fma_f32 v[236:237], v[200:201], v[110:111], v[236:237] op_sel_hi:[1,0,1]
	v_pk_fma_f32 v[238:239], v[200:201], v[110:111], v[238:239] op_sel:[0,1,0] op_sel_hi:[1,1,1]
	v_add_f32_dpp v240, v240, v240 quad_perm:[1,0,3,2] row_mask:0xf bank_mask:0xf bound_ctrl:1
	v_add_f32_dpp v241, v241, v241 quad_perm:[1,0,3,2] row_mask:0xf bank_mask:0xf bound_ctrl:1
	v_add_f32_dpp v244, v244, v244 quad_perm:[1,0,3,2] row_mask:0xf bank_mask:0xf bound_ctrl:1
	v_add_f32_dpp v240, v240, v240 quad_perm:[2,3,0,1] row_mask:0xf bank_mask:0xf bound_ctrl:1
	v_add_f32_dpp v241, v241, v241 quad_perm:[2,3,0,1] row_mask:0xf bank_mask:0xf bound_ctrl:1
	v_add_f32_dpp v245, v245, v245 quad_perm:[1,0,3,2] row_mask:0xf bank_mask:0xf bound_ctrl:1
	v_add_f32_dpp v248, v240, v240 row_half_mirror row_mask:0xf bank_mask:0xf bound_ctrl:1
	v_add_f32_dpp v249, v241, v241 row_half_mirror row_mask:0xf bank_mask:0xf bound_ctrl:1
	v_add_f32_dpp v244, v244, v244 quad_perm:[2,3,0,1] row_mask:0xf bank_mask:0xf bound_ctrl:1
	v_add_f32_dpp v245, v245, v245 quad_perm:[2,3,0,1] row_mask:0xf bank_mask:0xf bound_ctrl:1
	v_pk_fma_f32 v[224:225], v[248:249], v[96:97], v[224:225] op_sel_hi:[1,0,1]
	v_pk_fma_f32 v[226:227], v[248:249], v[96:97], v[226:227] op_sel:[0,1,0] op_sel_hi:[1,1,1]
	v_add_f32_dpp v244, v244, v244 row_half_mirror row_mask:0xf bank_mask:0xf bound_ctrl:1
	v_add_f32_dpp v245, v245, v245 row_half_mirror row_mask:0xf bank_mask:0xf bound_ctrl:1
	v_pk_fma_f32 v[228:229], v[248:249], v[98:99], v[228:229] op_sel_hi:[1,0,1]
	v_cndmask_b32_e64 v75, v75, v244, s[8:9]
	v_cndmask_b32_e64 v76, v76, v245, s[8:9]
	v_pk_fma_f32 v[230:231], v[248:249], v[98:99], v[230:231] op_sel:[0,1,0] op_sel_hi:[1,1,1]
	s_waitcnt lgkmcnt(13)
	v_pk_mul_f32 v[244:245], v[224:225], v[112:113] op_sel_hi:[1,0]
	v_pk_fma_f32 v[232:233], v[248:249], v[100:101], v[232:233] op_sel_hi:[1,0,1]
	v_pk_fma_f32 v[234:235], v[248:249], v[100:101], v[234:235] op_sel:[0,1,0] op_sel_hi:[1,1,1]
	v_pk_fma_f32 v[244:245], v[226:227], v[112:113], v[244:245] op_sel:[0,1,0] op_sel_hi:[1,1,1]
	v_pk_fma_f32 v[236:237], v[248:249], v[102:103], v[236:237] op_sel_hi:[1,0,1]
	v_pk_fma_f32 v[238:239], v[248:249], v[102:103], v[238:239] op_sel:[0,1,0] op_sel_hi:[1,1,1]
	v_pk_fma_f32 v[244:245], v[228:229], v[114:115], v[244:245] op_sel_hi:[1,0,1]
	ds_read_b128 v[168:171], v72 offset:13312
	ds_read_b128 v[172:175], v72 offset:13328
	v_pk_fma_f32 v[244:245], v[230:231], v[114:115], v[244:245] op_sel:[0,1,0] op_sel_hi:[1,1,1]
	ds_read_b128 v[160:163], v72 offset:5120
	ds_read_b128 v[164:167], v72 offset:5136
	s_waitcnt lgkmcnt(15)
	v_pk_fma_f32 v[244:245], v[232:233], v[116:117], v[244:245] op_sel_hi:[1,0,1]
	ds_read_b32 v204, v73 offset:46080
	ds_read_b32 v205, v73 offset:46112
	v_pk_fma_f32 v[244:245], v[234:235], v[116:117], v[244:245] op_sel:[0,1,0] op_sel_hi:[1,1,1]
	ds_read_b128 v[184:187], v72 offset:29696
	ds_read_b128 v[188:191], v72 offset:29712
	v_pk_fma_f32 v[244:245], v[236:237], v[118:119], v[244:245] op_sel_hi:[1,0,1]
	ds_read_b128 v[176:179], v72 offset:21504
	ds_read_b128 v[180:183], v72 offset:21520
	v_pk_fma_f32 v[244:245], v[238:239], v[118:119], v[244:245] op_sel:[0,1,0] op_sel_hi:[1,1,1]
	ds_read_b128 v[192:195], v72 offset:37888
	ds_read_b128 v[196:199], v72 offset:37904
	v_pk_mul_f32 v[240:241], v[224:225], v[128:129] op_sel_hi:[1,0]
	s_waitcnt lgkmcnt(15)
	v_pk_mul_f32 v[208:209], v[224:225], v[120:121] op_sel_hi:[1,0]
	v_pk_mul_f32 v[210:211], v[226:227], v[120:121] op_sel:[0,1] op_sel_hi:[1,1]
	v_pk_fma_f32 v[240:241], v[226:227], v[128:129], v[240:241] op_sel:[0,1,0] op_sel_hi:[1,1,1]
	v_pk_mul_f32 v[212:213], v[228:229], v[122:123] op_sel_hi:[1,0]
	v_pk_mul_f32 v[214:215], v[230:231], v[122:123] op_sel:[0,1] op_sel_hi:[1,1]
	v_pk_fma_f32 v[240:241], v[228:229], v[130:131], v[240:241] op_sel_hi:[1,0,1]
	v_pk_mul_f32 v[216:217], v[232:233], v[124:125] op_sel_hi:[1,0]
	v_pk_mul_f32 v[218:219], v[234:235], v[124:125] op_sel:[0,1] op_sel_hi:[1,1]
	v_pk_fma_f32 v[240:241], v[230:231], v[130:131], v[240:241] op_sel:[0,1,0] op_sel_hi:[1,1,1]
	v_pk_mul_f32 v[220:221], v[236:237], v[126:127] op_sel_hi:[1,0]
	v_pk_mul_f32 v[222:223], v[238:239], v[126:127] op_sel:[0,1] op_sel_hi:[1,1]
	v_pk_fma_f32 v[240:241], v[232:233], v[132:133], v[240:241] op_sel_hi:[1,0,1]
	v_pk_fma_f32 v[208:209], v[202:203], v[144:145], v[208:209] op_sel_hi:[1,0,1]
	v_pk_fma_f32 v[210:211], v[202:203], v[144:145], v[210:211] op_sel:[0,1,0] op_sel_hi:[1,1,1]
	v_pk_fma_f32 v[240:241], v[234:235], v[132:133], v[240:241] op_sel:[0,1,0] op_sel_hi:[1,1,1]
	v_pk_fma_f32 v[212:213], v[202:203], v[146:147], v[212:213] op_sel_hi:[1,0,1]
	v_pk_fma_f32 v[214:215], v[202:203], v[146:147], v[214:215] op_sel:[0,1,0] op_sel_hi:[1,1,1]
	v_pk_fma_f32 v[240:241], v[236:237], v[134:135], v[240:241] op_sel_hi:[1,0,1]
	v_pk_fma_f32 v[216:217], v[202:203], v[148:149], v[216:217] op_sel_hi:[1,0,1]
	v_pk_fma_f32 v[218:219], v[202:203], v[148:149], v[218:219] op_sel:[0,1,0] op_sel_hi:[1,1,1]
	v_pk_fma_f32 v[240:241], v[238:239], v[134:135], v[240:241] op_sel:[0,1,0] op_sel_hi:[1,1,1]
	v_pk_fma_f32 v[220:221], v[202:203], v[150:151], v[220:221] op_sel_hi:[1,0,1]
	v_pk_fma_f32 v[222:223], v[202:203], v[150:151], v[222:223] op_sel:[0,1,0] op_sel_hi:[1,1,1]
	v_add_f32_dpp v240, v240, v240 quad_perm:[1,0,3,2] row_mask:0xf bank_mask:0xf bound_ctrl:1
	v_add_f32_dpp v241, v241, v241 quad_perm:[1,0,3,2] row_mask:0xf bank_mask:0xf bound_ctrl:1
	v_add_f32_dpp v244, v244, v244 quad_perm:[1,0,3,2] row_mask:0xf bank_mask:0xf bound_ctrl:1
	v_add_f32_dpp v240, v240, v240 quad_perm:[2,3,0,1] row_mask:0xf bank_mask:0xf bound_ctrl:1
	v_add_f32_dpp v241, v241, v241 quad_perm:[2,3,0,1] row_mask:0xf bank_mask:0xf bound_ctrl:1
	v_add_f32_dpp v245, v245, v245 quad_perm:[1,0,3,2] row_mask:0xf bank_mask:0xf bound_ctrl:1
	v_add_f32_dpp v248, v240, v240 row_half_mirror row_mask:0xf bank_mask:0xf bound_ctrl:1
	v_add_f32_dpp v249, v241, v241 row_half_mirror row_mask:0xf bank_mask:0xf bound_ctrl:1
	v_add_f32_dpp v244, v244, v244 quad_perm:[2,3,0,1] row_mask:0xf bank_mask:0xf bound_ctrl:1
	v_add_f32_dpp v245, v245, v245 quad_perm:[2,3,0,1] row_mask:0xf bank_mask:0xf bound_ctrl:1
	v_pk_fma_f32 v[208:209], v[248:249], v[136:137], v[208:209] op_sel_hi:[1,0,1]
	v_pk_fma_f32 v[210:211], v[248:249], v[136:137], v[210:211] op_sel:[0,1,0] op_sel_hi:[1,1,1]
	v_add_f32_dpp v244, v244, v244 row_half_mirror row_mask:0xf bank_mask:0xf bound_ctrl:1
	v_add_f32_dpp v245, v245, v245 row_half_mirror row_mask:0xf bank_mask:0xf bound_ctrl:1
	v_pk_fma_f32 v[212:213], v[248:249], v[138:139], v[212:213] op_sel_hi:[1,0,1]
	v_cndmask_b32_e64 v75, v75, v244, s[10:11]
	v_cndmask_b32_e64 v76, v76, v245, s[10:11]
	v_pk_fma_f32 v[214:215], v[248:249], v[138:139], v[214:215] op_sel:[0,1,0] op_sel_hi:[1,1,1]
	s_waitcnt lgkmcnt(13)
	v_pk_mul_f32 v[244:245], v[208:209], v[152:153] op_sel_hi:[1,0]
	v_pk_fma_f32 v[216:217], v[248:249], v[140:141], v[216:217] op_sel_hi:[1,0,1]
	v_pk_fma_f32 v[218:219], v[248:249], v[140:141], v[218:219] op_sel:[0,1,0] op_sel_hi:[1,1,1]
	v_pk_fma_f32 v[244:245], v[210:211], v[152:153], v[244:245] op_sel:[0,1,0] op_sel_hi:[1,1,1]
	v_pk_fma_f32 v[220:221], v[248:249], v[142:143], v[220:221] op_sel_hi:[1,0,1]
	v_pk_fma_f32 v[222:223], v[248:249], v[142:143], v[222:223] op_sel:[0,1,0] op_sel_hi:[1,1,1]
	v_pk_fma_f32 v[244:245], v[212:213], v[154:155], v[244:245] op_sel_hi:[1,0,1]
	ds_read_b128 v[88:91], v72 offset:13568
	ds_read_b128 v[92:95], v72 offset:13584
	v_pk_fma_f32 v[244:245], v[214:215], v[154:155], v[244:245] op_sel:[0,1,0] op_sel_hi:[1,1,1]
	ds_read_b128 v[80:83], v72 offset:5376
	ds_read_b128 v[84:87], v72 offset:5392
	s_waitcnt lgkmcnt(15)
	v_pk_fma_f32 v[244:245], v[216:217], v[156:157], v[244:245] op_sel_hi:[1,0,1]
	ds_read_b32 v200, v73 offset:46336
	ds_read_b32 v201, v73 offset:46368
	v_pk_fma_f32 v[244:245], v[218:219], v[156:157], v[244:245] op_sel:[0,1,0] op_sel_hi:[1,1,1]
	ds_read_b128 v[104:107], v72 offset:29952
	ds_read_b128 v[108:111], v72 offset:29968
	v_pk_fma_f32 v[244:245], v[220:221], v[158:159], v[244:245] op_sel_hi:[1,0,1]
	ds_read_b128 v[96:99], v72 offset:21760
	ds_read_b128 v[100:103], v72 offset:21776
	v_pk_fma_f32 v[244:245], v[222:223], v[158:159], v[244:245] op_sel:[0,1,0] op_sel_hi:[1,1,1]
	ds_read_b128 v[112:115], v72 offset:38144
	ds_read_b128 v[116:119], v72 offset:38160
	v_pk_mul_f32 v[240:241], v[208:209], v[168:169] op_sel_hi:[1,0]
	s_waitcnt lgkmcnt(15)
	v_pk_mul_f32 v[224:225], v[208:209], v[160:161] op_sel_hi:[1,0]
	v_pk_mul_f32 v[226:227], v[210:211], v[160:161] op_sel:[0,1] op_sel_hi:[1,1]
	v_pk_fma_f32 v[240:241], v[210:211], v[168:169], v[240:241] op_sel:[0,1,0] op_sel_hi:[1,1,1]
	v_pk_mul_f32 v[228:229], v[212:213], v[162:163] op_sel_hi:[1,0]
	v_pk_mul_f32 v[230:231], v[214:215], v[162:163] op_sel:[0,1] op_sel_hi:[1,1]
	v_pk_fma_f32 v[240:241], v[212:213], v[170:171], v[240:241] op_sel_hi:[1,0,1]
	v_pk_mul_f32 v[232:233], v[216:217], v[164:165] op_sel_hi:[1,0]
	v_pk_mul_f32 v[234:235], v[218:219], v[164:165] op_sel:[0,1] op_sel_hi:[1,1]
	v_pk_fma_f32 v[240:241], v[214:215], v[170:171], v[240:241] op_sel:[0,1,0] op_sel_hi:[1,1,1]
	v_pk_mul_f32 v[236:237], v[220:221], v[166:167] op_sel_hi:[1,0]
	v_pk_mul_f32 v[238:239], v[222:223], v[166:167] op_sel:[0,1] op_sel_hi:[1,1]
	v_pk_fma_f32 v[240:241], v[216:217], v[172:173], v[240:241] op_sel_hi:[1,0,1]
	v_pk_fma_f32 v[224:225], v[204:205], v[184:185], v[224:225] op_sel_hi:[1,0,1]
	v_pk_fma_f32 v[226:227], v[204:205], v[184:185], v[226:227] op_sel:[0,1,0] op_sel_hi:[1,1,1]
	v_pk_fma_f32 v[240:241], v[218:219], v[172:173], v[240:241] op_sel:[0,1,0] op_sel_hi:[1,1,1]
	v_pk_fma_f32 v[228:229], v[204:205], v[186:187], v[228:229] op_sel_hi:[1,0,1]
	v_pk_fma_f32 v[230:231], v[204:205], v[186:187], v[230:231] op_sel:[0,1,0] op_sel_hi:[1,1,1]
	v_pk_fma_f32 v[240:241], v[220:221], v[174:175], v[240:241] op_sel_hi:[1,0,1]
	v_pk_fma_f32 v[232:233], v[204:205], v[188:189], v[232:233] op_sel_hi:[1,0,1]
	v_pk_fma_f32 v[234:235], v[204:205], v[188:189], v[234:235] op_sel:[0,1,0] op_sel_hi:[1,1,1]
	v_pk_fma_f32 v[240:241], v[222:223], v[174:175], v[240:241] op_sel:[0,1,0] op_sel_hi:[1,1,1]
	v_pk_fma_f32 v[236:237], v[204:205], v[190:191], v[236:237] op_sel_hi:[1,0,1]
	v_pk_fma_f32 v[238:239], v[204:205], v[190:191], v[238:239] op_sel:[0,1,0] op_sel_hi:[1,1,1]
	v_add_f32_dpp v240, v240, v240 quad_perm:[1,0,3,2] row_mask:0xf bank_mask:0xf bound_ctrl:1
	v_add_f32_dpp v241, v241, v241 quad_perm:[1,0,3,2] row_mask:0xf bank_mask:0xf bound_ctrl:1
	v_add_f32_dpp v244, v244, v244 quad_perm:[1,0,3,2] row_mask:0xf bank_mask:0xf bound_ctrl:1
	v_add_f32_dpp v240, v240, v240 quad_perm:[2,3,0,1] row_mask:0xf bank_mask:0xf bound_ctrl:1
	v_add_f32_dpp v241, v241, v241 quad_perm:[2,3,0,1] row_mask:0xf bank_mask:0xf bound_ctrl:1
	v_add_f32_dpp v245, v245, v245 quad_perm:[1,0,3,2] row_mask:0xf bank_mask:0xf bound_ctrl:1
	v_add_f32_dpp v248, v240, v240 row_half_mirror row_mask:0xf bank_mask:0xf bound_ctrl:1
	v_add_f32_dpp v249, v241, v241 row_half_mirror row_mask:0xf bank_mask:0xf bound_ctrl:1
	v_add_f32_dpp v244, v244, v244 quad_perm:[2,3,0,1] row_mask:0xf bank_mask:0xf bound_ctrl:1
	v_add_f32_dpp v245, v245, v245 quad_perm:[2,3,0,1] row_mask:0xf bank_mask:0xf bound_ctrl:1
	v_pk_fma_f32 v[224:225], v[248:249], v[176:177], v[224:225] op_sel_hi:[1,0,1]
	v_pk_fma_f32 v[226:227], v[248:249], v[176:177], v[226:227] op_sel:[0,1,0] op_sel_hi:[1,1,1]
	v_add_f32_dpp v244, v244, v244 row_half_mirror row_mask:0xf bank_mask:0xf bound_ctrl:1
	v_add_f32_dpp v245, v245, v245 row_half_mirror row_mask:0xf bank_mask:0xf bound_ctrl:1
	v_pk_fma_f32 v[228:229], v[248:249], v[178:179], v[228:229] op_sel_hi:[1,0,1]
	v_cndmask_b32_e64 v75, v75, v244, s[12:13]
	v_cndmask_b32_e64 v76, v76, v245, s[12:13]
	v_pk_fma_f32 v[230:231], v[248:249], v[178:179], v[230:231] op_sel:[0,1,0] op_sel_hi:[1,1,1]
	s_waitcnt lgkmcnt(13)
	v_pk_mul_f32 v[244:245], v[224:225], v[192:193] op_sel_hi:[1,0]
	v_pk_fma_f32 v[232:233], v[248:249], v[180:181], v[232:233] op_sel_hi:[1,0,1]
	v_pk_fma_f32 v[234:235], v[248:249], v[180:181], v[234:235] op_sel:[0,1,0] op_sel_hi:[1,1,1]
	v_pk_fma_f32 v[244:245], v[226:227], v[192:193], v[244:245] op_sel:[0,1,0] op_sel_hi:[1,1,1]
	v_pk_fma_f32 v[236:237], v[248:249], v[182:183], v[236:237] op_sel_hi:[1,0,1]
	v_pk_fma_f32 v[238:239], v[248:249], v[182:183], v[238:239] op_sel:[0,1,0] op_sel_hi:[1,1,1]
	v_pk_fma_f32 v[244:245], v[228:229], v[194:195], v[244:245] op_sel_hi:[1,0,1]
	ds_read_b128 v[128:131], v72 offset:13824
	ds_read_b128 v[132:135], v72 offset:13840
	v_pk_fma_f32 v[244:245], v[230:231], v[194:195], v[244:245] op_sel:[0,1,0] op_sel_hi:[1,1,1]
	ds_read_b128 v[120:123], v72 offset:5632
	ds_read_b128 v[124:127], v72 offset:5648
	s_waitcnt lgkmcnt(15)
	v_pk_fma_f32 v[244:245], v[232:233], v[196:197], v[244:245] op_sel_hi:[1,0,1]
	ds_read_b32 v202, v73 offset:46592
	ds_read_b32 v203, v73 offset:46624
	v_pk_fma_f32 v[244:245], v[234:235], v[196:197], v[244:245] op_sel:[0,1,0] op_sel_hi:[1,1,1]
	ds_read_b128 v[144:147], v72 offset:30208
	ds_read_b128 v[148:151], v72 offset:30224
	v_pk_fma_f32 v[244:245], v[236:237], v[198:199], v[244:245] op_sel_hi:[1,0,1]
	ds_read_b128 v[136:139], v72 offset:22016
	ds_read_b128 v[140:143], v72 offset:22032
	v_pk_fma_f32 v[244:245], v[238:239], v[198:199], v[244:245] op_sel:[0,1,0] op_sel_hi:[1,1,1]
	ds_read_b128 v[152:155], v72 offset:38400
	ds_read_b128 v[156:159], v72 offset:38416
	v_pk_mul_f32 v[240:241], v[224:225], v[88:89] op_sel_hi:[1,0]
	s_waitcnt lgkmcnt(15)
	v_pk_mul_f32 v[208:209], v[224:225], v[80:81] op_sel_hi:[1,0]
	v_pk_mul_f32 v[210:211], v[226:227], v[80:81] op_sel:[0,1] op_sel_hi:[1,1]
	v_pk_fma_f32 v[240:241], v[226:227], v[88:89], v[240:241] op_sel:[0,1,0] op_sel_hi:[1,1,1]
	v_pk_mul_f32 v[212:213], v[228:229], v[82:83] op_sel_hi:[1,0]
	v_pk_mul_f32 v[214:215], v[230:231], v[82:83] op_sel:[0,1] op_sel_hi:[1,1]
	v_pk_fma_f32 v[240:241], v[228:229], v[90:91], v[240:241] op_sel_hi:[1,0,1]
	v_pk_mul_f32 v[216:217], v[232:233], v[84:85] op_sel_hi:[1,0]
	v_pk_mul_f32 v[218:219], v[234:235], v[84:85] op_sel:[0,1] op_sel_hi:[1,1]
	v_pk_fma_f32 v[240:241], v[230:231], v[90:91], v[240:241] op_sel:[0,1,0] op_sel_hi:[1,1,1]
	v_pk_mul_f32 v[220:221], v[236:237], v[86:87] op_sel_hi:[1,0]
	v_pk_mul_f32 v[222:223], v[238:239], v[86:87] op_sel:[0,1] op_sel_hi:[1,1]
	v_pk_fma_f32 v[240:241], v[232:233], v[92:93], v[240:241] op_sel_hi:[1,0,1]
	v_pk_fma_f32 v[208:209], v[200:201], v[104:105], v[208:209] op_sel_hi:[1,0,1]
	v_pk_fma_f32 v[210:211], v[200:201], v[104:105], v[210:211] op_sel:[0,1,0] op_sel_hi:[1,1,1]
	v_pk_fma_f32 v[240:241], v[234:235], v[92:93], v[240:241] op_sel:[0,1,0] op_sel_hi:[1,1,1]
	v_pk_fma_f32 v[212:213], v[200:201], v[106:107], v[212:213] op_sel_hi:[1,0,1]
	v_pk_fma_f32 v[214:215], v[200:201], v[106:107], v[214:215] op_sel:[0,1,0] op_sel_hi:[1,1,1]
	v_pk_fma_f32 v[240:241], v[236:237], v[94:95], v[240:241] op_sel_hi:[1,0,1]
	v_pk_fma_f32 v[216:217], v[200:201], v[108:109], v[216:217] op_sel_hi:[1,0,1]
	v_pk_fma_f32 v[218:219], v[200:201], v[108:109], v[218:219] op_sel:[0,1,0] op_sel_hi:[1,1,1]
	v_pk_fma_f32 v[240:241], v[238:239], v[94:95], v[240:241] op_sel:[0,1,0] op_sel_hi:[1,1,1]
	v_pk_fma_f32 v[220:221], v[200:201], v[110:111], v[220:221] op_sel_hi:[1,0,1]
	v_pk_fma_f32 v[222:223], v[200:201], v[110:111], v[222:223] op_sel:[0,1,0] op_sel_hi:[1,1,1]
	v_add_f32_dpp v240, v240, v240 quad_perm:[1,0,3,2] row_mask:0xf bank_mask:0xf bound_ctrl:1
	v_add_f32_dpp v241, v241, v241 quad_perm:[1,0,3,2] row_mask:0xf bank_mask:0xf bound_ctrl:1
	v_add_f32_dpp v244, v244, v244 quad_perm:[1,0,3,2] row_mask:0xf bank_mask:0xf bound_ctrl:1
	v_add_f32_dpp v240, v240, v240 quad_perm:[2,3,0,1] row_mask:0xf bank_mask:0xf bound_ctrl:1
	v_add_f32_dpp v241, v241, v241 quad_perm:[2,3,0,1] row_mask:0xf bank_mask:0xf bound_ctrl:1
	v_add_f32_dpp v245, v245, v245 quad_perm:[1,0,3,2] row_mask:0xf bank_mask:0xf bound_ctrl:1
	v_add_f32_dpp v248, v240, v240 row_half_mirror row_mask:0xf bank_mask:0xf bound_ctrl:1
	v_add_f32_dpp v249, v241, v241 row_half_mirror row_mask:0xf bank_mask:0xf bound_ctrl:1
	v_add_f32_dpp v244, v244, v244 quad_perm:[2,3,0,1] row_mask:0xf bank_mask:0xf bound_ctrl:1
	v_add_f32_dpp v245, v245, v245 quad_perm:[2,3,0,1] row_mask:0xf bank_mask:0xf bound_ctrl:1
	v_pk_fma_f32 v[208:209], v[248:249], v[96:97], v[208:209] op_sel_hi:[1,0,1]
	v_pk_fma_f32 v[210:211], v[248:249], v[96:97], v[210:211] op_sel:[0,1,0] op_sel_hi:[1,1,1]
	v_add_f32_dpp v244, v244, v244 row_half_mirror row_mask:0xf bank_mask:0xf bound_ctrl:1
	v_add_f32_dpp v245, v245, v245 row_half_mirror row_mask:0xf bank_mask:0xf bound_ctrl:1
	v_pk_fma_f32 v[212:213], v[248:249], v[98:99], v[212:213] op_sel_hi:[1,0,1]
	v_cndmask_b32_e64 v75, v75, v244, s[14:15]
	v_cndmask_b32_e64 v76, v76, v245, s[14:15]
	v_pk_fma_f32 v[214:215], v[248:249], v[98:99], v[214:215] op_sel:[0,1,0] op_sel_hi:[1,1,1]
	s_waitcnt lgkmcnt(13)
	v_pk_mul_f32 v[244:245], v[208:209], v[112:113] op_sel_hi:[1,0]
	v_pk_fma_f32 v[216:217], v[248:249], v[100:101], v[216:217] op_sel_hi:[1,0,1]
	v_pk_fma_f32 v[218:219], v[248:249], v[100:101], v[218:219] op_sel:[0,1,0] op_sel_hi:[1,1,1]
	v_pk_fma_f32 v[244:245], v[210:211], v[112:113], v[244:245] op_sel:[0,1,0] op_sel_hi:[1,1,1]
	v_pk_fma_f32 v[220:221], v[248:249], v[102:103], v[220:221] op_sel_hi:[1,0,1]
	v_pk_fma_f32 v[222:223], v[248:249], v[102:103], v[222:223] op_sel:[0,1,0] op_sel_hi:[1,1,1]
	v_pk_fma_f32 v[244:245], v[212:213], v[114:115], v[244:245] op_sel_hi:[1,0,1]
	ds_read_b128 v[168:171], v72 offset:14080
	ds_read_b128 v[172:175], v72 offset:14096
	v_pk_fma_f32 v[244:245], v[214:215], v[114:115], v[244:245] op_sel:[0,1,0] op_sel_hi:[1,1,1]
	ds_read_b128 v[160:163], v72 offset:5888
	ds_read_b128 v[164:167], v72 offset:5904
	s_waitcnt lgkmcnt(15)
	v_pk_fma_f32 v[244:245], v[216:217], v[116:117], v[244:245] op_sel_hi:[1,0,1]
	ds_read_b32 v204, v73 offset:46848
	ds_read_b32 v205, v73 offset:46880
	v_pk_fma_f32 v[244:245], v[218:219], v[116:117], v[244:245] op_sel:[0,1,0] op_sel_hi:[1,1,1]
	ds_read_b128 v[184:187], v72 offset:30464
	ds_read_b128 v[188:191], v72 offset:30480
	v_pk_fma_f32 v[244:245], v[220:221], v[118:119], v[244:245] op_sel_hi:[1,0,1]
	ds_read_b128 v[176:179], v72 offset:22272
	ds_read_b128 v[180:183], v72 offset:22288
	v_pk_fma_f32 v[244:245], v[222:223], v[118:119], v[244:245] op_sel:[0,1,0] op_sel_hi:[1,1,1]
	ds_read_b128 v[192:195], v72 offset:38656
	ds_read_b128 v[196:199], v72 offset:38672
	v_pk_mul_f32 v[240:241], v[208:209], v[128:129] op_sel_hi:[1,0]
	s_waitcnt lgkmcnt(15)
	v_pk_mul_f32 v[224:225], v[208:209], v[120:121] op_sel_hi:[1,0]
	v_pk_mul_f32 v[226:227], v[210:211], v[120:121] op_sel:[0,1] op_sel_hi:[1,1]
	v_pk_fma_f32 v[240:241], v[210:211], v[128:129], v[240:241] op_sel:[0,1,0] op_sel_hi:[1,1,1]
	v_pk_mul_f32 v[228:229], v[212:213], v[122:123] op_sel_hi:[1,0]
	v_pk_mul_f32 v[230:231], v[214:215], v[122:123] op_sel:[0,1] op_sel_hi:[1,1]
	v_pk_fma_f32 v[240:241], v[212:213], v[130:131], v[240:241] op_sel_hi:[1,0,1]
	v_pk_mul_f32 v[232:233], v[216:217], v[124:125] op_sel_hi:[1,0]
	v_pk_mul_f32 v[234:235], v[218:219], v[124:125] op_sel:[0,1] op_sel_hi:[1,1]
	v_pk_fma_f32 v[240:241], v[214:215], v[130:131], v[240:241] op_sel:[0,1,0] op_sel_hi:[1,1,1]
	v_pk_mul_f32 v[236:237], v[220:221], v[126:127] op_sel_hi:[1,0]
	v_pk_mul_f32 v[238:239], v[222:223], v[126:127] op_sel:[0,1] op_sel_hi:[1,1]
	v_pk_fma_f32 v[240:241], v[216:217], v[132:133], v[240:241] op_sel_hi:[1,0,1]
	v_pk_fma_f32 v[224:225], v[202:203], v[144:145], v[224:225] op_sel_hi:[1,0,1]
	v_pk_fma_f32 v[226:227], v[202:203], v[144:145], v[226:227] op_sel:[0,1,0] op_sel_hi:[1,1,1]
	v_pk_fma_f32 v[240:241], v[218:219], v[132:133], v[240:241] op_sel:[0,1,0] op_sel_hi:[1,1,1]
	v_pk_fma_f32 v[228:229], v[202:203], v[146:147], v[228:229] op_sel_hi:[1,0,1]
	v_pk_fma_f32 v[230:231], v[202:203], v[146:147], v[230:231] op_sel:[0,1,0] op_sel_hi:[1,1,1]
	v_pk_fma_f32 v[240:241], v[220:221], v[134:135], v[240:241] op_sel_hi:[1,0,1]
	v_pk_fma_f32 v[232:233], v[202:203], v[148:149], v[232:233] op_sel_hi:[1,0,1]
	v_pk_fma_f32 v[234:235], v[202:203], v[148:149], v[234:235] op_sel:[0,1,0] op_sel_hi:[1,1,1]
	v_pk_fma_f32 v[240:241], v[222:223], v[134:135], v[240:241] op_sel:[0,1,0] op_sel_hi:[1,1,1]
	v_pk_fma_f32 v[236:237], v[202:203], v[150:151], v[236:237] op_sel_hi:[1,0,1]
	v_pk_fma_f32 v[238:239], v[202:203], v[150:151], v[238:239] op_sel:[0,1,0] op_sel_hi:[1,1,1]
	v_add_f32_dpp v240, v240, v240 quad_perm:[1,0,3,2] row_mask:0xf bank_mask:0xf bound_ctrl:1
	v_add_f32_dpp v241, v241, v241 quad_perm:[1,0,3,2] row_mask:0xf bank_mask:0xf bound_ctrl:1
	v_add_f32_dpp v244, v244, v244 quad_perm:[1,0,3,2] row_mask:0xf bank_mask:0xf bound_ctrl:1
	v_add_f32_dpp v240, v240, v240 quad_perm:[2,3,0,1] row_mask:0xf bank_mask:0xf bound_ctrl:1
	v_add_f32_dpp v241, v241, v241 quad_perm:[2,3,0,1] row_mask:0xf bank_mask:0xf bound_ctrl:1
	v_add_f32_dpp v245, v245, v245 quad_perm:[1,0,3,2] row_mask:0xf bank_mask:0xf bound_ctrl:1
	v_add_f32_dpp v248, v240, v240 row_half_mirror row_mask:0xf bank_mask:0xf bound_ctrl:1
	v_add_f32_dpp v249, v241, v241 row_half_mirror row_mask:0xf bank_mask:0xf bound_ctrl:1
	v_add_f32_dpp v244, v244, v244 quad_perm:[2,3,0,1] row_mask:0xf bank_mask:0xf bound_ctrl:1
	v_add_f32_dpp v245, v245, v245 quad_perm:[2,3,0,1] row_mask:0xf bank_mask:0xf bound_ctrl:1
	v_pk_fma_f32 v[224:225], v[248:249], v[136:137], v[224:225] op_sel_hi:[1,0,1]
	v_pk_fma_f32 v[226:227], v[248:249], v[136:137], v[226:227] op_sel:[0,1,0] op_sel_hi:[1,1,1]
	v_add_f32_dpp v244, v244, v244 row_half_mirror row_mask:0xf bank_mask:0xf bound_ctrl:1
	v_add_f32_dpp v245, v245, v245 row_half_mirror row_mask:0xf bank_mask:0xf bound_ctrl:1
	v_pk_fma_f32 v[228:229], v[248:249], v[138:139], v[228:229] op_sel_hi:[1,0,1]
	v_cndmask_b32_e64 v75, v75, v244, s[16:17]
	v_cndmask_b32_e64 v76, v76, v245, s[16:17]
	v_pk_fma_f32 v[230:231], v[248:249], v[138:139], v[230:231] op_sel:[0,1,0] op_sel_hi:[1,1,1]
	s_waitcnt lgkmcnt(13)
	v_pk_mul_f32 v[244:245], v[224:225], v[152:153] op_sel_hi:[1,0]
	v_pk_fma_f32 v[232:233], v[248:249], v[140:141], v[232:233] op_sel_hi:[1,0,1]
	v_pk_fma_f32 v[234:235], v[248:249], v[140:141], v[234:235] op_sel:[0,1,0] op_sel_hi:[1,1,1]
	v_pk_fma_f32 v[244:245], v[226:227], v[152:153], v[244:245] op_sel:[0,1,0] op_sel_hi:[1,1,1]
	v_pk_fma_f32 v[236:237], v[248:249], v[142:143], v[236:237] op_sel_hi:[1,0,1]
	v_pk_fma_f32 v[238:239], v[248:249], v[142:143], v[238:239] op_sel:[0,1,0] op_sel_hi:[1,1,1]
	v_pk_fma_f32 v[244:245], v[228:229], v[154:155], v[244:245] op_sel_hi:[1,0,1]
	ds_read_b128 v[88:91], v72 offset:14336
	ds_read_b128 v[92:95], v72 offset:14352
	v_pk_fma_f32 v[244:245], v[230:231], v[154:155], v[244:245] op_sel:[0,1,0] op_sel_hi:[1,1,1]
	ds_read_b128 v[80:83], v72 offset:6144
	ds_read_b128 v[84:87], v72 offset:6160
	s_waitcnt lgkmcnt(15)
	v_pk_fma_f32 v[244:245], v[232:233], v[156:157], v[244:245] op_sel_hi:[1,0,1]
	ds_read_b32 v200, v73 offset:47104
	ds_read_b32 v201, v73 offset:47136
	v_pk_fma_f32 v[244:245], v[234:235], v[156:157], v[244:245] op_sel:[0,1,0] op_sel_hi:[1,1,1]
	ds_read_b128 v[104:107], v72 offset:30720
	ds_read_b128 v[108:111], v72 offset:30736
	v_pk_fma_f32 v[244:245], v[236:237], v[158:159], v[244:245] op_sel_hi:[1,0,1]
	ds_read_b128 v[96:99], v72 offset:22528
	ds_read_b128 v[100:103], v72 offset:22544
	v_pk_fma_f32 v[244:245], v[238:239], v[158:159], v[244:245] op_sel:[0,1,0] op_sel_hi:[1,1,1]
	ds_read_b128 v[112:115], v72 offset:38912
	ds_read_b128 v[116:119], v72 offset:38928
	v_pk_mul_f32 v[240:241], v[224:225], v[168:169] op_sel_hi:[1,0]
	s_waitcnt lgkmcnt(15)
	v_pk_mul_f32 v[208:209], v[224:225], v[160:161] op_sel_hi:[1,0]
	v_pk_mul_f32 v[210:211], v[226:227], v[160:161] op_sel:[0,1] op_sel_hi:[1,1]
	v_pk_fma_f32 v[240:241], v[226:227], v[168:169], v[240:241] op_sel:[0,1,0] op_sel_hi:[1,1,1]
	v_pk_mul_f32 v[212:213], v[228:229], v[162:163] op_sel_hi:[1,0]
	v_pk_mul_f32 v[214:215], v[230:231], v[162:163] op_sel:[0,1] op_sel_hi:[1,1]
	v_pk_fma_f32 v[240:241], v[228:229], v[170:171], v[240:241] op_sel_hi:[1,0,1]
	v_pk_mul_f32 v[216:217], v[232:233], v[164:165] op_sel_hi:[1,0]
	v_pk_mul_f32 v[218:219], v[234:235], v[164:165] op_sel:[0,1] op_sel_hi:[1,1]
	v_pk_fma_f32 v[240:241], v[230:231], v[170:171], v[240:241] op_sel:[0,1,0] op_sel_hi:[1,1,1]
	v_pk_mul_f32 v[220:221], v[236:237], v[166:167] op_sel_hi:[1,0]
	v_pk_mul_f32 v[222:223], v[238:239], v[166:167] op_sel:[0,1] op_sel_hi:[1,1]
	v_pk_fma_f32 v[240:241], v[232:233], v[172:173], v[240:241] op_sel_hi:[1,0,1]
	v_pk_fma_f32 v[208:209], v[204:205], v[184:185], v[208:209] op_sel_hi:[1,0,1]
	v_pk_fma_f32 v[210:211], v[204:205], v[184:185], v[210:211] op_sel:[0,1,0] op_sel_hi:[1,1,1]
	v_pk_fma_f32 v[240:241], v[234:235], v[172:173], v[240:241] op_sel:[0,1,0] op_sel_hi:[1,1,1]
	v_pk_fma_f32 v[212:213], v[204:205], v[186:187], v[212:213] op_sel_hi:[1,0,1]
	v_pk_fma_f32 v[214:215], v[204:205], v[186:187], v[214:215] op_sel:[0,1,0] op_sel_hi:[1,1,1]
	v_pk_fma_f32 v[240:241], v[236:237], v[174:175], v[240:241] op_sel_hi:[1,0,1]
	v_pk_fma_f32 v[216:217], v[204:205], v[188:189], v[216:217] op_sel_hi:[1,0,1]
	v_pk_fma_f32 v[218:219], v[204:205], v[188:189], v[218:219] op_sel:[0,1,0] op_sel_hi:[1,1,1]
	v_pk_fma_f32 v[240:241], v[238:239], v[174:175], v[240:241] op_sel:[0,1,0] op_sel_hi:[1,1,1]
	v_pk_fma_f32 v[220:221], v[204:205], v[190:191], v[220:221] op_sel_hi:[1,0,1]
	v_pk_fma_f32 v[222:223], v[204:205], v[190:191], v[222:223] op_sel:[0,1,0] op_sel_hi:[1,1,1]
	v_add_f32_dpp v240, v240, v240 quad_perm:[1,0,3,2] row_mask:0xf bank_mask:0xf bound_ctrl:1
	v_add_f32_dpp v241, v241, v241 quad_perm:[1,0,3,2] row_mask:0xf bank_mask:0xf bound_ctrl:1
	v_add_f32_dpp v244, v244, v244 quad_perm:[1,0,3,2] row_mask:0xf bank_mask:0xf bound_ctrl:1
	v_add_f32_dpp v240, v240, v240 quad_perm:[2,3,0,1] row_mask:0xf bank_mask:0xf bound_ctrl:1
	v_add_f32_dpp v241, v241, v241 quad_perm:[2,3,0,1] row_mask:0xf bank_mask:0xf bound_ctrl:1
	v_add_f32_dpp v245, v245, v245 quad_perm:[1,0,3,2] row_mask:0xf bank_mask:0xf bound_ctrl:1
	v_add_f32_dpp v248, v240, v240 row_half_mirror row_mask:0xf bank_mask:0xf bound_ctrl:1
	v_add_f32_dpp v249, v241, v241 row_half_mirror row_mask:0xf bank_mask:0xf bound_ctrl:1
	v_add_f32_dpp v244, v244, v244 quad_perm:[2,3,0,1] row_mask:0xf bank_mask:0xf bound_ctrl:1
	v_add_f32_dpp v245, v245, v245 quad_perm:[2,3,0,1] row_mask:0xf bank_mask:0xf bound_ctrl:1
	v_pk_fma_f32 v[208:209], v[248:249], v[176:177], v[208:209] op_sel_hi:[1,0,1]
	v_pk_fma_f32 v[210:211], v[248:249], v[176:177], v[210:211] op_sel:[0,1,0] op_sel_hi:[1,1,1]
	v_add_f32_dpp v244, v244, v244 row_half_mirror row_mask:0xf bank_mask:0xf bound_ctrl:1
	v_add_f32_dpp v245, v245, v245 row_half_mirror row_mask:0xf bank_mask:0xf bound_ctrl:1
	v_pk_fma_f32 v[212:213], v[248:249], v[178:179], v[212:213] op_sel_hi:[1,0,1]
	v_cndmask_b32_e64 v75, v75, v244, s[18:19]
	v_cndmask_b32_e64 v76, v76, v245, s[18:19]
	v_pk_fma_f32 v[214:215], v[248:249], v[178:179], v[214:215] op_sel:[0,1,0] op_sel_hi:[1,1,1]
	s_waitcnt lgkmcnt(13)
	v_pk_mul_f32 v[244:245], v[208:209], v[192:193] op_sel_hi:[1,0]
	v_pk_fma_f32 v[216:217], v[248:249], v[180:181], v[216:217] op_sel_hi:[1,0,1]
	v_pk_fma_f32 v[218:219], v[248:249], v[180:181], v[218:219] op_sel:[0,1,0] op_sel_hi:[1,1,1]
	v_pk_fma_f32 v[244:245], v[210:211], v[192:193], v[244:245] op_sel:[0,1,0] op_sel_hi:[1,1,1]
	v_pk_fma_f32 v[220:221], v[248:249], v[182:183], v[220:221] op_sel_hi:[1,0,1]
	v_pk_fma_f32 v[222:223], v[248:249], v[182:183], v[222:223] op_sel:[0,1,0] op_sel_hi:[1,1,1]
	v_pk_fma_f32 v[244:245], v[212:213], v[194:195], v[244:245] op_sel_hi:[1,0,1]
	ds_read_b128 v[128:131], v72 offset:14592
	ds_read_b128 v[132:135], v72 offset:14608
	v_pk_fma_f32 v[244:245], v[214:215], v[194:195], v[244:245] op_sel:[0,1,0] op_sel_hi:[1,1,1]
	ds_read_b128 v[120:123], v72 offset:6400
	ds_read_b128 v[124:127], v72 offset:6416
	s_waitcnt lgkmcnt(15)
	v_pk_fma_f32 v[244:245], v[216:217], v[196:197], v[244:245] op_sel_hi:[1,0,1]
	ds_read_b32 v202, v73 offset:47360
	ds_read_b32 v203, v73 offset:47392
	v_pk_fma_f32 v[244:245], v[218:219], v[196:197], v[244:245] op_sel:[0,1,0] op_sel_hi:[1,1,1]
	ds_read_b128 v[144:147], v72 offset:30976
	ds_read_b128 v[148:151], v72 offset:30992
	v_pk_fma_f32 v[244:245], v[220:221], v[198:199], v[244:245] op_sel_hi:[1,0,1]
	ds_read_b128 v[136:139], v72 offset:22784
	ds_read_b128 v[140:143], v72 offset:22800
	v_pk_fma_f32 v[244:245], v[222:223], v[198:199], v[244:245] op_sel:[0,1,0] op_sel_hi:[1,1,1]
	ds_read_b128 v[152:155], v72 offset:39168
	ds_read_b128 v[156:159], v72 offset:39184
	v_pk_mul_f32 v[240:241], v[208:209], v[88:89] op_sel_hi:[1,0]
	s_waitcnt lgkmcnt(15)
	v_pk_mul_f32 v[224:225], v[208:209], v[80:81] op_sel_hi:[1,0]
	v_pk_mul_f32 v[226:227], v[210:211], v[80:81] op_sel:[0,1] op_sel_hi:[1,1]
	v_pk_fma_f32 v[240:241], v[210:211], v[88:89], v[240:241] op_sel:[0,1,0] op_sel_hi:[1,1,1]
	v_pk_mul_f32 v[228:229], v[212:213], v[82:83] op_sel_hi:[1,0]
	v_pk_mul_f32 v[230:231], v[214:215], v[82:83] op_sel:[0,1] op_sel_hi:[1,1]
	v_pk_fma_f32 v[240:241], v[212:213], v[90:91], v[240:241] op_sel_hi:[1,0,1]
	v_pk_mul_f32 v[232:233], v[216:217], v[84:85] op_sel_hi:[1,0]
	v_pk_mul_f32 v[234:235], v[218:219], v[84:85] op_sel:[0,1] op_sel_hi:[1,1]
	v_pk_fma_f32 v[240:241], v[214:215], v[90:91], v[240:241] op_sel:[0,1,0] op_sel_hi:[1,1,1]
	v_pk_mul_f32 v[236:237], v[220:221], v[86:87] op_sel_hi:[1,0]
	v_pk_mul_f32 v[238:239], v[222:223], v[86:87] op_sel:[0,1] op_sel_hi:[1,1]
	v_pk_fma_f32 v[240:241], v[216:217], v[92:93], v[240:241] op_sel_hi:[1,0,1]
	v_pk_fma_f32 v[224:225], v[200:201], v[104:105], v[224:225] op_sel_hi:[1,0,1]
	v_pk_fma_f32 v[226:227], v[200:201], v[104:105], v[226:227] op_sel:[0,1,0] op_sel_hi:[1,1,1]
	v_pk_fma_f32 v[240:241], v[218:219], v[92:93], v[240:241] op_sel:[0,1,0] op_sel_hi:[1,1,1]
	v_pk_fma_f32 v[228:229], v[200:201], v[106:107], v[228:229] op_sel_hi:[1,0,1]
	v_pk_fma_f32 v[230:231], v[200:201], v[106:107], v[230:231] op_sel:[0,1,0] op_sel_hi:[1,1,1]
	v_pk_fma_f32 v[240:241], v[220:221], v[94:95], v[240:241] op_sel_hi:[1,0,1]
	v_pk_fma_f32 v[232:233], v[200:201], v[108:109], v[232:233] op_sel_hi:[1,0,1]
	v_pk_fma_f32 v[234:235], v[200:201], v[108:109], v[234:235] op_sel:[0,1,0] op_sel_hi:[1,1,1]
	v_pk_fma_f32 v[240:241], v[222:223], v[94:95], v[240:241] op_sel:[0,1,0] op_sel_hi:[1,1,1]
	v_pk_fma_f32 v[236:237], v[200:201], v[110:111], v[236:237] op_sel_hi:[1,0,1]
	v_pk_fma_f32 v[238:239], v[200:201], v[110:111], v[238:239] op_sel:[0,1,0] op_sel_hi:[1,1,1]
	v_add_f32_dpp v240, v240, v240 quad_perm:[1,0,3,2] row_mask:0xf bank_mask:0xf bound_ctrl:1
	v_add_f32_dpp v241, v241, v241 quad_perm:[1,0,3,2] row_mask:0xf bank_mask:0xf bound_ctrl:1
	v_add_f32_dpp v244, v244, v244 quad_perm:[1,0,3,2] row_mask:0xf bank_mask:0xf bound_ctrl:1
	v_add_f32_dpp v240, v240, v240 quad_perm:[2,3,0,1] row_mask:0xf bank_mask:0xf bound_ctrl:1
	v_add_f32_dpp v241, v241, v241 quad_perm:[2,3,0,1] row_mask:0xf bank_mask:0xf bound_ctrl:1
	v_add_f32_dpp v245, v245, v245 quad_perm:[1,0,3,2] row_mask:0xf bank_mask:0xf bound_ctrl:1
	v_add_f32_dpp v248, v240, v240 row_half_mirror row_mask:0xf bank_mask:0xf bound_ctrl:1
	v_add_f32_dpp v249, v241, v241 row_half_mirror row_mask:0xf bank_mask:0xf bound_ctrl:1
	v_add_f32_dpp v244, v244, v244 quad_perm:[2,3,0,1] row_mask:0xf bank_mask:0xf bound_ctrl:1
	v_add_f32_dpp v245, v245, v245 quad_perm:[2,3,0,1] row_mask:0xf bank_mask:0xf bound_ctrl:1
	v_pk_fma_f32 v[224:225], v[248:249], v[96:97], v[224:225] op_sel_hi:[1,0,1]
	v_pk_fma_f32 v[226:227], v[248:249], v[96:97], v[226:227] op_sel:[0,1,0] op_sel_hi:[1,1,1]
	v_add_f32_dpp v244, v244, v244 row_half_mirror row_mask:0xf bank_mask:0xf bound_ctrl:1
	v_add_f32_dpp v245, v245, v245 row_half_mirror row_mask:0xf bank_mask:0xf bound_ctrl:1
	v_pk_fma_f32 v[228:229], v[248:249], v[98:99], v[228:229] op_sel_hi:[1,0,1]
	v_cndmask_b32_e64 v75, v75, v244, s[20:21]
	v_cndmask_b32_e64 v76, v76, v245, s[20:21]
	ds_write_b32 v74, v75 offset:4096
	ds_write_b32 v74, v76 offset:4128
	v_pk_fma_f32 v[230:231], v[248:249], v[98:99], v[230:231] op_sel:[0,1,0] op_sel_hi:[1,1,1]
	s_waitcnt lgkmcnt(15)
	v_pk_mul_f32 v[244:245], v[224:225], v[112:113] op_sel_hi:[1,0]
	v_pk_fma_f32 v[232:233], v[248:249], v[100:101], v[232:233] op_sel_hi:[1,0,1]
	v_pk_fma_f32 v[234:235], v[248:249], v[100:101], v[234:235] op_sel:[0,1,0] op_sel_hi:[1,1,1]
	v_pk_fma_f32 v[244:245], v[226:227], v[112:113], v[244:245] op_sel:[0,1,0] op_sel_hi:[1,1,1]
	v_pk_fma_f32 v[236:237], v[248:249], v[102:103], v[236:237] op_sel_hi:[1,0,1]
	v_pk_fma_f32 v[238:239], v[248:249], v[102:103], v[238:239] op_sel:[0,1,0] op_sel_hi:[1,1,1]
	v_pk_fma_f32 v[244:245], v[228:229], v[114:115], v[244:245] op_sel_hi:[1,0,1]
	ds_read_b128 v[168:171], v72 offset:14848
	ds_read_b128 v[172:175], v72 offset:14864
	v_pk_fma_f32 v[244:245], v[230:231], v[114:115], v[244:245] op_sel:[0,1,0] op_sel_hi:[1,1,1]
	ds_read_b128 v[160:163], v72 offset:6656
	ds_read_b128 v[164:167], v72 offset:6672
	s_waitcnt lgkmcnt(15)
	v_pk_fma_f32 v[244:245], v[232:233], v[116:117], v[244:245] op_sel_hi:[1,0,1]
	ds_read_b32 v204, v73 offset:47616
	ds_read_b32 v205, v73 offset:47648
	v_pk_fma_f32 v[244:245], v[234:235], v[116:117], v[244:245] op_sel:[0,1,0] op_sel_hi:[1,1,1]
	ds_read_b128 v[184:187], v72 offset:31232
	ds_read_b128 v[188:191], v72 offset:31248
	v_pk_fma_f32 v[244:245], v[236:237], v[118:119], v[244:245] op_sel_hi:[1,0,1]
	ds_read_b128 v[176:179], v72 offset:23040
	ds_read_b128 v[180:183], v72 offset:23056
	v_pk_fma_f32 v[244:245], v[238:239], v[118:119], v[244:245] op_sel:[0,1,0] op_sel_hi:[1,1,1]
	ds_read_b128 v[192:195], v72 offset:39424
	ds_read_b128 v[196:199], v72 offset:39440
	v_pk_mul_f32 v[240:241], v[224:225], v[128:129] op_sel_hi:[1,0]
	v_pk_mul_f32 v[208:209], v[224:225], v[120:121] op_sel_hi:[1,0]
	v_pk_mul_f32 v[210:211], v[226:227], v[120:121] op_sel:[0,1] op_sel_hi:[1,1]
	v_pk_fma_f32 v[240:241], v[226:227], v[128:129], v[240:241] op_sel:[0,1,0] op_sel_hi:[1,1,1]
	v_pk_mul_f32 v[212:213], v[228:229], v[122:123] op_sel_hi:[1,0]
	v_pk_mul_f32 v[214:215], v[230:231], v[122:123] op_sel:[0,1] op_sel_hi:[1,1]
	v_pk_fma_f32 v[240:241], v[228:229], v[130:131], v[240:241] op_sel_hi:[1,0,1]
	s_waitcnt lgkmcnt(15)
	v_pk_mul_f32 v[216:217], v[232:233], v[124:125] op_sel_hi:[1,0]
	v_pk_mul_f32 v[218:219], v[234:235], v[124:125] op_sel:[0,1] op_sel_hi:[1,1]
	v_pk_fma_f32 v[240:241], v[230:231], v[130:131], v[240:241] op_sel:[0,1,0] op_sel_hi:[1,1,1]
	v_pk_mul_f32 v[220:221], v[236:237], v[126:127] op_sel_hi:[1,0]
	v_pk_mul_f32 v[222:223], v[238:239], v[126:127] op_sel:[0,1] op_sel_hi:[1,1]
	v_pk_fma_f32 v[240:241], v[232:233], v[132:133], v[240:241] op_sel_hi:[1,0,1]
	v_pk_fma_f32 v[208:209], v[202:203], v[144:145], v[208:209] op_sel_hi:[1,0,1]
	v_pk_fma_f32 v[210:211], v[202:203], v[144:145], v[210:211] op_sel:[0,1,0] op_sel_hi:[1,1,1]
	v_pk_fma_f32 v[240:241], v[234:235], v[132:133], v[240:241] op_sel:[0,1,0] op_sel_hi:[1,1,1]
	v_pk_fma_f32 v[212:213], v[202:203], v[146:147], v[212:213] op_sel_hi:[1,0,1]
	v_pk_fma_f32 v[214:215], v[202:203], v[146:147], v[214:215] op_sel:[0,1,0] op_sel_hi:[1,1,1]
	v_pk_fma_f32 v[240:241], v[236:237], v[134:135], v[240:241] op_sel_hi:[1,0,1]
	v_pk_fma_f32 v[216:217], v[202:203], v[148:149], v[216:217] op_sel_hi:[1,0,1]
	v_pk_fma_f32 v[218:219], v[202:203], v[148:149], v[218:219] op_sel:[0,1,0] op_sel_hi:[1,1,1]
	v_pk_fma_f32 v[240:241], v[238:239], v[134:135], v[240:241] op_sel:[0,1,0] op_sel_hi:[1,1,1]
	v_pk_fma_f32 v[220:221], v[202:203], v[150:151], v[220:221] op_sel_hi:[1,0,1]
	v_pk_fma_f32 v[222:223], v[202:203], v[150:151], v[222:223] op_sel:[0,1,0] op_sel_hi:[1,1,1]
	v_add_f32_dpp v240, v240, v240 quad_perm:[1,0,3,2] row_mask:0xf bank_mask:0xf bound_ctrl:1
	v_add_f32_dpp v241, v241, v241 quad_perm:[1,0,3,2] row_mask:0xf bank_mask:0xf bound_ctrl:1
	v_add_f32_dpp v244, v244, v244 quad_perm:[1,0,3,2] row_mask:0xf bank_mask:0xf bound_ctrl:1
	v_add_f32_dpp v240, v240, v240 quad_perm:[2,3,0,1] row_mask:0xf bank_mask:0xf bound_ctrl:1
	v_add_f32_dpp v241, v241, v241 quad_perm:[2,3,0,1] row_mask:0xf bank_mask:0xf bound_ctrl:1
	v_add_f32_dpp v245, v245, v245 quad_perm:[1,0,3,2] row_mask:0xf bank_mask:0xf bound_ctrl:1
	v_add_f32_dpp v248, v240, v240 row_half_mirror row_mask:0xf bank_mask:0xf bound_ctrl:1
	v_add_f32_dpp v249, v241, v241 row_half_mirror row_mask:0xf bank_mask:0xf bound_ctrl:1
	v_add_f32_dpp v244, v244, v244 quad_perm:[2,3,0,1] row_mask:0xf bank_mask:0xf bound_ctrl:1
	v_add_f32_dpp v245, v245, v245 quad_perm:[2,3,0,1] row_mask:0xf bank_mask:0xf bound_ctrl:1
	v_pk_fma_f32 v[208:209], v[248:249], v[136:137], v[208:209] op_sel_hi:[1,0,1]
	v_pk_fma_f32 v[210:211], v[248:249], v[136:137], v[210:211] op_sel:[0,1,0] op_sel_hi:[1,1,1]
	v_add_f32_dpp v244, v244, v244 row_half_mirror row_mask:0xf bank_mask:0xf bound_ctrl:1
	v_add_f32_dpp v245, v245, v245 row_half_mirror row_mask:0xf bank_mask:0xf bound_ctrl:1
	v_pk_fma_f32 v[212:213], v[248:249], v[138:139], v[212:213] op_sel_hi:[1,0,1]
	v_cndmask_b32_e64 v75, 0, v244, s[6:7]
	v_cndmask_b32_e64 v76, 0, v245, s[6:7]
	v_pk_fma_f32 v[214:215], v[248:249], v[138:139], v[214:215] op_sel:[0,1,0] op_sel_hi:[1,1,1]
	v_pk_mul_f32 v[244:245], v[208:209], v[152:153] op_sel_hi:[1,0]
	v_pk_fma_f32 v[216:217], v[248:249], v[140:141], v[216:217] op_sel_hi:[1,0,1]
	v_pk_fma_f32 v[218:219], v[248:249], v[140:141], v[218:219] op_sel:[0,1,0] op_sel_hi:[1,1,1]
	v_pk_fma_f32 v[244:245], v[210:211], v[152:153], v[244:245] op_sel:[0,1,0] op_sel_hi:[1,1,1]
	v_pk_fma_f32 v[220:221], v[248:249], v[142:143], v[220:221] op_sel_hi:[1,0,1]
	v_pk_fma_f32 v[222:223], v[248:249], v[142:143], v[222:223] op_sel:[0,1,0] op_sel_hi:[1,1,1]
	v_pk_fma_f32 v[244:245], v[212:213], v[154:155], v[244:245] op_sel_hi:[1,0,1]
	ds_read_b128 v[88:91], v72 offset:15104
	ds_read_b128 v[92:95], v72 offset:15120
	v_pk_fma_f32 v[244:245], v[214:215], v[154:155], v[244:245] op_sel:[0,1,0] op_sel_hi:[1,1,1]
	ds_read_b128 v[80:83], v72 offset:6912
	ds_read_b128 v[84:87], v72 offset:6928
	s_waitcnt lgkmcnt(15)
	v_pk_fma_f32 v[244:245], v[216:217], v[156:157], v[244:245] op_sel_hi:[1,0,1]
	ds_read_b32 v200, v73 offset:47872
	ds_read_b32 v201, v73 offset:47904
	v_pk_fma_f32 v[244:245], v[218:219], v[156:157], v[244:245] op_sel:[0,1,0] op_sel_hi:[1,1,1]
	ds_read_b128 v[104:107], v72 offset:31488
	ds_read_b128 v[108:111], v72 offset:31504
	v_pk_fma_f32 v[244:245], v[220:221], v[158:159], v[244:245] op_sel_hi:[1,0,1]
	ds_read_b128 v[96:99], v72 offset:23296
	ds_read_b128 v[100:103], v72 offset:23312
	v_pk_fma_f32 v[244:245], v[222:223], v[158:159], v[244:245] op_sel:[0,1,0] op_sel_hi:[1,1,1]
	ds_read_b128 v[112:115], v72 offset:39680
	ds_read_b128 v[116:119], v72 offset:39696
	v_pk_mul_f32 v[240:241], v[208:209], v[168:169] op_sel_hi:[1,0]
	s_waitcnt lgkmcnt(15)
	v_pk_mul_f32 v[224:225], v[208:209], v[160:161] op_sel_hi:[1,0]
	v_pk_mul_f32 v[226:227], v[210:211], v[160:161] op_sel:[0,1] op_sel_hi:[1,1]
	v_pk_fma_f32 v[240:241], v[210:211], v[168:169], v[240:241] op_sel:[0,1,0] op_sel_hi:[1,1,1]
	v_pk_mul_f32 v[228:229], v[212:213], v[162:163] op_sel_hi:[1,0]
	v_pk_mul_f32 v[230:231], v[214:215], v[162:163] op_sel:[0,1] op_sel_hi:[1,1]
	v_pk_fma_f32 v[240:241], v[212:213], v[170:171], v[240:241] op_sel_hi:[1,0,1]
	v_pk_mul_f32 v[232:233], v[216:217], v[164:165] op_sel_hi:[1,0]
	v_pk_mul_f32 v[234:235], v[218:219], v[164:165] op_sel:[0,1] op_sel_hi:[1,1]
	v_pk_fma_f32 v[240:241], v[214:215], v[170:171], v[240:241] op_sel:[0,1,0] op_sel_hi:[1,1,1]
	v_pk_mul_f32 v[236:237], v[220:221], v[166:167] op_sel_hi:[1,0]
	v_pk_mul_f32 v[238:239], v[222:223], v[166:167] op_sel:[0,1] op_sel_hi:[1,1]
	v_pk_fma_f32 v[240:241], v[216:217], v[172:173], v[240:241] op_sel_hi:[1,0,1]
	v_pk_fma_f32 v[224:225], v[204:205], v[184:185], v[224:225] op_sel_hi:[1,0,1]
	v_pk_fma_f32 v[226:227], v[204:205], v[184:185], v[226:227] op_sel:[0,1,0] op_sel_hi:[1,1,1]
	v_pk_fma_f32 v[240:241], v[218:219], v[172:173], v[240:241] op_sel:[0,1,0] op_sel_hi:[1,1,1]
	v_pk_fma_f32 v[228:229], v[204:205], v[186:187], v[228:229] op_sel_hi:[1,0,1]
	v_pk_fma_f32 v[230:231], v[204:205], v[186:187], v[230:231] op_sel:[0,1,0] op_sel_hi:[1,1,1]
	v_pk_fma_f32 v[240:241], v[220:221], v[174:175], v[240:241] op_sel_hi:[1,0,1]
	v_pk_fma_f32 v[232:233], v[204:205], v[188:189], v[232:233] op_sel_hi:[1,0,1]
	v_pk_fma_f32 v[234:235], v[204:205], v[188:189], v[234:235] op_sel:[0,1,0] op_sel_hi:[1,1,1]
	v_pk_fma_f32 v[240:241], v[222:223], v[174:175], v[240:241] op_sel:[0,1,0] op_sel_hi:[1,1,1]
	v_pk_fma_f32 v[236:237], v[204:205], v[190:191], v[236:237] op_sel_hi:[1,0,1]
	v_pk_fma_f32 v[238:239], v[204:205], v[190:191], v[238:239] op_sel:[0,1,0] op_sel_hi:[1,1,1]
	v_add_f32_dpp v240, v240, v240 quad_perm:[1,0,3,2] row_mask:0xf bank_mask:0xf bound_ctrl:1
	v_add_f32_dpp v241, v241, v241 quad_perm:[1,0,3,2] row_mask:0xf bank_mask:0xf bound_ctrl:1
	v_add_f32_dpp v244, v244, v244 quad_perm:[1,0,3,2] row_mask:0xf bank_mask:0xf bound_ctrl:1
	v_add_f32_dpp v240, v240, v240 quad_perm:[2,3,0,1] row_mask:0xf bank_mask:0xf bound_ctrl:1
	v_add_f32_dpp v241, v241, v241 quad_perm:[2,3,0,1] row_mask:0xf bank_mask:0xf bound_ctrl:1
	v_add_f32_dpp v245, v245, v245 quad_perm:[1,0,3,2] row_mask:0xf bank_mask:0xf bound_ctrl:1
	v_add_f32_dpp v248, v240, v240 row_half_mirror row_mask:0xf bank_mask:0xf bound_ctrl:1
	v_add_f32_dpp v249, v241, v241 row_half_mirror row_mask:0xf bank_mask:0xf bound_ctrl:1
	v_add_f32_dpp v244, v244, v244 quad_perm:[2,3,0,1] row_mask:0xf bank_mask:0xf bound_ctrl:1
	v_add_f32_dpp v245, v245, v245 quad_perm:[2,3,0,1] row_mask:0xf bank_mask:0xf bound_ctrl:1
	v_pk_fma_f32 v[224:225], v[248:249], v[176:177], v[224:225] op_sel_hi:[1,0,1]
	v_pk_fma_f32 v[226:227], v[248:249], v[176:177], v[226:227] op_sel:[0,1,0] op_sel_hi:[1,1,1]
	v_add_f32_dpp v244, v244, v244 row_half_mirror row_mask:0xf bank_mask:0xf bound_ctrl:1
	v_add_f32_dpp v245, v245, v245 row_half_mirror row_mask:0xf bank_mask:0xf bound_ctrl:1
	v_pk_fma_f32 v[228:229], v[248:249], v[178:179], v[228:229] op_sel_hi:[1,0,1]
	v_cndmask_b32_e64 v75, v75, v244, s[8:9]
	v_cndmask_b32_e64 v76, v76, v245, s[8:9]
	v_pk_fma_f32 v[230:231], v[248:249], v[178:179], v[230:231] op_sel:[0,1,0] op_sel_hi:[1,1,1]
	s_waitcnt lgkmcnt(13)
	v_pk_mul_f32 v[244:245], v[224:225], v[192:193] op_sel_hi:[1,0]
	v_pk_fma_f32 v[232:233], v[248:249], v[180:181], v[232:233] op_sel_hi:[1,0,1]
	v_pk_fma_f32 v[234:235], v[248:249], v[180:181], v[234:235] op_sel:[0,1,0] op_sel_hi:[1,1,1]
	v_pk_fma_f32 v[244:245], v[226:227], v[192:193], v[244:245] op_sel:[0,1,0] op_sel_hi:[1,1,1]
	v_pk_fma_f32 v[236:237], v[248:249], v[182:183], v[236:237] op_sel_hi:[1,0,1]
	v_pk_fma_f32 v[238:239], v[248:249], v[182:183], v[238:239] op_sel:[0,1,0] op_sel_hi:[1,1,1]
	v_pk_fma_f32 v[244:245], v[228:229], v[194:195], v[244:245] op_sel_hi:[1,0,1]
	ds_read_b128 v[128:131], v72 offset:15360
	ds_read_b128 v[132:135], v72 offset:15376
	v_pk_fma_f32 v[244:245], v[230:231], v[194:195], v[244:245] op_sel:[0,1,0] op_sel_hi:[1,1,1]
	ds_read_b128 v[120:123], v72 offset:7168
	ds_read_b128 v[124:127], v72 offset:7184
	s_waitcnt lgkmcnt(15)
	v_pk_fma_f32 v[244:245], v[232:233], v[196:197], v[244:245] op_sel_hi:[1,0,1]
	ds_read_b32 v202, v73 offset:48128
	ds_read_b32 v203, v73 offset:48160
	v_pk_fma_f32 v[244:245], v[234:235], v[196:197], v[244:245] op_sel:[0,1,0] op_sel_hi:[1,1,1]
	ds_read_b128 v[144:147], v72 offset:31744
	ds_read_b128 v[148:151], v72 offset:31760
	v_pk_fma_f32 v[244:245], v[236:237], v[198:199], v[244:245] op_sel_hi:[1,0,1]
	ds_read_b128 v[136:139], v72 offset:23552
	ds_read_b128 v[140:143], v72 offset:23568
	v_pk_fma_f32 v[244:245], v[238:239], v[198:199], v[244:245] op_sel:[0,1,0] op_sel_hi:[1,1,1]
	ds_read_b128 v[152:155], v72 offset:39936
	ds_read_b128 v[156:159], v72 offset:39952
	v_pk_mul_f32 v[240:241], v[224:225], v[88:89] op_sel_hi:[1,0]
	s_waitcnt lgkmcnt(15)
	v_pk_mul_f32 v[208:209], v[224:225], v[80:81] op_sel_hi:[1,0]
	v_pk_mul_f32 v[210:211], v[226:227], v[80:81] op_sel:[0,1] op_sel_hi:[1,1]
	v_pk_fma_f32 v[240:241], v[226:227], v[88:89], v[240:241] op_sel:[0,1,0] op_sel_hi:[1,1,1]
	v_pk_mul_f32 v[212:213], v[228:229], v[82:83] op_sel_hi:[1,0]
	v_pk_mul_f32 v[214:215], v[230:231], v[82:83] op_sel:[0,1] op_sel_hi:[1,1]
	v_pk_fma_f32 v[240:241], v[228:229], v[90:91], v[240:241] op_sel_hi:[1,0,1]
	v_pk_mul_f32 v[216:217], v[232:233], v[84:85] op_sel_hi:[1,0]
	v_pk_mul_f32 v[218:219], v[234:235], v[84:85] op_sel:[0,1] op_sel_hi:[1,1]
	v_pk_fma_f32 v[240:241], v[230:231], v[90:91], v[240:241] op_sel:[0,1,0] op_sel_hi:[1,1,1]
	v_pk_mul_f32 v[220:221], v[236:237], v[86:87] op_sel_hi:[1,0]
	v_pk_mul_f32 v[222:223], v[238:239], v[86:87] op_sel:[0,1] op_sel_hi:[1,1]
	v_pk_fma_f32 v[240:241], v[232:233], v[92:93], v[240:241] op_sel_hi:[1,0,1]
	v_pk_fma_f32 v[208:209], v[200:201], v[104:105], v[208:209] op_sel_hi:[1,0,1]
	v_pk_fma_f32 v[210:211], v[200:201], v[104:105], v[210:211] op_sel:[0,1,0] op_sel_hi:[1,1,1]
	v_pk_fma_f32 v[240:241], v[234:235], v[92:93], v[240:241] op_sel:[0,1,0] op_sel_hi:[1,1,1]
	v_pk_fma_f32 v[212:213], v[200:201], v[106:107], v[212:213] op_sel_hi:[1,0,1]
	v_pk_fma_f32 v[214:215], v[200:201], v[106:107], v[214:215] op_sel:[0,1,0] op_sel_hi:[1,1,1]
	v_pk_fma_f32 v[240:241], v[236:237], v[94:95], v[240:241] op_sel_hi:[1,0,1]
	v_pk_fma_f32 v[216:217], v[200:201], v[108:109], v[216:217] op_sel_hi:[1,0,1]
	v_pk_fma_f32 v[218:219], v[200:201], v[108:109], v[218:219] op_sel:[0,1,0] op_sel_hi:[1,1,1]
	v_pk_fma_f32 v[240:241], v[238:239], v[94:95], v[240:241] op_sel:[0,1,0] op_sel_hi:[1,1,1]
	v_pk_fma_f32 v[220:221], v[200:201], v[110:111], v[220:221] op_sel_hi:[1,0,1]
	v_pk_fma_f32 v[222:223], v[200:201], v[110:111], v[222:223] op_sel:[0,1,0] op_sel_hi:[1,1,1]
	v_add_f32_dpp v240, v240, v240 quad_perm:[1,0,3,2] row_mask:0xf bank_mask:0xf bound_ctrl:1
	v_add_f32_dpp v241, v241, v241 quad_perm:[1,0,3,2] row_mask:0xf bank_mask:0xf bound_ctrl:1
	v_add_f32_dpp v244, v244, v244 quad_perm:[1,0,3,2] row_mask:0xf bank_mask:0xf bound_ctrl:1
	v_add_f32_dpp v240, v240, v240 quad_perm:[2,3,0,1] row_mask:0xf bank_mask:0xf bound_ctrl:1
	v_add_f32_dpp v241, v241, v241 quad_perm:[2,3,0,1] row_mask:0xf bank_mask:0xf bound_ctrl:1
	v_add_f32_dpp v245, v245, v245 quad_perm:[1,0,3,2] row_mask:0xf bank_mask:0xf bound_ctrl:1
	v_add_f32_dpp v248, v240, v240 row_half_mirror row_mask:0xf bank_mask:0xf bound_ctrl:1
	v_add_f32_dpp v249, v241, v241 row_half_mirror row_mask:0xf bank_mask:0xf bound_ctrl:1
	v_add_f32_dpp v244, v244, v244 quad_perm:[2,3,0,1] row_mask:0xf bank_mask:0xf bound_ctrl:1
	v_add_f32_dpp v245, v245, v245 quad_perm:[2,3,0,1] row_mask:0xf bank_mask:0xf bound_ctrl:1
	v_pk_fma_f32 v[208:209], v[248:249], v[96:97], v[208:209] op_sel_hi:[1,0,1]
	v_pk_fma_f32 v[210:211], v[248:249], v[96:97], v[210:211] op_sel:[0,1,0] op_sel_hi:[1,1,1]
	v_add_f32_dpp v244, v244, v244 row_half_mirror row_mask:0xf bank_mask:0xf bound_ctrl:1
	v_add_f32_dpp v245, v245, v245 row_half_mirror row_mask:0xf bank_mask:0xf bound_ctrl:1
	v_pk_fma_f32 v[212:213], v[248:249], v[98:99], v[212:213] op_sel_hi:[1,0,1]
	v_cndmask_b32_e64 v75, v75, v244, s[10:11]
	v_cndmask_b32_e64 v76, v76, v245, s[10:11]
	v_pk_fma_f32 v[214:215], v[248:249], v[98:99], v[214:215] op_sel:[0,1,0] op_sel_hi:[1,1,1]
	s_waitcnt lgkmcnt(13)
	v_pk_mul_f32 v[244:245], v[208:209], v[112:113] op_sel_hi:[1,0]
	v_pk_fma_f32 v[216:217], v[248:249], v[100:101], v[216:217] op_sel_hi:[1,0,1]
	v_pk_fma_f32 v[218:219], v[248:249], v[100:101], v[218:219] op_sel:[0,1,0] op_sel_hi:[1,1,1]
	v_pk_fma_f32 v[244:245], v[210:211], v[112:113], v[244:245] op_sel:[0,1,0] op_sel_hi:[1,1,1]
	v_pk_fma_f32 v[220:221], v[248:249], v[102:103], v[220:221] op_sel_hi:[1,0,1]
	v_pk_fma_f32 v[222:223], v[248:249], v[102:103], v[222:223] op_sel:[0,1,0] op_sel_hi:[1,1,1]
	v_pk_fma_f32 v[244:245], v[212:213], v[114:115], v[244:245] op_sel_hi:[1,0,1]
	ds_read_b128 v[168:171], v72 offset:15616
	ds_read_b128 v[172:175], v72 offset:15632
	v_pk_fma_f32 v[244:245], v[214:215], v[114:115], v[244:245] op_sel:[0,1,0] op_sel_hi:[1,1,1]
	ds_read_b128 v[160:163], v72 offset:7424
	ds_read_b128 v[164:167], v72 offset:7440
	s_waitcnt lgkmcnt(15)
	v_pk_fma_f32 v[244:245], v[216:217], v[116:117], v[244:245] op_sel_hi:[1,0,1]
	ds_read_b32 v204, v73 offset:48384
	ds_read_b32 v205, v73 offset:48416
	v_pk_fma_f32 v[244:245], v[218:219], v[116:117], v[244:245] op_sel:[0,1,0] op_sel_hi:[1,1,1]
	ds_read_b128 v[184:187], v72 offset:32000
	ds_read_b128 v[188:191], v72 offset:32016
	v_pk_fma_f32 v[244:245], v[220:221], v[118:119], v[244:245] op_sel_hi:[1,0,1]
	ds_read_b128 v[176:179], v72 offset:23808
	ds_read_b128 v[180:183], v72 offset:23824
	v_pk_fma_f32 v[244:245], v[222:223], v[118:119], v[244:245] op_sel:[0,1,0] op_sel_hi:[1,1,1]
	ds_read_b128 v[192:195], v72 offset:40192
	ds_read_b128 v[196:199], v72 offset:40208
	v_pk_mul_f32 v[240:241], v[208:209], v[128:129] op_sel_hi:[1,0]
	s_waitcnt lgkmcnt(15)
	v_pk_mul_f32 v[224:225], v[208:209], v[120:121] op_sel_hi:[1,0]
	v_pk_mul_f32 v[226:227], v[210:211], v[120:121] op_sel:[0,1] op_sel_hi:[1,1]
	v_pk_fma_f32 v[240:241], v[210:211], v[128:129], v[240:241] op_sel:[0,1,0] op_sel_hi:[1,1,1]
	v_pk_mul_f32 v[228:229], v[212:213], v[122:123] op_sel_hi:[1,0]
	v_pk_mul_f32 v[230:231], v[214:215], v[122:123] op_sel:[0,1] op_sel_hi:[1,1]
	v_pk_fma_f32 v[240:241], v[212:213], v[130:131], v[240:241] op_sel_hi:[1,0,1]
	v_pk_mul_f32 v[232:233], v[216:217], v[124:125] op_sel_hi:[1,0]
	v_pk_mul_f32 v[234:235], v[218:219], v[124:125] op_sel:[0,1] op_sel_hi:[1,1]
	v_pk_fma_f32 v[240:241], v[214:215], v[130:131], v[240:241] op_sel:[0,1,0] op_sel_hi:[1,1,1]
	v_pk_mul_f32 v[236:237], v[220:221], v[126:127] op_sel_hi:[1,0]
	v_pk_mul_f32 v[238:239], v[222:223], v[126:127] op_sel:[0,1] op_sel_hi:[1,1]
	v_pk_fma_f32 v[240:241], v[216:217], v[132:133], v[240:241] op_sel_hi:[1,0,1]
	v_pk_fma_f32 v[224:225], v[202:203], v[144:145], v[224:225] op_sel_hi:[1,0,1]
	v_pk_fma_f32 v[226:227], v[202:203], v[144:145], v[226:227] op_sel:[0,1,0] op_sel_hi:[1,1,1]
	v_pk_fma_f32 v[240:241], v[218:219], v[132:133], v[240:241] op_sel:[0,1,0] op_sel_hi:[1,1,1]
	v_pk_fma_f32 v[228:229], v[202:203], v[146:147], v[228:229] op_sel_hi:[1,0,1]
	v_pk_fma_f32 v[230:231], v[202:203], v[146:147], v[230:231] op_sel:[0,1,0] op_sel_hi:[1,1,1]
	v_pk_fma_f32 v[240:241], v[220:221], v[134:135], v[240:241] op_sel_hi:[1,0,1]
	v_pk_fma_f32 v[232:233], v[202:203], v[148:149], v[232:233] op_sel_hi:[1,0,1]
	v_pk_fma_f32 v[234:235], v[202:203], v[148:149], v[234:235] op_sel:[0,1,0] op_sel_hi:[1,1,1]
	v_pk_fma_f32 v[240:241], v[222:223], v[134:135], v[240:241] op_sel:[0,1,0] op_sel_hi:[1,1,1]
	v_pk_fma_f32 v[236:237], v[202:203], v[150:151], v[236:237] op_sel_hi:[1,0,1]
	v_pk_fma_f32 v[238:239], v[202:203], v[150:151], v[238:239] op_sel:[0,1,0] op_sel_hi:[1,1,1]
	v_add_f32_dpp v240, v240, v240 quad_perm:[1,0,3,2] row_mask:0xf bank_mask:0xf bound_ctrl:1
	v_add_f32_dpp v241, v241, v241 quad_perm:[1,0,3,2] row_mask:0xf bank_mask:0xf bound_ctrl:1
	v_add_f32_dpp v244, v244, v244 quad_perm:[1,0,3,2] row_mask:0xf bank_mask:0xf bound_ctrl:1
	v_add_f32_dpp v240, v240, v240 quad_perm:[2,3,0,1] row_mask:0xf bank_mask:0xf bound_ctrl:1
	v_add_f32_dpp v241, v241, v241 quad_perm:[2,3,0,1] row_mask:0xf bank_mask:0xf bound_ctrl:1
	v_add_f32_dpp v245, v245, v245 quad_perm:[1,0,3,2] row_mask:0xf bank_mask:0xf bound_ctrl:1
	v_add_f32_dpp v248, v240, v240 row_half_mirror row_mask:0xf bank_mask:0xf bound_ctrl:1
	v_add_f32_dpp v249, v241, v241 row_half_mirror row_mask:0xf bank_mask:0xf bound_ctrl:1
	v_add_f32_dpp v244, v244, v244 quad_perm:[2,3,0,1] row_mask:0xf bank_mask:0xf bound_ctrl:1
	v_add_f32_dpp v245, v245, v245 quad_perm:[2,3,0,1] row_mask:0xf bank_mask:0xf bound_ctrl:1
	v_pk_fma_f32 v[224:225], v[248:249], v[136:137], v[224:225] op_sel_hi:[1,0,1]
	v_pk_fma_f32 v[226:227], v[248:249], v[136:137], v[226:227] op_sel:[0,1,0] op_sel_hi:[1,1,1]
	v_add_f32_dpp v244, v244, v244 row_half_mirror row_mask:0xf bank_mask:0xf bound_ctrl:1
	v_add_f32_dpp v245, v245, v245 row_half_mirror row_mask:0xf bank_mask:0xf bound_ctrl:1
	v_pk_fma_f32 v[228:229], v[248:249], v[138:139], v[228:229] op_sel_hi:[1,0,1]
	v_cndmask_b32_e64 v75, v75, v244, s[12:13]
	v_cndmask_b32_e64 v76, v76, v245, s[12:13]
	v_pk_fma_f32 v[230:231], v[248:249], v[138:139], v[230:231] op_sel:[0,1,0] op_sel_hi:[1,1,1]
	s_waitcnt lgkmcnt(13)
	v_pk_mul_f32 v[244:245], v[224:225], v[152:153] op_sel_hi:[1,0]
	v_pk_fma_f32 v[232:233], v[248:249], v[140:141], v[232:233] op_sel_hi:[1,0,1]
	v_pk_fma_f32 v[234:235], v[248:249], v[140:141], v[234:235] op_sel:[0,1,0] op_sel_hi:[1,1,1]
	v_pk_fma_f32 v[244:245], v[226:227], v[152:153], v[244:245] op_sel:[0,1,0] op_sel_hi:[1,1,1]
	v_pk_fma_f32 v[236:237], v[248:249], v[142:143], v[236:237] op_sel_hi:[1,0,1]
	v_pk_fma_f32 v[238:239], v[248:249], v[142:143], v[238:239] op_sel:[0,1,0] op_sel_hi:[1,1,1]
	v_pk_fma_f32 v[244:245], v[228:229], v[154:155], v[244:245] op_sel_hi:[1,0,1]
	ds_read_b128 v[88:91], v72 offset:15872
	ds_read_b128 v[92:95], v72 offset:15888
	v_pk_fma_f32 v[244:245], v[230:231], v[154:155], v[244:245] op_sel:[0,1,0] op_sel_hi:[1,1,1]
	ds_read_b128 v[80:83], v72 offset:7680
	ds_read_b128 v[84:87], v72 offset:7696
	s_waitcnt lgkmcnt(15)
	v_pk_fma_f32 v[244:245], v[232:233], v[156:157], v[244:245] op_sel_hi:[1,0,1]
	ds_read_b32 v200, v73 offset:48640
	ds_read_b32 v201, v73 offset:48672
	v_pk_fma_f32 v[244:245], v[234:235], v[156:157], v[244:245] op_sel:[0,1,0] op_sel_hi:[1,1,1]
	ds_read_b128 v[104:107], v72 offset:32256
	ds_read_b128 v[108:111], v72 offset:32272
	v_pk_fma_f32 v[244:245], v[236:237], v[158:159], v[244:245] op_sel_hi:[1,0,1]
	ds_read_b128 v[96:99], v72 offset:24064
	ds_read_b128 v[100:103], v72 offset:24080
	v_pk_fma_f32 v[244:245], v[238:239], v[158:159], v[244:245] op_sel:[0,1,0] op_sel_hi:[1,1,1]
	ds_read_b128 v[112:115], v72 offset:40448
	ds_read_b128 v[116:119], v72 offset:40464
	v_pk_mul_f32 v[240:241], v[224:225], v[168:169] op_sel_hi:[1,0]
	s_waitcnt lgkmcnt(15)
	v_pk_mul_f32 v[208:209], v[224:225], v[160:161] op_sel_hi:[1,0]
	v_pk_mul_f32 v[210:211], v[226:227], v[160:161] op_sel:[0,1] op_sel_hi:[1,1]
	v_pk_fma_f32 v[240:241], v[226:227], v[168:169], v[240:241] op_sel:[0,1,0] op_sel_hi:[1,1,1]
	v_pk_mul_f32 v[212:213], v[228:229], v[162:163] op_sel_hi:[1,0]
	v_pk_mul_f32 v[214:215], v[230:231], v[162:163] op_sel:[0,1] op_sel_hi:[1,1]
	v_pk_fma_f32 v[240:241], v[228:229], v[170:171], v[240:241] op_sel_hi:[1,0,1]
	v_pk_mul_f32 v[216:217], v[232:233], v[164:165] op_sel_hi:[1,0]
	v_pk_mul_f32 v[218:219], v[234:235], v[164:165] op_sel:[0,1] op_sel_hi:[1,1]
	v_pk_fma_f32 v[240:241], v[230:231], v[170:171], v[240:241] op_sel:[0,1,0] op_sel_hi:[1,1,1]
	v_pk_mul_f32 v[220:221], v[236:237], v[166:167] op_sel_hi:[1,0]
	v_pk_mul_f32 v[222:223], v[238:239], v[166:167] op_sel:[0,1] op_sel_hi:[1,1]
	v_pk_fma_f32 v[240:241], v[232:233], v[172:173], v[240:241] op_sel_hi:[1,0,1]
	v_pk_fma_f32 v[208:209], v[204:205], v[184:185], v[208:209] op_sel_hi:[1,0,1]
	v_pk_fma_f32 v[210:211], v[204:205], v[184:185], v[210:211] op_sel:[0,1,0] op_sel_hi:[1,1,1]
	v_pk_fma_f32 v[240:241], v[234:235], v[172:173], v[240:241] op_sel:[0,1,0] op_sel_hi:[1,1,1]
	v_pk_fma_f32 v[212:213], v[204:205], v[186:187], v[212:213] op_sel_hi:[1,0,1]
	v_pk_fma_f32 v[214:215], v[204:205], v[186:187], v[214:215] op_sel:[0,1,0] op_sel_hi:[1,1,1]
	v_pk_fma_f32 v[240:241], v[236:237], v[174:175], v[240:241] op_sel_hi:[1,0,1]
	v_pk_fma_f32 v[216:217], v[204:205], v[188:189], v[216:217] op_sel_hi:[1,0,1]
	v_pk_fma_f32 v[218:219], v[204:205], v[188:189], v[218:219] op_sel:[0,1,0] op_sel_hi:[1,1,1]
	v_pk_fma_f32 v[240:241], v[238:239], v[174:175], v[240:241] op_sel:[0,1,0] op_sel_hi:[1,1,1]
	v_pk_fma_f32 v[220:221], v[204:205], v[190:191], v[220:221] op_sel_hi:[1,0,1]
	v_pk_fma_f32 v[222:223], v[204:205], v[190:191], v[222:223] op_sel:[0,1,0] op_sel_hi:[1,1,1]
	v_add_f32_dpp v240, v240, v240 quad_perm:[1,0,3,2] row_mask:0xf bank_mask:0xf bound_ctrl:1
	v_add_f32_dpp v241, v241, v241 quad_perm:[1,0,3,2] row_mask:0xf bank_mask:0xf bound_ctrl:1
	v_add_f32_dpp v244, v244, v244 quad_perm:[1,0,3,2] row_mask:0xf bank_mask:0xf bound_ctrl:1
	v_add_f32_dpp v240, v240, v240 quad_perm:[2,3,0,1] row_mask:0xf bank_mask:0xf bound_ctrl:1
	v_add_f32_dpp v241, v241, v241 quad_perm:[2,3,0,1] row_mask:0xf bank_mask:0xf bound_ctrl:1
	v_add_f32_dpp v245, v245, v245 quad_perm:[1,0,3,2] row_mask:0xf bank_mask:0xf bound_ctrl:1
	v_add_f32_dpp v248, v240, v240 row_half_mirror row_mask:0xf bank_mask:0xf bound_ctrl:1
	v_add_f32_dpp v249, v241, v241 row_half_mirror row_mask:0xf bank_mask:0xf bound_ctrl:1
	v_add_f32_dpp v244, v244, v244 quad_perm:[2,3,0,1] row_mask:0xf bank_mask:0xf bound_ctrl:1
	v_add_f32_dpp v245, v245, v245 quad_perm:[2,3,0,1] row_mask:0xf bank_mask:0xf bound_ctrl:1
	v_pk_fma_f32 v[208:209], v[248:249], v[176:177], v[208:209] op_sel_hi:[1,0,1]
	v_pk_fma_f32 v[210:211], v[248:249], v[176:177], v[210:211] op_sel:[0,1,0] op_sel_hi:[1,1,1]
	v_add_f32_dpp v244, v244, v244 row_half_mirror row_mask:0xf bank_mask:0xf bound_ctrl:1
	v_add_f32_dpp v245, v245, v245 row_half_mirror row_mask:0xf bank_mask:0xf bound_ctrl:1
	v_pk_fma_f32 v[212:213], v[248:249], v[178:179], v[212:213] op_sel_hi:[1,0,1]
	v_cndmask_b32_e64 v75, v75, v244, s[14:15]
	v_cndmask_b32_e64 v76, v76, v245, s[14:15]
	v_pk_fma_f32 v[214:215], v[248:249], v[178:179], v[214:215] op_sel:[0,1,0] op_sel_hi:[1,1,1]
	s_waitcnt lgkmcnt(13)
	v_pk_mul_f32 v[244:245], v[208:209], v[192:193] op_sel_hi:[1,0]
	v_pk_fma_f32 v[216:217], v[248:249], v[180:181], v[216:217] op_sel_hi:[1,0,1]
	v_pk_fma_f32 v[218:219], v[248:249], v[180:181], v[218:219] op_sel:[0,1,0] op_sel_hi:[1,1,1]
	v_pk_fma_f32 v[244:245], v[210:211], v[192:193], v[244:245] op_sel:[0,1,0] op_sel_hi:[1,1,1]
	v_pk_fma_f32 v[220:221], v[248:249], v[182:183], v[220:221] op_sel_hi:[1,0,1]
	v_pk_fma_f32 v[222:223], v[248:249], v[182:183], v[222:223] op_sel:[0,1,0] op_sel_hi:[1,1,1]
	v_pk_fma_f32 v[244:245], v[212:213], v[194:195], v[244:245] op_sel_hi:[1,0,1]
	ds_read_b128 v[128:131], v72 offset:16128
	ds_read_b128 v[132:135], v72 offset:16144
	v_pk_fma_f32 v[244:245], v[214:215], v[194:195], v[244:245] op_sel:[0,1,0] op_sel_hi:[1,1,1]
	ds_read_b128 v[120:123], v72 offset:7936
	ds_read_b128 v[124:127], v72 offset:7952
	s_waitcnt lgkmcnt(15)
	v_pk_fma_f32 v[244:245], v[216:217], v[196:197], v[244:245] op_sel_hi:[1,0,1]
	ds_read_b32 v202, v73 offset:48896
	ds_read_b32 v203, v73 offset:48928
	v_pk_fma_f32 v[244:245], v[218:219], v[196:197], v[244:245] op_sel:[0,1,0] op_sel_hi:[1,1,1]
	ds_read_b128 v[144:147], v72 offset:32512
	ds_read_b128 v[148:151], v72 offset:32528
	v_pk_fma_f32 v[244:245], v[220:221], v[198:199], v[244:245] op_sel_hi:[1,0,1]
	ds_read_b128 v[136:139], v72 offset:24320
	ds_read_b128 v[140:143], v72 offset:24336
	v_pk_fma_f32 v[244:245], v[222:223], v[198:199], v[244:245] op_sel:[0,1,0] op_sel_hi:[1,1,1]
	ds_read_b128 v[152:155], v72 offset:40704
	ds_read_b128 v[156:159], v72 offset:40720
	v_pk_mul_f32 v[240:241], v[208:209], v[88:89] op_sel_hi:[1,0]
	s_waitcnt lgkmcnt(15)
	v_pk_mul_f32 v[224:225], v[208:209], v[80:81] op_sel_hi:[1,0]
	v_pk_mul_f32 v[226:227], v[210:211], v[80:81] op_sel:[0,1] op_sel_hi:[1,1]
	v_pk_fma_f32 v[240:241], v[210:211], v[88:89], v[240:241] op_sel:[0,1,0] op_sel_hi:[1,1,1]
	v_pk_mul_f32 v[228:229], v[212:213], v[82:83] op_sel_hi:[1,0]
	v_pk_mul_f32 v[230:231], v[214:215], v[82:83] op_sel:[0,1] op_sel_hi:[1,1]
	v_pk_fma_f32 v[240:241], v[212:213], v[90:91], v[240:241] op_sel_hi:[1,0,1]
	v_pk_mul_f32 v[232:233], v[216:217], v[84:85] op_sel_hi:[1,0]
	v_pk_mul_f32 v[234:235], v[218:219], v[84:85] op_sel:[0,1] op_sel_hi:[1,1]
	v_pk_fma_f32 v[240:241], v[214:215], v[90:91], v[240:241] op_sel:[0,1,0] op_sel_hi:[1,1,1]
	v_pk_mul_f32 v[236:237], v[220:221], v[86:87] op_sel_hi:[1,0]
	v_pk_mul_f32 v[238:239], v[222:223], v[86:87] op_sel:[0,1] op_sel_hi:[1,1]
	v_pk_fma_f32 v[240:241], v[216:217], v[92:93], v[240:241] op_sel_hi:[1,0,1]
	v_pk_fma_f32 v[224:225], v[200:201], v[104:105], v[224:225] op_sel_hi:[1,0,1]
	v_pk_fma_f32 v[226:227], v[200:201], v[104:105], v[226:227] op_sel:[0,1,0] op_sel_hi:[1,1,1]
	v_pk_fma_f32 v[240:241], v[218:219], v[92:93], v[240:241] op_sel:[0,1,0] op_sel_hi:[1,1,1]
	v_pk_fma_f32 v[228:229], v[200:201], v[106:107], v[228:229] op_sel_hi:[1,0,1]
	v_pk_fma_f32 v[230:231], v[200:201], v[106:107], v[230:231] op_sel:[0,1,0] op_sel_hi:[1,1,1]
	v_pk_fma_f32 v[240:241], v[220:221], v[94:95], v[240:241] op_sel_hi:[1,0,1]
	v_pk_fma_f32 v[232:233], v[200:201], v[108:109], v[232:233] op_sel_hi:[1,0,1]
	v_pk_fma_f32 v[234:235], v[200:201], v[108:109], v[234:235] op_sel:[0,1,0] op_sel_hi:[1,1,1]
	v_pk_fma_f32 v[240:241], v[222:223], v[94:95], v[240:241] op_sel:[0,1,0] op_sel_hi:[1,1,1]
	v_pk_fma_f32 v[236:237], v[200:201], v[110:111], v[236:237] op_sel_hi:[1,0,1]
	v_pk_fma_f32 v[238:239], v[200:201], v[110:111], v[238:239] op_sel:[0,1,0] op_sel_hi:[1,1,1]
	v_add_f32_dpp v240, v240, v240 quad_perm:[1,0,3,2] row_mask:0xf bank_mask:0xf bound_ctrl:1
	v_add_f32_dpp v241, v241, v241 quad_perm:[1,0,3,2] row_mask:0xf bank_mask:0xf bound_ctrl:1
	v_add_f32_dpp v244, v244, v244 quad_perm:[1,0,3,2] row_mask:0xf bank_mask:0xf bound_ctrl:1
	v_add_f32_dpp v240, v240, v240 quad_perm:[2,3,0,1] row_mask:0xf bank_mask:0xf bound_ctrl:1
	v_add_f32_dpp v241, v241, v241 quad_perm:[2,3,0,1] row_mask:0xf bank_mask:0xf bound_ctrl:1
	v_add_f32_dpp v245, v245, v245 quad_perm:[1,0,3,2] row_mask:0xf bank_mask:0xf bound_ctrl:1
	v_add_f32_dpp v248, v240, v240 row_half_mirror row_mask:0xf bank_mask:0xf bound_ctrl:1
	v_add_f32_dpp v249, v241, v241 row_half_mirror row_mask:0xf bank_mask:0xf bound_ctrl:1
	v_add_f32_dpp v244, v244, v244 quad_perm:[2,3,0,1] row_mask:0xf bank_mask:0xf bound_ctrl:1
	v_add_f32_dpp v245, v245, v245 quad_perm:[2,3,0,1] row_mask:0xf bank_mask:0xf bound_ctrl:1
	v_pk_fma_f32 v[224:225], v[248:249], v[96:97], v[224:225] op_sel_hi:[1,0,1]
	v_pk_fma_f32 v[226:227], v[248:249], v[96:97], v[226:227] op_sel:[0,1,0] op_sel_hi:[1,1,1]
	v_add_f32_dpp v244, v244, v244 row_half_mirror row_mask:0xf bank_mask:0xf bound_ctrl:1
	v_add_f32_dpp v245, v245, v245 row_half_mirror row_mask:0xf bank_mask:0xf bound_ctrl:1
	v_pk_fma_f32 v[228:229], v[248:249], v[98:99], v[228:229] op_sel_hi:[1,0,1]
	v_cndmask_b32_e64 v75, v75, v244, s[16:17]
	v_cndmask_b32_e64 v76, v76, v245, s[16:17]
	v_pk_fma_f32 v[230:231], v[248:249], v[98:99], v[230:231] op_sel:[0,1,0] op_sel_hi:[1,1,1]
	s_waitcnt lgkmcnt(13)
	v_pk_mul_f32 v[244:245], v[224:225], v[112:113] op_sel_hi:[1,0]
	v_pk_fma_f32 v[232:233], v[248:249], v[100:101], v[232:233] op_sel_hi:[1,0,1]
	v_pk_fma_f32 v[234:235], v[248:249], v[100:101], v[234:235] op_sel:[0,1,0] op_sel_hi:[1,1,1]
	v_pk_fma_f32 v[244:245], v[226:227], v[112:113], v[244:245] op_sel:[0,1,0] op_sel_hi:[1,1,1]
	v_pk_fma_f32 v[236:237], v[248:249], v[102:103], v[236:237] op_sel_hi:[1,0,1]
	v_pk_fma_f32 v[238:239], v[248:249], v[102:103], v[238:239] op_sel:[0,1,0] op_sel_hi:[1,1,1]
	v_pk_fma_f32 v[244:245], v[228:229], v[114:115], v[244:245] op_sel_hi:[1,0,1]
	v_pk_fma_f32 v[244:245], v[230:231], v[114:115], v[244:245] op_sel:[0,1,0] op_sel_hi:[1,1,1]
	s_waitcnt lgkmcnt(12)
	v_pk_fma_f32 v[244:245], v[232:233], v[116:117], v[244:245] op_sel_hi:[1,0,1]
	v_pk_fma_f32 v[244:245], v[234:235], v[116:117], v[244:245] op_sel:[0,1,0] op_sel_hi:[1,1,1]
	v_pk_fma_f32 v[244:245], v[236:237], v[118:119], v[244:245] op_sel_hi:[1,0,1]
	v_pk_fma_f32 v[244:245], v[238:239], v[118:119], v[244:245] op_sel:[0,1,0] op_sel_hi:[1,1,1]
	s_waitcnt lgkmcnt(11)
	v_pk_mul_f32 v[240:241], v[224:225], v[128:129] op_sel_hi:[1,0]
	s_waitcnt lgkmcnt(9)
	v_pk_mul_f32 v[208:209], v[224:225], v[120:121] op_sel_hi:[1,0]
	v_pk_mul_f32 v[210:211], v[226:227], v[120:121] op_sel:[0,1] op_sel_hi:[1,1]
	v_pk_fma_f32 v[240:241], v[226:227], v[128:129], v[240:241] op_sel:[0,1,0] op_sel_hi:[1,1,1]
	v_pk_mul_f32 v[212:213], v[228:229], v[122:123] op_sel_hi:[1,0]
	v_pk_mul_f32 v[214:215], v[230:231], v[122:123] op_sel:[0,1] op_sel_hi:[1,1]
	v_pk_fma_f32 v[240:241], v[228:229], v[130:131], v[240:241] op_sel_hi:[1,0,1]
	s_waitcnt lgkmcnt(8)
	v_pk_mul_f32 v[216:217], v[232:233], v[124:125] op_sel_hi:[1,0]
	v_pk_mul_f32 v[218:219], v[234:235], v[124:125] op_sel:[0,1] op_sel_hi:[1,1]
	v_pk_fma_f32 v[240:241], v[230:231], v[130:131], v[240:241] op_sel:[0,1,0] op_sel_hi:[1,1,1]
	v_pk_mul_f32 v[220:221], v[236:237], v[126:127] op_sel_hi:[1,0]
	v_pk_mul_f32 v[222:223], v[238:239], v[126:127] op_sel:[0,1] op_sel_hi:[1,1]
	v_pk_fma_f32 v[240:241], v[232:233], v[132:133], v[240:241] op_sel_hi:[1,0,1]
	s_waitcnt lgkmcnt(5)
	v_pk_fma_f32 v[208:209], v[202:203], v[144:145], v[208:209] op_sel_hi:[1,0,1]
	v_pk_fma_f32 v[210:211], v[202:203], v[144:145], v[210:211] op_sel:[0,1,0] op_sel_hi:[1,1,1]
	v_pk_fma_f32 v[240:241], v[234:235], v[132:133], v[240:241] op_sel:[0,1,0] op_sel_hi:[1,1,1]
	v_pk_fma_f32 v[212:213], v[202:203], v[146:147], v[212:213] op_sel_hi:[1,0,1]
	v_pk_fma_f32 v[214:215], v[202:203], v[146:147], v[214:215] op_sel:[0,1,0] op_sel_hi:[1,1,1]
	v_pk_fma_f32 v[240:241], v[236:237], v[134:135], v[240:241] op_sel_hi:[1,0,1]
	s_waitcnt lgkmcnt(4)
	v_pk_fma_f32 v[216:217], v[202:203], v[148:149], v[216:217] op_sel_hi:[1,0,1]
	v_pk_fma_f32 v[218:219], v[202:203], v[148:149], v[218:219] op_sel:[0,1,0] op_sel_hi:[1,1,1]
	v_pk_fma_f32 v[240:241], v[238:239], v[134:135], v[240:241] op_sel:[0,1,0] op_sel_hi:[1,1,1]
	v_pk_fma_f32 v[220:221], v[202:203], v[150:151], v[220:221] op_sel_hi:[1,0,1]
	v_pk_fma_f32 v[222:223], v[202:203], v[150:151], v[222:223] op_sel:[0,1,0] op_sel_hi:[1,1,1]
	v_add_f32_dpp v240, v240, v240 quad_perm:[1,0,3,2] row_mask:0xf bank_mask:0xf bound_ctrl:1
	v_add_f32_dpp v241, v241, v241 quad_perm:[1,0,3,2] row_mask:0xf bank_mask:0xf bound_ctrl:1
	v_add_f32_dpp v244, v244, v244 quad_perm:[1,0,3,2] row_mask:0xf bank_mask:0xf bound_ctrl:1
	v_add_f32_dpp v240, v240, v240 quad_perm:[2,3,0,1] row_mask:0xf bank_mask:0xf bound_ctrl:1
	v_add_f32_dpp v241, v241, v241 quad_perm:[2,3,0,1] row_mask:0xf bank_mask:0xf bound_ctrl:1
	v_add_f32_dpp v245, v245, v245 quad_perm:[1,0,3,2] row_mask:0xf bank_mask:0xf bound_ctrl:1
	v_add_f32_dpp v248, v240, v240 row_half_mirror row_mask:0xf bank_mask:0xf bound_ctrl:1
	v_add_f32_dpp v249, v241, v241 row_half_mirror row_mask:0xf bank_mask:0xf bound_ctrl:1
	v_add_f32_dpp v244, v244, v244 quad_perm:[2,3,0,1] row_mask:0xf bank_mask:0xf bound_ctrl:1
	v_add_f32_dpp v245, v245, v245 quad_perm:[2,3,0,1] row_mask:0xf bank_mask:0xf bound_ctrl:1
	s_waitcnt lgkmcnt(3)
	v_pk_fma_f32 v[208:209], v[248:249], v[136:137], v[208:209] op_sel_hi:[1,0,1]
	v_pk_fma_f32 v[210:211], v[248:249], v[136:137], v[210:211] op_sel:[0,1,0] op_sel_hi:[1,1,1]
	v_add_f32_dpp v244, v244, v244 row_half_mirror row_mask:0xf bank_mask:0xf bound_ctrl:1
	v_add_f32_dpp v245, v245, v245 row_half_mirror row_mask:0xf bank_mask:0xf bound_ctrl:1
	v_pk_fma_f32 v[212:213], v[248:249], v[138:139], v[212:213] op_sel_hi:[1,0,1]
	v_cndmask_b32_e64 v75, v75, v244, s[18:19]
	v_cndmask_b32_e64 v76, v76, v245, s[18:19]
	v_pk_fma_f32 v[214:215], v[248:249], v[138:139], v[214:215] op_sel:[0,1,0] op_sel_hi:[1,1,1]
	s_waitcnt lgkmcnt(1)
	v_pk_mul_f32 v[244:245], v[208:209], v[152:153] op_sel_hi:[1,0]
	v_pk_fma_f32 v[216:217], v[248:249], v[140:141], v[216:217] op_sel_hi:[1,0,1]
	v_pk_fma_f32 v[218:219], v[248:249], v[140:141], v[218:219] op_sel:[0,1,0] op_sel_hi:[1,1,1]
	v_pk_fma_f32 v[244:245], v[210:211], v[152:153], v[244:245] op_sel:[0,1,0] op_sel_hi:[1,1,1]
	v_pk_fma_f32 v[220:221], v[248:249], v[142:143], v[220:221] op_sel_hi:[1,0,1]
	v_pk_fma_f32 v[222:223], v[248:249], v[142:143], v[222:223] op_sel:[0,1,0] op_sel_hi:[1,1,1]
	v_pk_fma_f32 v[244:245], v[212:213], v[154:155], v[244:245] op_sel_hi:[1,0,1]
	v_pk_fma_f32 v[244:245], v[214:215], v[154:155], v[244:245] op_sel:[0,1,0] op_sel_hi:[1,1,1]
	s_waitcnt lgkmcnt(0)
	v_pk_fma_f32 v[244:245], v[216:217], v[156:157], v[244:245] op_sel_hi:[1,0,1]
	v_pk_fma_f32 v[244:245], v[218:219], v[156:157], v[244:245] op_sel:[0,1,0] op_sel_hi:[1,1,1]
	v_pk_fma_f32 v[244:245], v[220:221], v[158:159], v[244:245] op_sel_hi:[1,0,1]
	v_pk_fma_f32 v[244:245], v[222:223], v[158:159], v[244:245] op_sel:[0,1,0] op_sel_hi:[1,1,1]
	s_nop 1
	v_add_f32_dpp v244, v244, v244 quad_perm:[1,0,3,2] row_mask:0xf bank_mask:0xf bound_ctrl:1
	v_add_f32_dpp v245, v245, v245 quad_perm:[1,0,3,2] row_mask:0xf bank_mask:0xf bound_ctrl:1
	s_nop 0
	v_add_f32_dpp v244, v244, v244 quad_perm:[2,3,0,1] row_mask:0xf bank_mask:0xf bound_ctrl:1
	v_add_f32_dpp v245, v245, v245 quad_perm:[2,3,0,1] row_mask:0xf bank_mask:0xf bound_ctrl:1
	s_nop 0
	v_add_f32_dpp v244, v244, v244 row_half_mirror row_mask:0xf bank_mask:0xf bound_ctrl:1
	v_add_f32_dpp v245, v245, v245 row_half_mirror row_mask:0xf bank_mask:0xf bound_ctrl:1
	v_cndmask_b32_e64 v75, v75, v244, s[20:21]
	v_cndmask_b32_e64 v76, v76, v245, s[20:21]
	ds_write_b32 v74, v75 offset:6144
	ds_write_b32 v74, v76 offset:6176
.Lmy_scan_skip:
	s_andn2_b64 vcc, exec, s[50:51]
	s_cbranch_vccnz .LBB0_655
	s_waitcnt vmcnt(4)
	v_lshlrev_b32_e32 v72, 16, v28
	v_and_b32_e32 v73, 0xffff0000, v28
	v_lshlrev_b32_e32 v76, 16, v30
	v_and_b32_e32 v77, 0xffff0000, v30
	v_lshlrev_b32_e32 v74, 16, v26
	v_and_b32_e32 v75, 0xffff0000, v26
	v_pk_add_f32 v[72:73], v[72:73], v[76:77]
	s_waitcnt vmcnt(2)
	v_lshlrev_b32_e32 v78, 16, v42
	v_pk_fma_f32 v[72:73], v[72:73], 0.5, v[74:75] op_sel_hi:[1,0,1] neg_lo:[0,0,1] neg_hi:[0,0,1]
	v_and_b32_e32 v79, 0xffff0000, v42
	v_pk_fma_f32 v[72:73], v[0:1], v[72:73], v[74:75]
	v_lshlrev_b32_e32 v74, 16, v40
	v_and_b32_e32 v75, 0xffff0000, v40
	v_lshlrev_b32_e32 v76, 16, v38
	v_and_b32_e32 v77, 0xffff0000, v38
	v_pk_add_f32 v[74:75], v[74:75], v[78:79]
	s_waitcnt vmcnt(1)
	v_cvt_f32_f16_e32 v21, v44
	v_pk_fma_f32 v[74:75], v[74:75], 0.5, v[76:77] op_sel_hi:[1,0,1] neg_lo:[0,0,1] neg_hi:[0,0,1]
	v_lshlrev_b32_e32 v80, 16, v31
	v_pk_fma_f32 v[76:77], v[8:9], v[74:75], v[76:77]
	v_lshlrev_b32_e32 v74, 16, v29
	v_and_b32_e32 v75, 0xffff0000, v29
	v_and_b32_e32 v81, 0xffff0000, v31
	v_lshlrev_b32_e32 v78, 16, v27
	v_and_b32_e32 v79, 0xffff0000, v27
	v_pk_add_f32 v[74:75], v[74:75], v[80:81]
	v_cvt_f32_f16_sdwa v84, v44 dst_sel:DWORD dst_unused:UNUSED_PAD src0_sel:WORD_1
	v_pk_fma_f32 v[74:75], v[74:75], 0.5, v[78:79] op_sel_hi:[1,0,1] neg_lo:[0,0,1] neg_hi:[0,0,1]
	v_lshlrev_b32_e32 v82, 16, v43
	v_pk_fma_f32 v[74:75], v[2:3], v[74:75], v[78:79]
	v_lshlrev_b32_e32 v78, 16, v41
	v_and_b32_e32 v79, 0xffff0000, v41
	v_and_b32_e32 v83, 0xffff0000, v43
	v_cvt_f32_f16_e32 v88, v45
	v_lshlrev_b32_e32 v80, 16, v39
	v_and_b32_e32 v81, 0xffff0000, v39
	v_pk_add_f32 v[78:79], v[78:79], v[82:83]
	v_mul_f32_e32 v21, 0xbf1b4598, v21
	v_pk_fma_f32 v[78:79], v[78:79], 0.5, v[80:81] op_sel_hi:[1,0,1] neg_lo:[0,0,1] neg_hi:[0,0,1]
	v_mul_f32_e32 v21, 0x3fb8aa3b, v21
	v_cvt_f32_f16_sdwa v89, v45 dst_sel:DWORD dst_unused:UNUSED_PAD src0_sel:WORD_1
	v_pk_fma_f32 v[78:79], v[10:11], v[78:79], v[80:81]
	v_exp_f32_e32 v80, v21
	v_mul_f32_e32 v21, 0xbf1b4598, v84
	v_mul_f32_e32 v21, 0x3fb8aa3b, v21
	v_lshlrev_b32_e32 v82, 16, v34
	v_and_b32_e32 v83, 0xffff0000, v34
	v_lshlrev_b32_e32 v86, 16, v36
	v_and_b32_e32 v87, 0xffff0000, v36
	v_exp_f32_e32 v81, v21
	v_lshlrev_b32_e32 v84, 16, v32
	v_and_b32_e32 v85, 0xffff0000, v32
	v_pk_add_f32 v[82:83], v[82:83], v[86:87]
	v_mul_f32_e32 v21, 0xbf1b4598, v88
	v_pk_fma_f32 v[82:83], v[82:83], 0.5, v[84:85] op_sel_hi:[1,0,1] neg_lo:[0,0,1] neg_hi:[0,0,1]
	v_mul_f32_e32 v21, 0x3fb8aa3b, v21
	v_pk_fma_f32 v[96:97], v[4:5], v[82:83], v[84:85]
	v_exp_f32_e32 v82, v21
	v_mul_f32_e32 v21, 0xbf1b4598, v89
	v_lshlrev_b32_e32 v84, 16, v35
	v_and_b32_e32 v85, 0xffff0000, v35
	v_lshlrev_b32_e32 v88, 16, v37
	v_and_b32_e32 v89, 0xffff0000, v37
	v_lshlrev_b32_e32 v86, 16, v33
	v_and_b32_e32 v87, 0xffff0000, v33
	v_pk_add_f32 v[84:85], v[84:85], v[88:89]
	s_waitcnt vmcnt(0)
	v_cvt_f32_f16_sdwa v93, v46 dst_sel:DWORD dst_unused:UNUSED_PAD src0_sel:WORD_1
	v_pk_fma_f32 v[84:85], v[84:85], 0.5, v[86:87] op_sel_hi:[1,0,1] neg_lo:[0,0,1] neg_hi:[0,0,1]
	v_cvt_f32_f16_e32 v92, v46
	v_pk_fma_f32 v[94:95], v[6:7], v[84:85], v[86:87]
	v_pk_mul_f32 v[84:85], v[12:13], v[96:97]
	v_pk_mul_f32 v[88:89], v[14:15], v[94:95]
	v_pk_mul_f32 v[86:87], v[84:85], v[84:85]
	v_pk_mul_f32 v[90:91], v[88:89], v[88:89]
	v_add_f32_e32 v83, v86, v87
	v_add_f32_e32 v83, v90, v83
	v_add_f32_e32 v83, v91, v83
	v_cvt_f32_f16_sdwa v99, v47 dst_sel:DWORD dst_unused:UNUSED_PAD src0_sel:WORD_1
	v_cvt_f32_f16_e32 v98, v47
	v_add_f32_dpp v83, v83, v83 quad_perm:[1,0,3,2] row_mask:0xf bank_mask:0xf bound_ctrl:1
	v_mul_f32_e32 v21, 0x3fb8aa3b, v21
	s_bitcmp1_b32 s22, 0
	v_add_f32_dpp v83, v83, v83 quad_perm:[2,3,0,1] row_mask:0xf bank_mask:0xf bound_ctrl:1
	s_cselect_b32 s23, 0xc000, 0
	s_nop 0
	v_add_f32_dpp v83, v83, v83 row_half_mirror row_mask:0xf bank_mask:0xf bound_ctrl:1
	s_nop 1
	v_add_f32_dpp v83, v83, v83 row_mirror row_mask:0xf bank_mask:0xf bound_ctrl:1
	v_max_f32_e32 v83, 0x179abe15, v83
	v_rsq_f32_e32 v86, v83
	v_exp_f32_e32 v83, v21
	v_add_u32_e32 v21, s23, v67
	v_pk_mul_f32 v[90:91], v[84:85], v[86:87] op_sel_hi:[1,0]
	v_pk_mul_f32 v[100:101], v[88:89], v[86:87] op_sel_hi:[1,0]
	v_xor_b32_e32 v85, 0x80000000, v91
	v_xor_b32_e32 v84, 0x80000000, v90
	v_pk_mul_f32 v[88:89], v[90:91], v[92:93]
	v_pk_mul_f32 v[90:91], v[100:101], v[98:99]
	v_pk_add_f32 v[92:93], v[92:93], -1.0 op_sel_hi:[1,0]
	v_pk_add_f32 v[98:99], v[98:99], -1.0 op_sel_hi:[1,0]
	v_pk_fma_f32 v[92:93], v[16:17], v[92:93], 1.0 op_sel_hi:[1,1,0]
	v_pk_fma_f32 v[98:99], v[18:19], v[98:99], 1.0 op_sel_hi:[1,1,0]
	v_xor_b32_e32 v86, 0x80000000, v100
	v_xor_b32_e32 v87, 0x80000000, v101
	v_pk_mul_f32 v[94:95], v[94:95], v[98:99]
	v_pk_mul_f32 v[92:93], v[96:97], v[92:93]
	ds_write_b128 v21, v[80:83]
	ds_write_b128 v21, v[84:87] offset:8192
	ds_write_b128 v21, v[88:91] offset:16384
	ds_write_b128 v21, v[92:95] offset:24576
	ds_write_b128 v21, v[72:75] offset:32768
	ds_write_b128 v21, v[76:79] offset:40960
	s_branch .LBB0_655
